# P0 weight conversion also by the hand-written depth-3 nt transpose routine (ev_w_in, ev_w_out, od_w_in with column permutation); tails depth 3; staggered diff-attention
# speedup vs baseline: 1.0375x; 1.0008x over previous
.LBB0_73:
	s_mov_b32 s99, 0xc800
	s_cmp_eq_u32 s87, 0x100
	s_cselect_b32 s99, 0x4000, s99
	s_add_i32 s98, s99, -1
	s_lshl_b32 s0, s96, 3
	s_add_i32 s20, s93, s0
	s_cmp_gt_i32 s20, s98
	s_waitcnt lgkmcnt(0)
	s_barrier
	s_cbranch_scc1 .LBB0_158
	s_cmp_lg_u32 s87, 0x100
	s_cbranch_scc1 .Lp0_orig
	s_cmp_lg_u32 s87, 0x100
	s_cbranch_scc1 .Ltp0_done
	s_cmp_lt_u32 s96, 0
	s_cbranch_scc1 .Ltp0_done
	s_sub_u32 s20, s96, 0
	s_lshl_b32 s20, s20, 3
	s_add_u32 s20, s20, s93
	s_movk_i32 s23, 2048
	v_mbcnt_hi_u32_b32 v0, -1, v212
	v_and_b32_e32 v0, 63, v0
	v_lshrrev_b32_e32 v1, 3, v0
	v_and_b32_e32 v2, 7, v0
	s_lshl_b32 s25, s93, 14
	v_mul_u32_u24_e32 v3, 0x84, v1
	v_mul_u32_u24_e32 v4, 0x420, v2
	v_lshlrev_b32_e32 v2, 4, v2
	v_add3_u32 v3, v3, v2, s25
	v_lshl_add_u32 v4, v1, 2, v4
	v_add_u32_e32 v4, s25, v4
	v_and_b32_e32 v7, 4, v1
	v_and_b32_e32 v5, 3, v1
	v_lshl_add_u32 v7, v7, 1, v5
	v_readlane_b32 s62, v244, 23
	v_readlane_b32 s63, v244, 24
	s_add_u32 s64, s76, 0x189000
	s_addc_u32 s65, s77, 0
	v_readlane_b32 s66, v244, 25
	v_readlane_b32 s67, v244, 26
	s_add_u32 s68, s76, 0x2189000
	s_addc_u32 s69, s77, 0
	v_readlane_b32 s70, v244, 37
	v_readlane_b32 s71, v244, 38
	s_add_u32 s82, s76, 0x2989000
	s_addc_u32 s83, s77, 0
	s_cmp_ge_u32 s20, 16384
	s_cbranch_scc1 .Ltp0_done
	s_cmp_lt_u32 s20, 8192
	s_cbranch_scc1 .Ltp0_r1_s0
	s_cmp_lt_u32 s20, 10240
	s_cbranch_scc1 .Ltp0_r1_s1
	s_sub_u32 s25, s20, 10240
	s_mul_i32 s27, s25, 0xaaab
	s_lshr_b32 s27, s27, 23
	s_mul_i32 s31, s27, 192
	s_sub_u32 s31, s25, s31
	s_mul_i32 s35, s27, 0x180000
	s_lshl_b32 s41, s31, 7
	s_add_u32 s35, s35, s41
	s_add_u32 s0, s70, s35
	s_addc_u32 s1, s71, 0
	s_lshl_b32 s35, s31, 5
	s_mov_b32 s45, 0
	s_cmp_ge_u32 s31, 128
	s_cbranch_scc1 .Ltp0_r1_np
	s_and_b32 s41, s35, 32
	s_lshl_b32 s41, s41, 1
	s_and_b32 s45, s35, 64
	s_lshr_b32 s45, s45, 4
	s_add_u32 s41, s41, s45
	s_andn2_b32 s35, s35, 0x7f
	s_add_u32 s35, s35, s41
	s_mov_b32 s45, 1
.Ltp0_r1_np:
	s_mul_i32 s35, s35, 0x1000
	s_lshl_b32 s41, s27, 7
	s_add_u32 s35, s35, s41
	s_add_u32 s2, s82, s35
	s_addc_u32 s3, s83, 0
	s_mov_b32 s5, 0x6000
	s_mov_b32 s6, 0x30000
	s_mov_b32 s7, 0x1000
	s_branch .Ltp0_r1_e
.Ltp0_r1_s1:
	s_sub_u32 s25, s20, 8192
	s_lshr_b32 s27, s25, 6
	s_and_b32 s31, s25, 63
	s_mul_i32 s35, s27, 0x80000
	s_lshl_b32 s41, s31, 7
	s_add_u32 s35, s35, s41
	s_add_u32 s0, s66, s35
	s_addc_u32 s1, s67, 0
	s_mov_b32 s45, 0
	s_mul_i32 s35, s31, 0x20000
	s_lshl_b32 s41, s27, 7
	s_add_u32 s35, s35, s41
	s_add_u32 s2, s68, s35
	s_addc_u32 s3, s69, 0
	s_mov_b32 s5, 0x2000
	s_mov_b32 s6, 0x10000
	s_mov_b32 s7, 0x1000
	s_branch .Ltp0_r1_e
.Ltp0_r1_s0:
	s_sub_u32 s25, s20, 0
	s_lshr_b32 s27, s25, 8
	s_and_b32 s31, s25, 255
	s_mul_i32 s35, s27, 0x200000
	s_lshl_b32 s41, s31, 7
	s_add_u32 s35, s35, s41
	s_add_u32 s0, s62, s35
	s_addc_u32 s1, s63, 0
	s_mov_b32 s45, 0
	s_mul_i32 s35, s31, 0x20000
	s_lshl_b32 s41, s27, 7
	s_add_u32 s35, s35, s41
	s_add_u32 s2, s64, s35
	s_addc_u32 s3, s65, 0
	s_mov_b32 s5, 0x8000
	s_mov_b32 s6, 0x40000
	s_mov_b32 s7, 0x1000
.Ltp0_r1_e:
	v_mad_u32_u24 v5, v1, s5, v2
	global_load_dwordx4 v[8:11], v5, s[0:1] nt
	s_add_u32 s0, s0, s6
	s_addc_u32 s1, s1, 0
	global_load_dwordx4 v[12:15], v5, s[0:1] nt
	s_add_u32 s0, s0, s6
	s_addc_u32 s1, s1, 0
	global_load_dwordx4 v[16:19], v5, s[0:1] nt
	s_add_u32 s0, s0, s6
	s_addc_u32 s1, s1, 0
	global_load_dwordx4 v[20:23], v5, s[0:1] nt
	s_add_u32 s0, s0, s6
	s_addc_u32 s1, s1, 0
	global_load_dwordx4 v[24:27], v5, s[0:1] nt
	s_add_u32 s0, s0, s6
	s_addc_u32 s1, s1, 0
	global_load_dwordx4 v[28:31], v5, s[0:1] nt
	s_add_u32 s0, s0, s6
	s_addc_u32 s1, s1, 0
	global_load_dwordx4 v[32:35], v5, s[0:1] nt
	s_add_u32 s0, s0, s6
	s_addc_u32 s1, s1, 0
	global_load_dwordx4 v[36:39], v5, s[0:1] nt
	s_add_u32 s0, s0, s6
	s_addc_u32 s1, s1, 0
	s_add_u32 s20, s20, s23
	s_cmp_ge_u32 s20, 16384
	s_cbranch_scc1 .Ltp0_dr1
	s_cmp_lt_u32 s20, 8192
	s_cbranch_scc1 .Ltp0_r2_s0
	s_cmp_lt_u32 s20, 10240
	s_cbranch_scc1 .Ltp0_r2_s1
	s_sub_u32 s25, s20, 10240
	s_mul_i32 s27, s25, 0xaaab
	s_lshr_b32 s27, s27, 23
	s_mul_i32 s31, s27, 192
	s_sub_u32 s31, s25, s31
	s_mul_i32 s35, s27, 0x180000
	s_lshl_b32 s41, s31, 7
	s_add_u32 s35, s35, s41
	s_add_u32 s0, s70, s35
	s_addc_u32 s1, s71, 0
	s_lshl_b32 s35, s31, 5
	s_mov_b32 s50, 0
	s_cmp_ge_u32 s31, 128
	s_cbranch_scc1 .Ltp0_r2_np
	s_and_b32 s41, s35, 32
	s_lshl_b32 s41, s41, 1
	s_and_b32 s50, s35, 64
	s_lshr_b32 s50, s50, 4
	s_add_u32 s41, s41, s50
	s_andn2_b32 s35, s35, 0x7f
	s_add_u32 s35, s35, s41
	s_mov_b32 s50, 1
.Ltp0_r2_np:
	s_mul_i32 s35, s35, 0x1000
	s_lshl_b32 s41, s27, 7
	s_add_u32 s35, s35, s41
	s_add_u32 s10, s82, s35
	s_addc_u32 s11, s83, 0
	s_mov_b32 s5, 0x6000
	s_mov_b32 s6, 0x30000
	s_mov_b32 s47, 0x1000
	s_branch .Ltp0_r2_e
.Ltp0_r2_s1:
	s_sub_u32 s25, s20, 8192
	s_lshr_b32 s27, s25, 6
	s_and_b32 s31, s25, 63
	s_mul_i32 s35, s27, 0x80000
	s_lshl_b32 s41, s31, 7
	s_add_u32 s35, s35, s41
	s_add_u32 s0, s66, s35
	s_addc_u32 s1, s67, 0
	s_mov_b32 s50, 0
	s_mul_i32 s35, s31, 0x20000
	s_lshl_b32 s41, s27, 7
	s_add_u32 s35, s35, s41
	s_add_u32 s10, s68, s35
	s_addc_u32 s11, s69, 0
	s_mov_b32 s5, 0x2000
	s_mov_b32 s6, 0x10000
	s_mov_b32 s47, 0x1000
	s_branch .Ltp0_r2_e
.Ltp0_r2_s0:
	s_sub_u32 s25, s20, 0
	s_lshr_b32 s27, s25, 8
	s_and_b32 s31, s25, 255
	s_mul_i32 s35, s27, 0x200000
	s_lshl_b32 s41, s31, 7
	s_add_u32 s35, s35, s41
	s_add_u32 s0, s62, s35
	s_addc_u32 s1, s63, 0
	s_mov_b32 s50, 0
	s_mul_i32 s35, s31, 0x20000
	s_lshl_b32 s41, s27, 7
	s_add_u32 s35, s35, s41
	s_add_u32 s10, s64, s35
	s_addc_u32 s11, s65, 0
	s_mov_b32 s5, 0x8000
	s_mov_b32 s6, 0x40000
	s_mov_b32 s47, 0x1000
.Ltp0_r2_e:
	v_mad_u32_u24 v5, v1, s5, v2
	global_load_dwordx4 v[40:43], v5, s[0:1] nt
	s_add_u32 s0, s0, s6
	s_addc_u32 s1, s1, 0
	global_load_dwordx4 v[44:47], v5, s[0:1] nt
	s_add_u32 s0, s0, s6
	s_addc_u32 s1, s1, 0
	global_load_dwordx4 v[48:51], v5, s[0:1] nt
	s_add_u32 s0, s0, s6
	s_addc_u32 s1, s1, 0
	global_load_dwordx4 v[52:55], v5, s[0:1] nt
	s_add_u32 s0, s0, s6
	s_addc_u32 s1, s1, 0
	global_load_dwordx4 v[56:59], v5, s[0:1] nt
	s_add_u32 s0, s0, s6
	s_addc_u32 s1, s1, 0
	global_load_dwordx4 v[60:63], v5, s[0:1] nt
	s_add_u32 s0, s0, s6
	s_addc_u32 s1, s1, 0
	global_load_dwordx4 v[64:67], v5, s[0:1] nt
	s_add_u32 s0, s0, s6
	s_addc_u32 s1, s1, 0
	global_load_dwordx4 v[68:71], v5, s[0:1] nt
	s_add_u32 s0, s0, s6
	s_addc_u32 s1, s1, 0
	s_add_u32 s20, s20, s23
	s_cmp_ge_u32 s20, 16384
	s_cbranch_scc1 .Ltp0_dr2
	s_cmp_lt_u32 s20, 8192
	s_cbranch_scc1 .Ltp0_r3_s0
	s_cmp_lt_u32 s20, 10240
	s_cbranch_scc1 .Ltp0_r3_s1
	s_sub_u32 s25, s20, 10240
	s_mul_i32 s27, s25, 0xaaab
	s_lshr_b32 s27, s27, 23
	s_mul_i32 s31, s27, 192
	s_sub_u32 s31, s25, s31
	s_mul_i32 s35, s27, 0x180000
	s_lshl_b32 s41, s31, 7
	s_add_u32 s35, s35, s41
	s_add_u32 s0, s70, s35
	s_addc_u32 s1, s71, 0
	s_lshl_b32 s35, s31, 5
	s_mov_b32 s52, 0
	s_cmp_ge_u32 s31, 128
	s_cbranch_scc1 .Ltp0_r3_np
	s_and_b32 s41, s35, 32
	s_lshl_b32 s41, s41, 1
	s_and_b32 s52, s35, 64
	s_lshr_b32 s52, s52, 4
	s_add_u32 s41, s41, s52
	s_andn2_b32 s35, s35, 0x7f
	s_add_u32 s35, s35, s41
	s_mov_b32 s52, 1
.Ltp0_r3_np:
	s_mul_i32 s35, s35, 0x1000
	s_lshl_b32 s41, s27, 7
	s_add_u32 s35, s35, s41
	s_add_u32 s42, s82, s35
	s_addc_u32 s43, s83, 0
	s_mov_b32 s5, 0x6000
	s_mov_b32 s6, 0x30000
	s_mov_b32 s44, 0x1000
	s_branch .Ltp0_r3_e
.Ltp0_r3_s1:
	s_sub_u32 s25, s20, 8192
	s_lshr_b32 s27, s25, 6
	s_and_b32 s31, s25, 63
	s_mul_i32 s35, s27, 0x80000
	s_lshl_b32 s41, s31, 7
	s_add_u32 s35, s35, s41
	s_add_u32 s0, s66, s35
	s_addc_u32 s1, s67, 0
	s_mov_b32 s52, 0
	s_mul_i32 s35, s31, 0x20000
	s_lshl_b32 s41, s27, 7
	s_add_u32 s35, s35, s41
	s_add_u32 s42, s68, s35
	s_addc_u32 s43, s69, 0
	s_mov_b32 s5, 0x2000
	s_mov_b32 s6, 0x10000
	s_mov_b32 s44, 0x1000
	s_branch .Ltp0_r3_e
.Ltp0_r3_s0:
	s_sub_u32 s25, s20, 0
	s_lshr_b32 s27, s25, 8
	s_and_b32 s31, s25, 255
	s_mul_i32 s35, s27, 0x200000
	s_lshl_b32 s41, s31, 7
	s_add_u32 s35, s35, s41
	s_add_u32 s0, s62, s35
	s_addc_u32 s1, s63, 0
	s_mov_b32 s52, 0
	s_mul_i32 s35, s31, 0x20000
	s_lshl_b32 s41, s27, 7
	s_add_u32 s35, s35, s41
	s_add_u32 s42, s64, s35
	s_addc_u32 s43, s65, 0
	s_mov_b32 s5, 0x8000
	s_mov_b32 s6, 0x40000
	s_mov_b32 s44, 0x1000
.Ltp0_r3_e:
	v_mad_u32_u24 v5, v1, s5, v2
	global_load_dwordx4 v[72:75], v5, s[0:1] nt
	s_add_u32 s0, s0, s6
	s_addc_u32 s1, s1, 0
	global_load_dwordx4 v[76:79], v5, s[0:1] nt
	s_add_u32 s0, s0, s6
	s_addc_u32 s1, s1, 0
	global_load_dwordx4 v[80:83], v5, s[0:1] nt
	s_add_u32 s0, s0, s6
	s_addc_u32 s1, s1, 0
	global_load_dwordx4 v[84:87], v5, s[0:1] nt
	s_add_u32 s0, s0, s6
	s_addc_u32 s1, s1, 0
	global_load_dwordx4 v[88:91], v5, s[0:1] nt
	s_add_u32 s0, s0, s6
	s_addc_u32 s1, s1, 0
	global_load_dwordx4 v[92:95], v5, s[0:1] nt
	s_add_u32 s0, s0, s6
	s_addc_u32 s1, s1, 0
	global_load_dwordx4 v[96:99], v5, s[0:1] nt
	s_add_u32 s0, s0, s6
	s_addc_u32 s1, s1, 0
	global_load_dwordx4 v[100:103], v5, s[0:1] nt
	s_add_u32 s0, s0, s6
	s_addc_u32 s1, s1, 0
	s_add_u32 s20, s20, s23
	s_waitcnt vmcnt(16)
	ds_write_b32 v3, v8 offset:0
	ds_write_b32 v3, v9 offset:4
	ds_write_b32 v3, v10 offset:8
	ds_write_b32 v3, v11 offset:12
	ds_write_b32 v3, v12 offset:1056
	ds_write_b32 v3, v13 offset:1060
	ds_write_b32 v3, v14 offset:1064
	ds_write_b32 v3, v15 offset:1068
	ds_write_b32 v3, v16 offset:2112
	ds_write_b32 v3, v17 offset:2116
	ds_write_b32 v3, v18 offset:2120
	ds_write_b32 v3, v19 offset:2124
	ds_write_b32 v3, v20 offset:3168
	ds_write_b32 v3, v21 offset:3172
	ds_write_b32 v3, v22 offset:3176
	ds_write_b32 v3, v23 offset:3180
	ds_write_b32 v3, v24 offset:4224
	ds_write_b32 v3, v25 offset:4228
	ds_write_b32 v3, v26 offset:4232
	ds_write_b32 v3, v27 offset:4236
	ds_write_b32 v3, v28 offset:5280
	ds_write_b32 v3, v29 offset:5284
	ds_write_b32 v3, v30 offset:5288
	ds_write_b32 v3, v31 offset:5292
	ds_write_b32 v3, v32 offset:6336
	ds_write_b32 v3, v33 offset:6340
	ds_write_b32 v3, v34 offset:6344
	ds_write_b32 v3, v35 offset:6348
	ds_write_b32 v3, v36 offset:7392
	ds_write_b32 v3, v37 offset:7396
	ds_write_b32 v3, v38 offset:7400
	ds_write_b32 v3, v39 offset:7404
	s_mov_b32 s32, s2
	s_mov_b32 s33, s3
	s_lshl_b32 s49, s7, 3
	s_lshl_b32 s41, s49, 1
	s_cmp_lg_u32 s45, 0
	s_cselect_b64 vcc, -1, 0
	s_cselect_b32 s49, s41, s49
	v_cndmask_b32_e32 v6, v1, v7, vcc
	v_mad_u32_u24 v6, v6, s7, v2
	s_waitcnt lgkmcnt(0)
	ds_read_b32 v104, v4 offset:0
	ds_read_b32 v105, v4 offset:132
	ds_read_b32 v106, v4 offset:264
	ds_read_b32 v107, v4 offset:396
	ds_read_b32 v108, v4 offset:528
	ds_read_b32 v109, v4 offset:660
	ds_read_b32 v110, v4 offset:792
	ds_read_b32 v111, v4 offset:924
	ds_read_b32 v112, v4 offset:32
	ds_read_b32 v113, v4 offset:164
	ds_read_b32 v114, v4 offset:296
	ds_read_b32 v115, v4 offset:428
	ds_read_b32 v116, v4 offset:560
	ds_read_b32 v117, v4 offset:692
	ds_read_b32 v118, v4 offset:824
	ds_read_b32 v119, v4 offset:956
	s_waitcnt lgkmcnt(8)
	v_cvt_pk_bf16_f32 v136, v104, v105
	v_cvt_pk_bf16_f32 v137, v106, v107
	v_cvt_pk_bf16_f32 v138, v108, v109
	v_cvt_pk_bf16_f32 v139, v110, v111
	global_store_dwordx4 v6, v[136:139], s[32:33] nt
	s_add_u32 s32, s32, s49
	s_addc_u32 s33, s33, 0
	ds_read_b32 v120, v4 offset:64
	ds_read_b32 v121, v4 offset:196
	ds_read_b32 v122, v4 offset:328
	ds_read_b32 v123, v4 offset:460
	ds_read_b32 v124, v4 offset:592
	ds_read_b32 v125, v4 offset:724
	ds_read_b32 v126, v4 offset:856
	ds_read_b32 v127, v4 offset:988
	s_waitcnt lgkmcnt(8)
	v_cvt_pk_bf16_f32 v140, v112, v113
	v_cvt_pk_bf16_f32 v141, v114, v115
	v_cvt_pk_bf16_f32 v142, v116, v117
	v_cvt_pk_bf16_f32 v143, v118, v119
	global_store_dwordx4 v6, v[140:143], s[32:33] nt
	s_add_u32 s32, s32, s49
	s_addc_u32 s33, s33, 0
	ds_read_b32 v128, v4 offset:96
	ds_read_b32 v129, v4 offset:228
	ds_read_b32 v130, v4 offset:360
	ds_read_b32 v131, v4 offset:492
	ds_read_b32 v132, v4 offset:624
	ds_read_b32 v133, v4 offset:756
	ds_read_b32 v134, v4 offset:888
	ds_read_b32 v135, v4 offset:1020
	s_waitcnt lgkmcnt(8)
	v_cvt_pk_bf16_f32 v136, v120, v121
	v_cvt_pk_bf16_f32 v137, v122, v123
	v_cvt_pk_bf16_f32 v138, v124, v125
	v_cvt_pk_bf16_f32 v139, v126, v127
	global_store_dwordx4 v6, v[136:139], s[32:33] nt
	s_add_u32 s32, s32, s49
	s_addc_u32 s33, s33, 0
	s_waitcnt lgkmcnt(0)
	v_cvt_pk_bf16_f32 v140, v128, v129
	v_cvt_pk_bf16_f32 v141, v130, v131
	v_cvt_pk_bf16_f32 v142, v132, v133
	v_cvt_pk_bf16_f32 v143, v134, v135
	global_store_dwordx4 v6, v[140:143], s[32:33] nt
	s_add_u32 s32, s32, s49
	s_addc_u32 s33, s33, 0
	s_cmp_ge_u32 s20, 16384
	s_cbranch_scc1 .Ltp0_dr3
	s_cmp_lt_u32 s20, 8192
	s_cbranch_scc1 .Ltp0_r4_s0
	s_cmp_lt_u32 s20, 10240
	s_cbranch_scc1 .Ltp0_r4_s1
	s_sub_u32 s25, s20, 10240
	s_mul_i32 s27, s25, 0xaaab
	s_lshr_b32 s27, s27, 23
	s_mul_i32 s31, s27, 192
	s_sub_u32 s31, s25, s31
	s_mul_i32 s35, s27, 0x180000
	s_lshl_b32 s41, s31, 7
	s_add_u32 s35, s35, s41
	s_add_u32 s0, s70, s35
	s_addc_u32 s1, s71, 0
	s_lshl_b32 s35, s31, 5
	s_mov_b32 s45, 0
	s_cmp_ge_u32 s31, 128
	s_cbranch_scc1 .Ltp0_r4_np
	s_and_b32 s41, s35, 32
	s_lshl_b32 s41, s41, 1
	s_and_b32 s45, s35, 64
	s_lshr_b32 s45, s45, 4
	s_add_u32 s41, s41, s45
	s_andn2_b32 s35, s35, 0x7f
	s_add_u32 s35, s35, s41
	s_mov_b32 s45, 1

.Ltp0_r4_e:
	v_mad_u32_u24 v5, v1, s5, v2
	global_load_dwordx4 v[8:11], v5, s[0:1] nt
	s_add_u32 s0, s0, s6
	s_addc_u32 s1, s1, 0
	global_load_dwordx4 v[12:15], v5, s[0:1] nt
	s_add_u32 s0, s0, s6
	s_addc_u32 s1, s1, 0
	global_load_dwordx4 v[16:19], v5, s[0:1] nt
	s_add_u32 s0, s0, s6
	s_addc_u32 s1, s1, 0
	global_load_dwordx4 v[20:23], v5, s[0:1] nt
	s_add_u32 s0, s0, s6
	s_addc_u32 s1, s1, 0
	global_load_dwordx4 v[24:27], v5, s[0:1] nt
	s_add_u32 s0, s0, s6
	s_addc_u32 s1, s1, 0
	global_load_dwordx4 v[28:31], v5, s[0:1] nt
	s_add_u32 s0, s0, s6
	s_addc_u32 s1, s1, 0
	global_load_dwordx4 v[32:35], v5, s[0:1] nt
	s_add_u32 s0, s0, s6
	s_addc_u32 s1, s1, 0
	global_load_dwordx4 v[36:39], v5, s[0:1] nt
	s_add_u32 s0, s0, s6
	s_addc_u32 s1, s1, 0
	s_add_u32 s20, s20, s23
	s_waitcnt vmcnt(16)
	ds_write_b32 v3, v40 offset:0
	ds_write_b32 v3, v41 offset:4
	ds_write_b32 v3, v42 offset:8
	ds_write_b32 v3, v43 offset:12
	ds_write_b32 v3, v44 offset:1056
	ds_write_b32 v3, v45 offset:1060
	ds_write_b32 v3, v46 offset:1064
	ds_write_b32 v3, v47 offset:1068
	ds_write_b32 v3, v48 offset:2112
	ds_write_b32 v3, v49 offset:2116
	ds_write_b32 v3, v50 offset:2120
	ds_write_b32 v3, v51 offset:2124
	ds_write_b32 v3, v52 offset:3168
	ds_write_b32 v3, v53 offset:3172
	ds_write_b32 v3, v54 offset:3176
	ds_write_b32 v3, v55 offset:3180
	ds_write_b32 v3, v56 offset:4224
	ds_write_b32 v3, v57 offset:4228
	ds_write_b32 v3, v58 offset:4232
	ds_write_b32 v3, v59 offset:4236
	ds_write_b32 v3, v60 offset:5280
	ds_write_b32 v3, v61 offset:5284
	ds_write_b32 v3, v62 offset:5288
	ds_write_b32 v3, v63 offset:5292
	ds_write_b32 v3, v64 offset:6336
	ds_write_b32 v3, v65 offset:6340
	ds_write_b32 v3, v66 offset:6344
	ds_write_b32 v3, v67 offset:6348
	ds_write_b32 v3, v68 offset:7392
	ds_write_b32 v3, v69 offset:7396
	ds_write_b32 v3, v70 offset:7400
	ds_write_b32 v3, v71 offset:7404
	s_mov_b32 s32, s10
	s_mov_b32 s33, s11
	s_lshl_b32 s49, s47, 3
	s_lshl_b32 s41, s49, 1
	s_cmp_lg_u32 s50, 0
	s_cselect_b64 vcc, -1, 0
	s_cselect_b32 s49, s41, s49
	v_cndmask_b32_e32 v6, v1, v7, vcc
	v_mad_u32_u24 v6, v6, s47, v2
	s_waitcnt lgkmcnt(0)
	ds_read_b32 v104, v4 offset:0
	ds_read_b32 v105, v4 offset:132
	ds_read_b32 v106, v4 offset:264
	ds_read_b32 v107, v4 offset:396
	ds_read_b32 v108, v4 offset:528
	ds_read_b32 v109, v4 offset:660
	ds_read_b32 v110, v4 offset:792
	ds_read_b32 v111, v4 offset:924
	ds_read_b32 v112, v4 offset:32
	ds_read_b32 v113, v4 offset:164
	ds_read_b32 v114, v4 offset:296
	ds_read_b32 v115, v4 offset:428
	ds_read_b32 v116, v4 offset:560
	ds_read_b32 v117, v4 offset:692
	ds_read_b32 v118, v4 offset:824
	ds_read_b32 v119, v4 offset:956
	s_waitcnt lgkmcnt(8)
	v_cvt_pk_bf16_f32 v136, v104, v105
	v_cvt_pk_bf16_f32 v137, v106, v107
	v_cvt_pk_bf16_f32 v138, v108, v109
	v_cvt_pk_bf16_f32 v139, v110, v111
	global_store_dwordx4 v6, v[136:139], s[32:33] nt
	s_add_u32 s32, s32, s49
	s_addc_u32 s33, s33, 0
	ds_read_b32 v120, v4 offset:64
	ds_read_b32 v121, v4 offset:196
	ds_read_b32 v122, v4 offset:328
	ds_read_b32 v123, v4 offset:460
	ds_read_b32 v124, v4 offset:592
	ds_read_b32 v125, v4 offset:724
	ds_read_b32 v126, v4 offset:856
	ds_read_b32 v127, v4 offset:988
	s_waitcnt lgkmcnt(8)
	v_cvt_pk_bf16_f32 v140, v112, v113
	v_cvt_pk_bf16_f32 v141, v114, v115
	v_cvt_pk_bf16_f32 v142, v116, v117
	v_cvt_pk_bf16_f32 v143, v118, v119
	global_store_dwordx4 v6, v[140:143], s[32:33] nt
	s_add_u32 s32, s32, s49
	s_addc_u32 s33, s33, 0
	ds_read_b32 v128, v4 offset:96
	ds_read_b32 v129, v4 offset:228
	ds_read_b32 v130, v4 offset:360
	ds_read_b32 v131, v4 offset:492
	ds_read_b32 v132, v4 offset:624
	ds_read_b32 v133, v4 offset:756
	ds_read_b32 v134, v4 offset:888
	ds_read_b32 v135, v4 offset:1020
	s_waitcnt lgkmcnt(8)
	v_cvt_pk_bf16_f32 v136, v120, v121
	v_cvt_pk_bf16_f32 v137, v122, v123
	v_cvt_pk_bf16_f32 v138, v124, v125
	v_cvt_pk_bf16_f32 v139, v126, v127
	global_store_dwordx4 v6, v[136:139], s[32:33] nt
	s_add_u32 s32, s32, s49
	s_addc_u32 s33, s33, 0
	s_waitcnt lgkmcnt(0)
	v_cvt_pk_bf16_f32 v140, v128, v129
	v_cvt_pk_bf16_f32 v141, v130, v131
	v_cvt_pk_bf16_f32 v142, v132, v133
	v_cvt_pk_bf16_f32 v143, v134, v135
	global_store_dwordx4 v6, v[140:143], s[32:33] nt
	s_add_u32 s32, s32, s49
	s_addc_u32 s33, s33, 0
.Ltp0_loop:
	s_cmp_ge_u32 s20, 16384
	s_cbranch_scc1 .Ltp0_dr4
	s_cmp_lt_u32 s20, 8192
	s_cbranch_scc1 .Ltp0_r5_s0
	s_cmp_lt_u32 s20, 10240
	s_cbranch_scc1 .Ltp0_r5_s1
	s_sub_u32 s25, s20, 10240
	s_mul_i32 s27, s25, 0xaaab
	s_lshr_b32 s27, s27, 23
	s_mul_i32 s31, s27, 192
	s_sub_u32 s31, s25, s31
	s_mul_i32 s35, s27, 0x180000
	s_lshl_b32 s41, s31, 7
	s_add_u32 s35, s35, s41
	s_add_u32 s0, s70, s35
	s_addc_u32 s1, s71, 0
	s_lshl_b32 s35, s31, 5
	s_mov_b32 s50, 0
	s_cmp_ge_u32 s31, 128
	s_cbranch_scc1 .Ltp0_r5_np
	s_and_b32 s41, s35, 32
	s_lshl_b32 s41, s41, 1
	s_and_b32 s50, s35, 64
	s_lshr_b32 s50, s50, 4
	s_add_u32 s41, s41, s50
	s_andn2_b32 s35, s35, 0x7f
	s_add_u32 s35, s35, s41
	s_mov_b32 s50, 1

.Ltp0_r5_e:
	v_mad_u32_u24 v5, v1, s5, v2
	global_load_dwordx4 v[40:43], v5, s[0:1] nt
	s_add_u32 s0, s0, s6
	s_addc_u32 s1, s1, 0
	global_load_dwordx4 v[44:47], v5, s[0:1] nt
	s_add_u32 s0, s0, s6
	s_addc_u32 s1, s1, 0
	global_load_dwordx4 v[48:51], v5, s[0:1] nt
	s_add_u32 s0, s0, s6
	s_addc_u32 s1, s1, 0
	global_load_dwordx4 v[52:55], v5, s[0:1] nt
	s_add_u32 s0, s0, s6
	s_addc_u32 s1, s1, 0
	global_load_dwordx4 v[56:59], v5, s[0:1] nt
	s_add_u32 s0, s0, s6
	s_addc_u32 s1, s1, 0
	global_load_dwordx4 v[60:63], v5, s[0:1] nt
	s_add_u32 s0, s0, s6
	s_addc_u32 s1, s1, 0
	global_load_dwordx4 v[64:67], v5, s[0:1] nt
	s_add_u32 s0, s0, s6
	s_addc_u32 s1, s1, 0
	global_load_dwordx4 v[68:71], v5, s[0:1] nt
	s_add_u32 s0, s0, s6
	s_addc_u32 s1, s1, 0
	s_add_u32 s20, s20, s23
	s_waitcnt vmcnt(24)
	ds_write_b32 v3, v72 offset:0
	ds_write_b32 v3, v73 offset:4
	ds_write_b32 v3, v74 offset:8
	ds_write_b32 v3, v75 offset:12
	ds_write_b32 v3, v76 offset:1056
	ds_write_b32 v3, v77 offset:1060
	ds_write_b32 v3, v78 offset:1064
	ds_write_b32 v3, v79 offset:1068
	ds_write_b32 v3, v80 offset:2112
	ds_write_b32 v3, v81 offset:2116
	ds_write_b32 v3, v82 offset:2120
	ds_write_b32 v3, v83 offset:2124
	ds_write_b32 v3, v84 offset:3168
	ds_write_b32 v3, v85 offset:3172
	ds_write_b32 v3, v86 offset:3176
	ds_write_b32 v3, v87 offset:3180
	ds_write_b32 v3, v88 offset:4224
	ds_write_b32 v3, v89 offset:4228
	ds_write_b32 v3, v90 offset:4232
	ds_write_b32 v3, v91 offset:4236
	ds_write_b32 v3, v92 offset:5280
	ds_write_b32 v3, v93 offset:5284
	ds_write_b32 v3, v94 offset:5288
	ds_write_b32 v3, v95 offset:5292
	ds_write_b32 v3, v96 offset:6336
	ds_write_b32 v3, v97 offset:6340
	ds_write_b32 v3, v98 offset:6344
	ds_write_b32 v3, v99 offset:6348
	ds_write_b32 v3, v100 offset:7392
	ds_write_b32 v3, v101 offset:7396
	ds_write_b32 v3, v102 offset:7400
	ds_write_b32 v3, v103 offset:7404
	s_mov_b32 s32, s42
	s_mov_b32 s33, s43
	s_lshl_b32 s49, s44, 3
	s_lshl_b32 s41, s49, 1
	s_cmp_lg_u32 s52, 0
	s_cselect_b64 vcc, -1, 0
	s_cselect_b32 s49, s41, s49
	v_cndmask_b32_e32 v6, v1, v7, vcc
	v_mad_u32_u24 v6, v6, s44, v2
	s_waitcnt lgkmcnt(0)
	ds_read_b32 v104, v4 offset:0
	ds_read_b32 v105, v4 offset:132
	ds_read_b32 v106, v4 offset:264
	ds_read_b32 v107, v4 offset:396
	ds_read_b32 v108, v4 offset:528
	ds_read_b32 v109, v4 offset:660
	ds_read_b32 v110, v4 offset:792
	ds_read_b32 v111, v4 offset:924
	ds_read_b32 v112, v4 offset:32
	ds_read_b32 v113, v4 offset:164
	ds_read_b32 v114, v4 offset:296
	ds_read_b32 v115, v4 offset:428
	ds_read_b32 v116, v4 offset:560
	ds_read_b32 v117, v4 offset:692
	ds_read_b32 v118, v4 offset:824
	ds_read_b32 v119, v4 offset:956
	s_waitcnt lgkmcnt(8)
	v_cvt_pk_bf16_f32 v136, v104, v105
	v_cvt_pk_bf16_f32 v137, v106, v107
	v_cvt_pk_bf16_f32 v138, v108, v109
	v_cvt_pk_bf16_f32 v139, v110, v111
	global_store_dwordx4 v6, v[136:139], s[32:33] nt
	s_add_u32 s32, s32, s49
	s_addc_u32 s33, s33, 0
	ds_read_b32 v120, v4 offset:64
	ds_read_b32 v121, v4 offset:196
	ds_read_b32 v122, v4 offset:328
	ds_read_b32 v123, v4 offset:460
	ds_read_b32 v124, v4 offset:592
	ds_read_b32 v125, v4 offset:724
	ds_read_b32 v126, v4 offset:856
	ds_read_b32 v127, v4 offset:988
	s_waitcnt lgkmcnt(8)
	v_cvt_pk_bf16_f32 v140, v112, v113
	v_cvt_pk_bf16_f32 v141, v114, v115
	v_cvt_pk_bf16_f32 v142, v116, v117
	v_cvt_pk_bf16_f32 v143, v118, v119
	global_store_dwordx4 v6, v[140:143], s[32:33] nt
	s_add_u32 s32, s32, s49
	s_addc_u32 s33, s33, 0
	ds_read_b32 v128, v4 offset:96
	ds_read_b32 v129, v4 offset:228
	ds_read_b32 v130, v4 offset:360
	ds_read_b32 v131, v4 offset:492
	ds_read_b32 v132, v4 offset:624
	ds_read_b32 v133, v4 offset:756
	ds_read_b32 v134, v4 offset:888
	ds_read_b32 v135, v4 offset:1020
	s_waitcnt lgkmcnt(8)
	v_cvt_pk_bf16_f32 v136, v120, v121
	v_cvt_pk_bf16_f32 v137, v122, v123
	v_cvt_pk_bf16_f32 v138, v124, v125
	v_cvt_pk_bf16_f32 v139, v126, v127
	global_store_dwordx4 v6, v[136:139], s[32:33] nt
	s_add_u32 s32, s32, s49
	s_addc_u32 s33, s33, 0
	s_waitcnt lgkmcnt(0)
	v_cvt_pk_bf16_f32 v140, v128, v129
	v_cvt_pk_bf16_f32 v141, v130, v131
	v_cvt_pk_bf16_f32 v142, v132, v133
	v_cvt_pk_bf16_f32 v143, v134, v135
	global_store_dwordx4 v6, v[140:143], s[32:33] nt
	s_add_u32 s32, s32, s49
	s_addc_u32 s33, s33, 0
	s_cmp_ge_u32 s20, 16384
	s_cbranch_scc1 .Ltp0_dr5
	s_cmp_lt_u32 s20, 8192
	s_cbranch_scc1 .Ltp0_r6_s0
	s_cmp_lt_u32 s20, 10240
	s_cbranch_scc1 .Ltp0_r6_s1
	s_sub_u32 s25, s20, 10240
	s_mul_i32 s27, s25, 0xaaab
	s_lshr_b32 s27, s27, 23
	s_mul_i32 s31, s27, 192
	s_sub_u32 s31, s25, s31
	s_mul_i32 s35, s27, 0x180000
	s_lshl_b32 s41, s31, 7
	s_add_u32 s35, s35, s41
	s_add_u32 s0, s70, s35
	s_addc_u32 s1, s71, 0
	s_lshl_b32 s35, s31, 5
	s_mov_b32 s52, 0
	s_cmp_ge_u32 s31, 128
	s_cbranch_scc1 .Ltp0_r6_np
	s_and_b32 s41, s35, 32
	s_lshl_b32 s41, s41, 1
	s_and_b32 s52, s35, 64
	s_lshr_b32 s52, s52, 4
	s_add_u32 s41, s41, s52
	s_andn2_b32 s35, s35, 0x7f
	s_add_u32 s35, s35, s41
	s_mov_b32 s52, 1

.Ltp0_r6_e:
	v_mad_u32_u24 v5, v1, s5, v2
	global_load_dwordx4 v[72:75], v5, s[0:1] nt
	s_add_u32 s0, s0, s6
	s_addc_u32 s1, s1, 0
	global_load_dwordx4 v[76:79], v5, s[0:1] nt
	s_add_u32 s0, s0, s6
	s_addc_u32 s1, s1, 0
	global_load_dwordx4 v[80:83], v5, s[0:1] nt
	s_add_u32 s0, s0, s6
	s_addc_u32 s1, s1, 0
	global_load_dwordx4 v[84:87], v5, s[0:1] nt
	s_add_u32 s0, s0, s6
	s_addc_u32 s1, s1, 0
	global_load_dwordx4 v[88:91], v5, s[0:1] nt
	s_add_u32 s0, s0, s6
	s_addc_u32 s1, s1, 0
	global_load_dwordx4 v[92:95], v5, s[0:1] nt
	s_add_u32 s0, s0, s6
	s_addc_u32 s1, s1, 0
	global_load_dwordx4 v[96:99], v5, s[0:1] nt
	s_add_u32 s0, s0, s6
	s_addc_u32 s1, s1, 0
	global_load_dwordx4 v[100:103], v5, s[0:1] nt
	s_add_u32 s0, s0, s6
	s_addc_u32 s1, s1, 0
	s_add_u32 s20, s20, s23
	s_waitcnt vmcnt(24)
	ds_write_b32 v3, v8 offset:0
	ds_write_b32 v3, v9 offset:4
	ds_write_b32 v3, v10 offset:8
	ds_write_b32 v3, v11 offset:12
	ds_write_b32 v3, v12 offset:1056
	ds_write_b32 v3, v13 offset:1060
	ds_write_b32 v3, v14 offset:1064
	ds_write_b32 v3, v15 offset:1068
	ds_write_b32 v3, v16 offset:2112
	ds_write_b32 v3, v17 offset:2116
	ds_write_b32 v3, v18 offset:2120
	ds_write_b32 v3, v19 offset:2124
	ds_write_b32 v3, v20 offset:3168
	ds_write_b32 v3, v21 offset:3172
	ds_write_b32 v3, v22 offset:3176
	ds_write_b32 v3, v23 offset:3180
	ds_write_b32 v3, v24 offset:4224
	ds_write_b32 v3, v25 offset:4228
	ds_write_b32 v3, v26 offset:4232
	ds_write_b32 v3, v27 offset:4236
	ds_write_b32 v3, v28 offset:5280
	ds_write_b32 v3, v29 offset:5284
	ds_write_b32 v3, v30 offset:5288
	ds_write_b32 v3, v31 offset:5292
	ds_write_b32 v3, v32 offset:6336
	ds_write_b32 v3, v33 offset:6340
	ds_write_b32 v3, v34 offset:6344
	ds_write_b32 v3, v35 offset:6348
	ds_write_b32 v3, v36 offset:7392
	ds_write_b32 v3, v37 offset:7396
	ds_write_b32 v3, v38 offset:7400
	ds_write_b32 v3, v39 offset:7404
	s_mov_b32 s32, s2
	s_mov_b32 s33, s3
	s_lshl_b32 s49, s7, 3
	s_lshl_b32 s41, s49, 1
	s_cmp_lg_u32 s45, 0
	s_cselect_b64 vcc, -1, 0
	s_cselect_b32 s49, s41, s49
	v_cndmask_b32_e32 v6, v1, v7, vcc
	v_mad_u32_u24 v6, v6, s7, v2
	s_waitcnt lgkmcnt(0)
	ds_read_b32 v104, v4 offset:0
	ds_read_b32 v105, v4 offset:132
	ds_read_b32 v106, v4 offset:264
	ds_read_b32 v107, v4 offset:396
	ds_read_b32 v108, v4 offset:528
	ds_read_b32 v109, v4 offset:660
	ds_read_b32 v110, v4 offset:792
	ds_read_b32 v111, v4 offset:924
	ds_read_b32 v112, v4 offset:32
	ds_read_b32 v113, v4 offset:164
	ds_read_b32 v114, v4 offset:296
	ds_read_b32 v115, v4 offset:428
	ds_read_b32 v116, v4 offset:560
	ds_read_b32 v117, v4 offset:692
	ds_read_b32 v118, v4 offset:824
	ds_read_b32 v119, v4 offset:956
	s_waitcnt lgkmcnt(8)
	v_cvt_pk_bf16_f32 v136, v104, v105
	v_cvt_pk_bf16_f32 v137, v106, v107
	v_cvt_pk_bf16_f32 v138, v108, v109
	v_cvt_pk_bf16_f32 v139, v110, v111
	global_store_dwordx4 v6, v[136:139], s[32:33] nt
	s_add_u32 s32, s32, s49
	s_addc_u32 s33, s33, 0
	ds_read_b32 v120, v4 offset:64
	ds_read_b32 v121, v4 offset:196
	ds_read_b32 v122, v4 offset:328
	ds_read_b32 v123, v4 offset:460
	ds_read_b32 v124, v4 offset:592
	ds_read_b32 v125, v4 offset:724
	ds_read_b32 v126, v4 offset:856
	ds_read_b32 v127, v4 offset:988
	s_waitcnt lgkmcnt(8)
	v_cvt_pk_bf16_f32 v140, v112, v113
	v_cvt_pk_bf16_f32 v141, v114, v115
	v_cvt_pk_bf16_f32 v142, v116, v117
	v_cvt_pk_bf16_f32 v143, v118, v119
	global_store_dwordx4 v6, v[140:143], s[32:33] nt
	s_add_u32 s32, s32, s49
	s_addc_u32 s33, s33, 0
	ds_read_b32 v128, v4 offset:96
	ds_read_b32 v129, v4 offset:228
	ds_read_b32 v130, v4 offset:360
	ds_read_b32 v131, v4 offset:492
	ds_read_b32 v132, v4 offset:624
	ds_read_b32 v133, v4 offset:756
	ds_read_b32 v134, v4 offset:888
	ds_read_b32 v135, v4 offset:1020
	s_waitcnt lgkmcnt(8)
	v_cvt_pk_bf16_f32 v136, v120, v121
	v_cvt_pk_bf16_f32 v137, v122, v123
	v_cvt_pk_bf16_f32 v138, v124, v125
	v_cvt_pk_bf16_f32 v139, v126, v127
	global_store_dwordx4 v6, v[136:139], s[32:33] nt
	s_add_u32 s32, s32, s49
	s_addc_u32 s33, s33, 0
	s_waitcnt lgkmcnt(0)
	v_cvt_pk_bf16_f32 v140, v128, v129
	v_cvt_pk_bf16_f32 v141, v130, v131
	v_cvt_pk_bf16_f32 v142, v132, v133
	v_cvt_pk_bf16_f32 v143, v134, v135
	global_store_dwordx4 v6, v[140:143], s[32:33] nt
	s_add_u32 s32, s32, s49
	s_addc_u32 s33, s33, 0
	s_cmp_ge_u32 s20, 16384
	s_cbranch_scc1 .Ltp0_dr6
	s_cmp_lt_u32 s20, 8192
	s_cbranch_scc1 .Ltp0_r7_s0
	s_cmp_lt_u32 s20, 10240
	s_cbranch_scc1 .Ltp0_r7_s1
	s_sub_u32 s25, s20, 10240
	s_mul_i32 s27, s25, 0xaaab
	s_lshr_b32 s27, s27, 23
	s_mul_i32 s31, s27, 192
	s_sub_u32 s31, s25, s31
	s_mul_i32 s35, s27, 0x180000
	s_lshl_b32 s41, s31, 7
	s_add_u32 s35, s35, s41
	s_add_u32 s0, s70, s35
	s_addc_u32 s1, s71, 0
	s_lshl_b32 s35, s31, 5
	s_mov_b32 s45, 0
	s_cmp_ge_u32 s31, 128
	s_cbranch_scc1 .Ltp0_r7_np
	s_and_b32 s41, s35, 32
	s_lshl_b32 s41, s41, 1
	s_and_b32 s45, s35, 64
	s_lshr_b32 s45, s45, 4
	s_add_u32 s41, s41, s45
	s_andn2_b32 s35, s35, 0x7f
	s_add_u32 s35, s35, s41
	s_mov_b32 s45, 1

.Ltp0_r7_e:
	v_mad_u32_u24 v5, v1, s5, v2
	global_load_dwordx4 v[8:11], v5, s[0:1] nt
	s_add_u32 s0, s0, s6
	s_addc_u32 s1, s1, 0
	global_load_dwordx4 v[12:15], v5, s[0:1] nt
	s_add_u32 s0, s0, s6
	s_addc_u32 s1, s1, 0
	global_load_dwordx4 v[16:19], v5, s[0:1] nt
	s_add_u32 s0, s0, s6
	s_addc_u32 s1, s1, 0
	global_load_dwordx4 v[20:23], v5, s[0:1] nt
	s_add_u32 s0, s0, s6
	s_addc_u32 s1, s1, 0
	global_load_dwordx4 v[24:27], v5, s[0:1] nt
	s_add_u32 s0, s0, s6
	s_addc_u32 s1, s1, 0
	global_load_dwordx4 v[28:31], v5, s[0:1] nt
	s_add_u32 s0, s0, s6
	s_addc_u32 s1, s1, 0
	global_load_dwordx4 v[32:35], v5, s[0:1] nt
	s_add_u32 s0, s0, s6
	s_addc_u32 s1, s1, 0
	global_load_dwordx4 v[36:39], v5, s[0:1] nt
	s_add_u32 s0, s0, s6
	s_addc_u32 s1, s1, 0
	s_add_u32 s20, s20, s23
	s_waitcnt vmcnt(24)
	ds_write_b32 v3, v40 offset:0
	ds_write_b32 v3, v41 offset:4
	ds_write_b32 v3, v42 offset:8
	ds_write_b32 v3, v43 offset:12
	ds_write_b32 v3, v44 offset:1056
	ds_write_b32 v3, v45 offset:1060
	ds_write_b32 v3, v46 offset:1064
	ds_write_b32 v3, v47 offset:1068
	ds_write_b32 v3, v48 offset:2112
	ds_write_b32 v3, v49 offset:2116
	ds_write_b32 v3, v50 offset:2120
	ds_write_b32 v3, v51 offset:2124
	ds_write_b32 v3, v52 offset:3168
	ds_write_b32 v3, v53 offset:3172
	ds_write_b32 v3, v54 offset:3176
	ds_write_b32 v3, v55 offset:3180
	ds_write_b32 v3, v56 offset:4224
	ds_write_b32 v3, v57 offset:4228
	ds_write_b32 v3, v58 offset:4232
	ds_write_b32 v3, v59 offset:4236
	ds_write_b32 v3, v60 offset:5280
	ds_write_b32 v3, v61 offset:5284
	ds_write_b32 v3, v62 offset:5288
	ds_write_b32 v3, v63 offset:5292
	ds_write_b32 v3, v64 offset:6336
	ds_write_b32 v3, v65 offset:6340
	ds_write_b32 v3, v66 offset:6344
	ds_write_b32 v3, v67 offset:6348
	ds_write_b32 v3, v68 offset:7392
	ds_write_b32 v3, v69 offset:7396
	ds_write_b32 v3, v70 offset:7400
	ds_write_b32 v3, v71 offset:7404
	s_mov_b32 s32, s10
	s_mov_b32 s33, s11
	s_lshl_b32 s49, s47, 3
	s_lshl_b32 s41, s49, 1
	s_cmp_lg_u32 s50, 0
	s_cselect_b64 vcc, -1, 0
	s_cselect_b32 s49, s41, s49
	v_cndmask_b32_e32 v6, v1, v7, vcc
	v_mad_u32_u24 v6, v6, s47, v2
	s_waitcnt lgkmcnt(0)
	ds_read_b32 v104, v4 offset:0
	ds_read_b32 v105, v4 offset:132
	ds_read_b32 v106, v4 offset:264
	ds_read_b32 v107, v4 offset:396
	ds_read_b32 v108, v4 offset:528
	ds_read_b32 v109, v4 offset:660
	ds_read_b32 v110, v4 offset:792
	ds_read_b32 v111, v4 offset:924
	ds_read_b32 v112, v4 offset:32
	ds_read_b32 v113, v4 offset:164
	ds_read_b32 v114, v4 offset:296
	ds_read_b32 v115, v4 offset:428
	ds_read_b32 v116, v4 offset:560
	ds_read_b32 v117, v4 offset:692
	ds_read_b32 v118, v4 offset:824
	ds_read_b32 v119, v4 offset:956
	s_waitcnt lgkmcnt(8)
	v_cvt_pk_bf16_f32 v136, v104, v105
	v_cvt_pk_bf16_f32 v137, v106, v107
	v_cvt_pk_bf16_f32 v138, v108, v109
	v_cvt_pk_bf16_f32 v139, v110, v111
	global_store_dwordx4 v6, v[136:139], s[32:33] nt
	s_add_u32 s32, s32, s49
	s_addc_u32 s33, s33, 0
	ds_read_b32 v120, v4 offset:64
	ds_read_b32 v121, v4 offset:196
	ds_read_b32 v122, v4 offset:328
	ds_read_b32 v123, v4 offset:460
	ds_read_b32 v124, v4 offset:592
	ds_read_b32 v125, v4 offset:724
	ds_read_b32 v126, v4 offset:856
	ds_read_b32 v127, v4 offset:988
	s_waitcnt lgkmcnt(8)
	v_cvt_pk_bf16_f32 v140, v112, v113
	v_cvt_pk_bf16_f32 v141, v114, v115
	v_cvt_pk_bf16_f32 v142, v116, v117
	v_cvt_pk_bf16_f32 v143, v118, v119
	global_store_dwordx4 v6, v[140:143], s[32:33] nt
	s_add_u32 s32, s32, s49
	s_addc_u32 s33, s33, 0
	ds_read_b32 v128, v4 offset:96
	ds_read_b32 v129, v4 offset:228
	ds_read_b32 v130, v4 offset:360
	ds_read_b32 v131, v4 offset:492
	ds_read_b32 v132, v4 offset:624
	ds_read_b32 v133, v4 offset:756
	ds_read_b32 v134, v4 offset:888
	ds_read_b32 v135, v4 offset:1020
	s_waitcnt lgkmcnt(8)
	v_cvt_pk_bf16_f32 v136, v120, v121
	v_cvt_pk_bf16_f32 v137, v122, v123
	v_cvt_pk_bf16_f32 v138, v124, v125
	v_cvt_pk_bf16_f32 v139, v126, v127
	global_store_dwordx4 v6, v[136:139], s[32:33] nt
	s_add_u32 s32, s32, s49
	s_addc_u32 s33, s33, 0
	s_waitcnt lgkmcnt(0)
	v_cvt_pk_bf16_f32 v140, v128, v129
	v_cvt_pk_bf16_f32 v141, v130, v131
	v_cvt_pk_bf16_f32 v142, v132, v133
	v_cvt_pk_bf16_f32 v143, v134, v135
	global_store_dwordx4 v6, v[140:143], s[32:33] nt
	s_add_u32 s32, s32, s49
	s_addc_u32 s33, s33, 0
	s_branch .Ltp0_loop
.Ltp0_dr1:
	s_waitcnt vmcnt(0)
	ds_write_b32 v3, v8 offset:0
	ds_write_b32 v3, v9 offset:4
	ds_write_b32 v3, v10 offset:8
	ds_write_b32 v3, v11 offset:12
	ds_write_b32 v3, v12 offset:1056
	ds_write_b32 v3, v13 offset:1060
	ds_write_b32 v3, v14 offset:1064
	ds_write_b32 v3, v15 offset:1068
	ds_write_b32 v3, v16 offset:2112
	ds_write_b32 v3, v17 offset:2116
	ds_write_b32 v3, v18 offset:2120
	ds_write_b32 v3, v19 offset:2124
	ds_write_b32 v3, v20 offset:3168
	ds_write_b32 v3, v21 offset:3172
	ds_write_b32 v3, v22 offset:3176
	ds_write_b32 v3, v23 offset:3180
	ds_write_b32 v3, v24 offset:4224
	ds_write_b32 v3, v25 offset:4228
	ds_write_b32 v3, v26 offset:4232
	ds_write_b32 v3, v27 offset:4236
	ds_write_b32 v3, v28 offset:5280
	ds_write_b32 v3, v29 offset:5284
	ds_write_b32 v3, v30 offset:5288
	ds_write_b32 v3, v31 offset:5292
	ds_write_b32 v3, v32 offset:6336
	ds_write_b32 v3, v33 offset:6340
	ds_write_b32 v3, v34 offset:6344
	ds_write_b32 v3, v35 offset:6348
	ds_write_b32 v3, v36 offset:7392
	ds_write_b32 v3, v37 offset:7396
	ds_write_b32 v3, v38 offset:7400
	ds_write_b32 v3, v39 offset:7404
	s_mov_b32 s32, s2
	s_mov_b32 s33, s3
	s_lshl_b32 s49, s7, 3
	s_lshl_b32 s41, s49, 1
	s_cmp_lg_u32 s45, 0
	s_cselect_b64 vcc, -1, 0
	s_cselect_b32 s49, s41, s49
	v_cndmask_b32_e32 v6, v1, v7, vcc
	v_mad_u32_u24 v6, v6, s7, v2
	s_waitcnt lgkmcnt(0)
	ds_read_b32 v104, v4 offset:0
	ds_read_b32 v105, v4 offset:132
	ds_read_b32 v106, v4 offset:264
	ds_read_b32 v107, v4 offset:396
	ds_read_b32 v108, v4 offset:528
	ds_read_b32 v109, v4 offset:660
	ds_read_b32 v110, v4 offset:792
	ds_read_b32 v111, v4 offset:924
	ds_read_b32 v112, v4 offset:32
	ds_read_b32 v113, v4 offset:164
	ds_read_b32 v114, v4 offset:296
	ds_read_b32 v115, v4 offset:428
	ds_read_b32 v116, v4 offset:560
	ds_read_b32 v117, v4 offset:692
	ds_read_b32 v118, v4 offset:824
	ds_read_b32 v119, v4 offset:956
	s_waitcnt lgkmcnt(8)
	v_cvt_pk_bf16_f32 v136, v104, v105
	v_cvt_pk_bf16_f32 v137, v106, v107
	v_cvt_pk_bf16_f32 v138, v108, v109
	v_cvt_pk_bf16_f32 v139, v110, v111
	global_store_dwordx4 v6, v[136:139], s[32:33] nt
	s_add_u32 s32, s32, s49
	s_addc_u32 s33, s33, 0
	ds_read_b32 v120, v4 offset:64
	ds_read_b32 v121, v4 offset:196
	ds_read_b32 v122, v4 offset:328
	ds_read_b32 v123, v4 offset:460
	ds_read_b32 v124, v4 offset:592
	ds_read_b32 v125, v4 offset:724
	ds_read_b32 v126, v4 offset:856
	ds_read_b32 v127, v4 offset:988
	s_waitcnt lgkmcnt(8)
	v_cvt_pk_bf16_f32 v140, v112, v113
	v_cvt_pk_bf16_f32 v141, v114, v115
	v_cvt_pk_bf16_f32 v142, v116, v117
	v_cvt_pk_bf16_f32 v143, v118, v119
	global_store_dwordx4 v6, v[140:143], s[32:33] nt
	s_add_u32 s32, s32, s49
	s_addc_u32 s33, s33, 0
	ds_read_b32 v128, v4 offset:96
	ds_read_b32 v129, v4 offset:228
	ds_read_b32 v130, v4 offset:360
	ds_read_b32 v131, v4 offset:492
	ds_read_b32 v132, v4 offset:624
	ds_read_b32 v133, v4 offset:756
	ds_read_b32 v134, v4 offset:888
	ds_read_b32 v135, v4 offset:1020
	s_waitcnt lgkmcnt(8)
	v_cvt_pk_bf16_f32 v136, v120, v121
	v_cvt_pk_bf16_f32 v137, v122, v123
	v_cvt_pk_bf16_f32 v138, v124, v125
	v_cvt_pk_bf16_f32 v139, v126, v127
	global_store_dwordx4 v6, v[136:139], s[32:33] nt
	s_add_u32 s32, s32, s49
	s_addc_u32 s33, s33, 0
	s_waitcnt lgkmcnt(0)
	v_cvt_pk_bf16_f32 v140, v128, v129
	v_cvt_pk_bf16_f32 v141, v130, v131
	v_cvt_pk_bf16_f32 v142, v132, v133
	v_cvt_pk_bf16_f32 v143, v134, v135
	global_store_dwordx4 v6, v[140:143], s[32:33] nt
	s_add_u32 s32, s32, s49
	s_addc_u32 s33, s33, 0
	s_branch .Ltp0_done
.Ltp0_dr2:
	s_waitcnt vmcnt(8)
	ds_write_b32 v3, v8 offset:0
	ds_write_b32 v3, v9 offset:4
	ds_write_b32 v3, v10 offset:8
	ds_write_b32 v3, v11 offset:12
	ds_write_b32 v3, v12 offset:1056
	ds_write_b32 v3, v13 offset:1060
	ds_write_b32 v3, v14 offset:1064
	ds_write_b32 v3, v15 offset:1068
	ds_write_b32 v3, v16 offset:2112
	ds_write_b32 v3, v17 offset:2116
	ds_write_b32 v3, v18 offset:2120
	ds_write_b32 v3, v19 offset:2124
	ds_write_b32 v3, v20 offset:3168
	ds_write_b32 v3, v21 offset:3172
	ds_write_b32 v3, v22 offset:3176
	ds_write_b32 v3, v23 offset:3180
	ds_write_b32 v3, v24 offset:4224
	ds_write_b32 v3, v25 offset:4228
	ds_write_b32 v3, v26 offset:4232
	ds_write_b32 v3, v27 offset:4236
	ds_write_b32 v3, v28 offset:5280
	ds_write_b32 v3, v29 offset:5284
	ds_write_b32 v3, v30 offset:5288
	ds_write_b32 v3, v31 offset:5292
	ds_write_b32 v3, v32 offset:6336
	ds_write_b32 v3, v33 offset:6340
	ds_write_b32 v3, v34 offset:6344
	ds_write_b32 v3, v35 offset:6348
	ds_write_b32 v3, v36 offset:7392
	ds_write_b32 v3, v37 offset:7396
	ds_write_b32 v3, v38 offset:7400
	ds_write_b32 v3, v39 offset:7404
	s_mov_b32 s32, s2
	s_mov_b32 s33, s3
	s_lshl_b32 s49, s7, 3
	s_lshl_b32 s41, s49, 1
	s_cmp_lg_u32 s45, 0
	s_cselect_b64 vcc, -1, 0
	s_cselect_b32 s49, s41, s49
	v_cndmask_b32_e32 v6, v1, v7, vcc
	v_mad_u32_u24 v6, v6, s7, v2
	s_waitcnt lgkmcnt(0)
	ds_read_b32 v104, v4 offset:0
	ds_read_b32 v105, v4 offset:132
	ds_read_b32 v106, v4 offset:264
	ds_read_b32 v107, v4 offset:396
	ds_read_b32 v108, v4 offset:528
	ds_read_b32 v109, v4 offset:660
	ds_read_b32 v110, v4 offset:792
	ds_read_b32 v111, v4 offset:924
	ds_read_b32 v112, v4 offset:32
	ds_read_b32 v113, v4 offset:164
	ds_read_b32 v114, v4 offset:296
	ds_read_b32 v115, v4 offset:428
	ds_read_b32 v116, v4 offset:560
	ds_read_b32 v117, v4 offset:692
	ds_read_b32 v118, v4 offset:824
	ds_read_b32 v119, v4 offset:956
	s_waitcnt lgkmcnt(8)
	v_cvt_pk_bf16_f32 v136, v104, v105
	v_cvt_pk_bf16_f32 v137, v106, v107
	v_cvt_pk_bf16_f32 v138, v108, v109
	v_cvt_pk_bf16_f32 v139, v110, v111
	global_store_dwordx4 v6, v[136:139], s[32:33] nt
	s_add_u32 s32, s32, s49
	s_addc_u32 s33, s33, 0
	ds_read_b32 v120, v4 offset:64
	ds_read_b32 v121, v4 offset:196
	ds_read_b32 v122, v4 offset:328
	ds_read_b32 v123, v4 offset:460
	ds_read_b32 v124, v4 offset:592
	ds_read_b32 v125, v4 offset:724
	ds_read_b32 v126, v4 offset:856
	ds_read_b32 v127, v4 offset:988
	s_waitcnt lgkmcnt(8)
	v_cvt_pk_bf16_f32 v140, v112, v113
	v_cvt_pk_bf16_f32 v141, v114, v115
	v_cvt_pk_bf16_f32 v142, v116, v117
	v_cvt_pk_bf16_f32 v143, v118, v119
	global_store_dwordx4 v6, v[140:143], s[32:33] nt
	s_add_u32 s32, s32, s49
	s_addc_u32 s33, s33, 0
	ds_read_b32 v128, v4 offset:96
	ds_read_b32 v129, v4 offset:228
	ds_read_b32 v130, v4 offset:360
	ds_read_b32 v131, v4 offset:492
	ds_read_b32 v132, v4 offset:624
	ds_read_b32 v133, v4 offset:756
	ds_read_b32 v134, v4 offset:888
	ds_read_b32 v135, v4 offset:1020
	s_waitcnt lgkmcnt(8)
	v_cvt_pk_bf16_f32 v136, v120, v121
	v_cvt_pk_bf16_f32 v137, v122, v123
	v_cvt_pk_bf16_f32 v138, v124, v125
	v_cvt_pk_bf16_f32 v139, v126, v127
	global_store_dwordx4 v6, v[136:139], s[32:33] nt
	s_add_u32 s32, s32, s49
	s_addc_u32 s33, s33, 0
	s_waitcnt lgkmcnt(0)
	v_cvt_pk_bf16_f32 v140, v128, v129
	v_cvt_pk_bf16_f32 v141, v130, v131
	v_cvt_pk_bf16_f32 v142, v132, v133
	v_cvt_pk_bf16_f32 v143, v134, v135
	global_store_dwordx4 v6, v[140:143], s[32:33] nt
	s_add_u32 s32, s32, s49
	s_addc_u32 s33, s33, 0
	s_waitcnt vmcnt(0)
	ds_write_b32 v3, v40 offset:0
	ds_write_b32 v3, v41 offset:4
	ds_write_b32 v3, v42 offset:8
	ds_write_b32 v3, v43 offset:12
	ds_write_b32 v3, v44 offset:1056
	ds_write_b32 v3, v45 offset:1060
	ds_write_b32 v3, v46 offset:1064
	ds_write_b32 v3, v47 offset:1068
	ds_write_b32 v3, v48 offset:2112
	ds_write_b32 v3, v49 offset:2116
	ds_write_b32 v3, v50 offset:2120
	ds_write_b32 v3, v51 offset:2124
	ds_write_b32 v3, v52 offset:3168
	ds_write_b32 v3, v53 offset:3172
	ds_write_b32 v3, v54 offset:3176
	ds_write_b32 v3, v55 offset:3180
	ds_write_b32 v3, v56 offset:4224
	ds_write_b32 v3, v57 offset:4228
	ds_write_b32 v3, v58 offset:4232
	ds_write_b32 v3, v59 offset:4236
	ds_write_b32 v3, v60 offset:5280
	ds_write_b32 v3, v61 offset:5284
	ds_write_b32 v3, v62 offset:5288
	ds_write_b32 v3, v63 offset:5292
	ds_write_b32 v3, v64 offset:6336
	ds_write_b32 v3, v65 offset:6340
	ds_write_b32 v3, v66 offset:6344
	ds_write_b32 v3, v67 offset:6348
	ds_write_b32 v3, v68 offset:7392
	ds_write_b32 v3, v69 offset:7396
	ds_write_b32 v3, v70 offset:7400
	ds_write_b32 v3, v71 offset:7404
	s_mov_b32 s32, s10
	s_mov_b32 s33, s11
	s_lshl_b32 s49, s47, 3
	s_lshl_b32 s41, s49, 1
	s_cmp_lg_u32 s50, 0
	s_cselect_b64 vcc, -1, 0
	s_cselect_b32 s49, s41, s49
	v_cndmask_b32_e32 v6, v1, v7, vcc
	v_mad_u32_u24 v6, v6, s47, v2
	s_waitcnt lgkmcnt(0)
	ds_read_b32 v104, v4 offset:0
	ds_read_b32 v105, v4 offset:132
	ds_read_b32 v106, v4 offset:264
	ds_read_b32 v107, v4 offset:396
	ds_read_b32 v108, v4 offset:528
	ds_read_b32 v109, v4 offset:660
	ds_read_b32 v110, v4 offset:792
	ds_read_b32 v111, v4 offset:924
	ds_read_b32 v112, v4 offset:32
	ds_read_b32 v113, v4 offset:164
	ds_read_b32 v114, v4 offset:296
	ds_read_b32 v115, v4 offset:428
	ds_read_b32 v116, v4 offset:560
	ds_read_b32 v117, v4 offset:692
	ds_read_b32 v118, v4 offset:824
	ds_read_b32 v119, v4 offset:956
	s_waitcnt lgkmcnt(8)
	v_cvt_pk_bf16_f32 v136, v104, v105
	v_cvt_pk_bf16_f32 v137, v106, v107
	v_cvt_pk_bf16_f32 v138, v108, v109
	v_cvt_pk_bf16_f32 v139, v110, v111
	global_store_dwordx4 v6, v[136:139], s[32:33] nt
	s_add_u32 s32, s32, s49
	s_addc_u32 s33, s33, 0
	ds_read_b32 v120, v4 offset:64
	ds_read_b32 v121, v4 offset:196
	ds_read_b32 v122, v4 offset:328
	ds_read_b32 v123, v4 offset:460
	ds_read_b32 v124, v4 offset:592
	ds_read_b32 v125, v4 offset:724
	ds_read_b32 v126, v4 offset:856
	ds_read_b32 v127, v4 offset:988
	s_waitcnt lgkmcnt(8)
	v_cvt_pk_bf16_f32 v140, v112, v113
	v_cvt_pk_bf16_f32 v141, v114, v115
	v_cvt_pk_bf16_f32 v142, v116, v117
	v_cvt_pk_bf16_f32 v143, v118, v119
	global_store_dwordx4 v6, v[140:143], s[32:33] nt
	s_add_u32 s32, s32, s49
	s_addc_u32 s33, s33, 0
	ds_read_b32 v128, v4 offset:96
	ds_read_b32 v129, v4 offset:228
	ds_read_b32 v130, v4 offset:360
	ds_read_b32 v131, v4 offset:492
	ds_read_b32 v132, v4 offset:624
	ds_read_b32 v133, v4 offset:756
	ds_read_b32 v134, v4 offset:888
	ds_read_b32 v135, v4 offset:1020
	s_waitcnt lgkmcnt(8)
	v_cvt_pk_bf16_f32 v136, v120, v121
	v_cvt_pk_bf16_f32 v137, v122, v123
	v_cvt_pk_bf16_f32 v138, v124, v125
	v_cvt_pk_bf16_f32 v139, v126, v127
	global_store_dwordx4 v6, v[136:139], s[32:33] nt
	s_add_u32 s32, s32, s49
	s_addc_u32 s33, s33, 0
	s_waitcnt lgkmcnt(0)
	v_cvt_pk_bf16_f32 v140, v128, v129
	v_cvt_pk_bf16_f32 v141, v130, v131
	v_cvt_pk_bf16_f32 v142, v132, v133
	v_cvt_pk_bf16_f32 v143, v134, v135
	global_store_dwordx4 v6, v[140:143], s[32:33] nt
	s_add_u32 s32, s32, s49
	s_addc_u32 s33, s33, 0
	s_branch .Ltp0_done
.Ltp0_dr3:
	s_waitcnt vmcnt(8)
	ds_write_b32 v3, v40 offset:0
	ds_write_b32 v3, v41 offset:4
	ds_write_b32 v3, v42 offset:8
	ds_write_b32 v3, v43 offset:12
	ds_write_b32 v3, v44 offset:1056
	ds_write_b32 v3, v45 offset:1060
	ds_write_b32 v3, v46 offset:1064
	ds_write_b32 v3, v47 offset:1068
	ds_write_b32 v3, v48 offset:2112
	ds_write_b32 v3, v49 offset:2116
	ds_write_b32 v3, v50 offset:2120
	ds_write_b32 v3, v51 offset:2124
	ds_write_b32 v3, v52 offset:3168
	ds_write_b32 v3, v53 offset:3172
	ds_write_b32 v3, v54 offset:3176
	ds_write_b32 v3, v55 offset:3180
	ds_write_b32 v3, v56 offset:4224
	ds_write_b32 v3, v57 offset:4228
	ds_write_b32 v3, v58 offset:4232
	ds_write_b32 v3, v59 offset:4236
	ds_write_b32 v3, v60 offset:5280
	ds_write_b32 v3, v61 offset:5284
	ds_write_b32 v3, v62 offset:5288
	ds_write_b32 v3, v63 offset:5292
	ds_write_b32 v3, v64 offset:6336
	ds_write_b32 v3, v65 offset:6340
	ds_write_b32 v3, v66 offset:6344
	ds_write_b32 v3, v67 offset:6348
	ds_write_b32 v3, v68 offset:7392
	ds_write_b32 v3, v69 offset:7396
	ds_write_b32 v3, v70 offset:7400
	ds_write_b32 v3, v71 offset:7404
	s_mov_b32 s32, s10
	s_mov_b32 s33, s11
	s_lshl_b32 s49, s47, 3
	s_lshl_b32 s41, s49, 1
	s_cmp_lg_u32 s50, 0
	s_cselect_b64 vcc, -1, 0
	s_cselect_b32 s49, s41, s49
	v_cndmask_b32_e32 v6, v1, v7, vcc
	v_mad_u32_u24 v6, v6, s47, v2
	s_waitcnt lgkmcnt(0)
	ds_read_b32 v104, v4 offset:0
	ds_read_b32 v105, v4 offset:132
	ds_read_b32 v106, v4 offset:264
	ds_read_b32 v107, v4 offset:396
	ds_read_b32 v108, v4 offset:528
	ds_read_b32 v109, v4 offset:660
	ds_read_b32 v110, v4 offset:792
	ds_read_b32 v111, v4 offset:924
	ds_read_b32 v112, v4 offset:32
	ds_read_b32 v113, v4 offset:164
	ds_read_b32 v114, v4 offset:296
	ds_read_b32 v115, v4 offset:428
	ds_read_b32 v116, v4 offset:560
	ds_read_b32 v117, v4 offset:692
	ds_read_b32 v118, v4 offset:824
	ds_read_b32 v119, v4 offset:956
	s_waitcnt lgkmcnt(8)
	v_cvt_pk_bf16_f32 v136, v104, v105
	v_cvt_pk_bf16_f32 v137, v106, v107
	v_cvt_pk_bf16_f32 v138, v108, v109
	v_cvt_pk_bf16_f32 v139, v110, v111
	global_store_dwordx4 v6, v[136:139], s[32:33] nt
	s_add_u32 s32, s32, s49
	s_addc_u32 s33, s33, 0
	ds_read_b32 v120, v4 offset:64
	ds_read_b32 v121, v4 offset:196
	ds_read_b32 v122, v4 offset:328
	ds_read_b32 v123, v4 offset:460
	ds_read_b32 v124, v4 offset:592
	ds_read_b32 v125, v4 offset:724
	ds_read_b32 v126, v4 offset:856
	ds_read_b32 v127, v4 offset:988
	s_waitcnt lgkmcnt(8)
	v_cvt_pk_bf16_f32 v140, v112, v113
	v_cvt_pk_bf16_f32 v141, v114, v115
	v_cvt_pk_bf16_f32 v142, v116, v117
	v_cvt_pk_bf16_f32 v143, v118, v119
	global_store_dwordx4 v6, v[140:143], s[32:33] nt
	s_add_u32 s32, s32, s49
	s_addc_u32 s33, s33, 0
	ds_read_b32 v128, v4 offset:96
	ds_read_b32 v129, v4 offset:228
	ds_read_b32 v130, v4 offset:360
	ds_read_b32 v131, v4 offset:492
	ds_read_b32 v132, v4 offset:624
	ds_read_b32 v133, v4 offset:756
	ds_read_b32 v134, v4 offset:888
	ds_read_b32 v135, v4 offset:1020
	s_waitcnt lgkmcnt(8)
	v_cvt_pk_bf16_f32 v136, v120, v121
	v_cvt_pk_bf16_f32 v137, v122, v123
	v_cvt_pk_bf16_f32 v138, v124, v125
	v_cvt_pk_bf16_f32 v139, v126, v127
	global_store_dwordx4 v6, v[136:139], s[32:33] nt
	s_add_u32 s32, s32, s49
	s_addc_u32 s33, s33, 0
	s_waitcnt lgkmcnt(0)
	v_cvt_pk_bf16_f32 v140, v128, v129
	v_cvt_pk_bf16_f32 v141, v130, v131
	v_cvt_pk_bf16_f32 v142, v132, v133
	v_cvt_pk_bf16_f32 v143, v134, v135
	global_store_dwordx4 v6, v[140:143], s[32:33] nt
	s_add_u32 s32, s32, s49
	s_addc_u32 s33, s33, 0
	s_waitcnt vmcnt(0)
	ds_write_b32 v3, v72 offset:0
	ds_write_b32 v3, v73 offset:4
	ds_write_b32 v3, v74 offset:8
	ds_write_b32 v3, v75 offset:12
	ds_write_b32 v3, v76 offset:1056
	ds_write_b32 v3, v77 offset:1060
	ds_write_b32 v3, v78 offset:1064
	ds_write_b32 v3, v79 offset:1068
	ds_write_b32 v3, v80 offset:2112
	ds_write_b32 v3, v81 offset:2116
	ds_write_b32 v3, v82 offset:2120
	ds_write_b32 v3, v83 offset:2124
	ds_write_b32 v3, v84 offset:3168
	ds_write_b32 v3, v85 offset:3172
	ds_write_b32 v3, v86 offset:3176
	ds_write_b32 v3, v87 offset:3180
	ds_write_b32 v3, v88 offset:4224
	ds_write_b32 v3, v89 offset:4228
	ds_write_b32 v3, v90 offset:4232
	ds_write_b32 v3, v91 offset:4236
	ds_write_b32 v3, v92 offset:5280
	ds_write_b32 v3, v93 offset:5284
	ds_write_b32 v3, v94 offset:5288
	ds_write_b32 v3, v95 offset:5292
	ds_write_b32 v3, v96 offset:6336
	ds_write_b32 v3, v97 offset:6340
	ds_write_b32 v3, v98 offset:6344
	ds_write_b32 v3, v99 offset:6348
	ds_write_b32 v3, v100 offset:7392
	ds_write_b32 v3, v101 offset:7396
	ds_write_b32 v3, v102 offset:7400
	ds_write_b32 v3, v103 offset:7404
	s_mov_b32 s32, s42
	s_mov_b32 s33, s43
	s_lshl_b32 s49, s44, 3
	s_lshl_b32 s41, s49, 1
	s_cmp_lg_u32 s52, 0
	s_cselect_b64 vcc, -1, 0
	s_cselect_b32 s49, s41, s49
	v_cndmask_b32_e32 v6, v1, v7, vcc
	v_mad_u32_u24 v6, v6, s44, v2
	s_waitcnt lgkmcnt(0)
	ds_read_b32 v104, v4 offset:0
	ds_read_b32 v105, v4 offset:132
	ds_read_b32 v106, v4 offset:264
	ds_read_b32 v107, v4 offset:396
	ds_read_b32 v108, v4 offset:528
	ds_read_b32 v109, v4 offset:660
	ds_read_b32 v110, v4 offset:792
	ds_read_b32 v111, v4 offset:924
	ds_read_b32 v112, v4 offset:32
	ds_read_b32 v113, v4 offset:164
	ds_read_b32 v114, v4 offset:296
	ds_read_b32 v115, v4 offset:428
	ds_read_b32 v116, v4 offset:560
	ds_read_b32 v117, v4 offset:692
	ds_read_b32 v118, v4 offset:824
	ds_read_b32 v119, v4 offset:956
	s_waitcnt lgkmcnt(8)
	v_cvt_pk_bf16_f32 v136, v104, v105
	v_cvt_pk_bf16_f32 v137, v106, v107
	v_cvt_pk_bf16_f32 v138, v108, v109
	v_cvt_pk_bf16_f32 v139, v110, v111
	global_store_dwordx4 v6, v[136:139], s[32:33] nt
	s_add_u32 s32, s32, s49
	s_addc_u32 s33, s33, 0
	ds_read_b32 v120, v4 offset:64
	ds_read_b32 v121, v4 offset:196
	ds_read_b32 v122, v4 offset:328
	ds_read_b32 v123, v4 offset:460
	ds_read_b32 v124, v4 offset:592
	ds_read_b32 v125, v4 offset:724
	ds_read_b32 v126, v4 offset:856
	ds_read_b32 v127, v4 offset:988
	s_waitcnt lgkmcnt(8)
	v_cvt_pk_bf16_f32 v140, v112, v113
	v_cvt_pk_bf16_f32 v141, v114, v115
	v_cvt_pk_bf16_f32 v142, v116, v117
	v_cvt_pk_bf16_f32 v143, v118, v119
	global_store_dwordx4 v6, v[140:143], s[32:33] nt
	s_add_u32 s32, s32, s49
	s_addc_u32 s33, s33, 0
	ds_read_b32 v128, v4 offset:96
	ds_read_b32 v129, v4 offset:228
	ds_read_b32 v130, v4 offset:360
	ds_read_b32 v131, v4 offset:492
	ds_read_b32 v132, v4 offset:624
	ds_read_b32 v133, v4 offset:756
	ds_read_b32 v134, v4 offset:888
	ds_read_b32 v135, v4 offset:1020
	s_waitcnt lgkmcnt(8)
	v_cvt_pk_bf16_f32 v136, v120, v121
	v_cvt_pk_bf16_f32 v137, v122, v123
	v_cvt_pk_bf16_f32 v138, v124, v125
	v_cvt_pk_bf16_f32 v139, v126, v127
	global_store_dwordx4 v6, v[136:139], s[32:33] nt
	s_add_u32 s32, s32, s49
	s_addc_u32 s33, s33, 0
	s_waitcnt lgkmcnt(0)
	v_cvt_pk_bf16_f32 v140, v128, v129
	v_cvt_pk_bf16_f32 v141, v130, v131
	v_cvt_pk_bf16_f32 v142, v132, v133
	v_cvt_pk_bf16_f32 v143, v134, v135
	global_store_dwordx4 v6, v[140:143], s[32:33] nt
	s_add_u32 s32, s32, s49
	s_addc_u32 s33, s33, 0
	s_branch .Ltp0_done
.Ltp0_dr4:
	s_waitcnt vmcnt(8)
	ds_write_b32 v3, v72 offset:0
	ds_write_b32 v3, v73 offset:4
	ds_write_b32 v3, v74 offset:8
	ds_write_b32 v3, v75 offset:12
	ds_write_b32 v3, v76 offset:1056
	ds_write_b32 v3, v77 offset:1060
	ds_write_b32 v3, v78 offset:1064
	ds_write_b32 v3, v79 offset:1068
	ds_write_b32 v3, v80 offset:2112
	ds_write_b32 v3, v81 offset:2116
	ds_write_b32 v3, v82 offset:2120
	ds_write_b32 v3, v83 offset:2124
	ds_write_b32 v3, v84 offset:3168
	ds_write_b32 v3, v85 offset:3172
	ds_write_b32 v3, v86 offset:3176
	ds_write_b32 v3, v87 offset:3180
	ds_write_b32 v3, v88 offset:4224
	ds_write_b32 v3, v89 offset:4228
	ds_write_b32 v3, v90 offset:4232
	ds_write_b32 v3, v91 offset:4236
	ds_write_b32 v3, v92 offset:5280
	ds_write_b32 v3, v93 offset:5284
	ds_write_b32 v3, v94 offset:5288
	ds_write_b32 v3, v95 offset:5292
	ds_write_b32 v3, v96 offset:6336
	ds_write_b32 v3, v97 offset:6340
	ds_write_b32 v3, v98 offset:6344
	ds_write_b32 v3, v99 offset:6348
	ds_write_b32 v3, v100 offset:7392
	ds_write_b32 v3, v101 offset:7396
	ds_write_b32 v3, v102 offset:7400
	ds_write_b32 v3, v103 offset:7404
	s_mov_b32 s32, s42
	s_mov_b32 s33, s43
	s_lshl_b32 s49, s44, 3
	s_lshl_b32 s41, s49, 1
	s_cmp_lg_u32 s52, 0
	s_cselect_b64 vcc, -1, 0
	s_cselect_b32 s49, s41, s49
	v_cndmask_b32_e32 v6, v1, v7, vcc
	v_mad_u32_u24 v6, v6, s44, v2
	s_waitcnt lgkmcnt(0)
	ds_read_b32 v104, v4 offset:0
	ds_read_b32 v105, v4 offset:132
	ds_read_b32 v106, v4 offset:264
	ds_read_b32 v107, v4 offset:396
	ds_read_b32 v108, v4 offset:528
	ds_read_b32 v109, v4 offset:660
	ds_read_b32 v110, v4 offset:792
	ds_read_b32 v111, v4 offset:924
	ds_read_b32 v112, v4 offset:32
	ds_read_b32 v113, v4 offset:164
	ds_read_b32 v114, v4 offset:296
	ds_read_b32 v115, v4 offset:428
	ds_read_b32 v116, v4 offset:560
	ds_read_b32 v117, v4 offset:692
	ds_read_b32 v118, v4 offset:824
	ds_read_b32 v119, v4 offset:956
	s_waitcnt lgkmcnt(8)
	v_cvt_pk_bf16_f32 v136, v104, v105
	v_cvt_pk_bf16_f32 v137, v106, v107
	v_cvt_pk_bf16_f32 v138, v108, v109
	v_cvt_pk_bf16_f32 v139, v110, v111
	global_store_dwordx4 v6, v[136:139], s[32:33] nt
	s_add_u32 s32, s32, s49
	s_addc_u32 s33, s33, 0
	ds_read_b32 v120, v4 offset:64
	ds_read_b32 v121, v4 offset:196
	ds_read_b32 v122, v4 offset:328
	ds_read_b32 v123, v4 offset:460
	ds_read_b32 v124, v4 offset:592
	ds_read_b32 v125, v4 offset:724
	ds_read_b32 v126, v4 offset:856
	ds_read_b32 v127, v4 offset:988
	s_waitcnt lgkmcnt(8)
	v_cvt_pk_bf16_f32 v140, v112, v113
	v_cvt_pk_bf16_f32 v141, v114, v115
	v_cvt_pk_bf16_f32 v142, v116, v117
	v_cvt_pk_bf16_f32 v143, v118, v119
	global_store_dwordx4 v6, v[140:143], s[32:33] nt
	s_add_u32 s32, s32, s49
	s_addc_u32 s33, s33, 0
	ds_read_b32 v128, v4 offset:96
	ds_read_b32 v129, v4 offset:228
	ds_read_b32 v130, v4 offset:360
	ds_read_b32 v131, v4 offset:492
	ds_read_b32 v132, v4 offset:624
	ds_read_b32 v133, v4 offset:756
	ds_read_b32 v134, v4 offset:888
	ds_read_b32 v135, v4 offset:1020
	s_waitcnt lgkmcnt(8)
	v_cvt_pk_bf16_f32 v136, v120, v121
	v_cvt_pk_bf16_f32 v137, v122, v123
	v_cvt_pk_bf16_f32 v138, v124, v125
	v_cvt_pk_bf16_f32 v139, v126, v127
	global_store_dwordx4 v6, v[136:139], s[32:33] nt
	s_add_u32 s32, s32, s49
	s_addc_u32 s33, s33, 0
	s_waitcnt lgkmcnt(0)
	v_cvt_pk_bf16_f32 v140, v128, v129
	v_cvt_pk_bf16_f32 v141, v130, v131
	v_cvt_pk_bf16_f32 v142, v132, v133
	v_cvt_pk_bf16_f32 v143, v134, v135
	global_store_dwordx4 v6, v[140:143], s[32:33] nt
	s_add_u32 s32, s32, s49
	s_addc_u32 s33, s33, 0
	s_waitcnt vmcnt(0)
	ds_write_b32 v3, v8 offset:0
	ds_write_b32 v3, v9 offset:4
	ds_write_b32 v3, v10 offset:8
	ds_write_b32 v3, v11 offset:12
	ds_write_b32 v3, v12 offset:1056
	ds_write_b32 v3, v13 offset:1060
	ds_write_b32 v3, v14 offset:1064
	ds_write_b32 v3, v15 offset:1068
	ds_write_b32 v3, v16 offset:2112
	ds_write_b32 v3, v17 offset:2116
	ds_write_b32 v3, v18 offset:2120
	ds_write_b32 v3, v19 offset:2124
	ds_write_b32 v3, v20 offset:3168
	ds_write_b32 v3, v21 offset:3172
	ds_write_b32 v3, v22 offset:3176
	ds_write_b32 v3, v23 offset:3180
	ds_write_b32 v3, v24 offset:4224
	ds_write_b32 v3, v25 offset:4228
	ds_write_b32 v3, v26 offset:4232
	ds_write_b32 v3, v27 offset:4236
	ds_write_b32 v3, v28 offset:5280
	ds_write_b32 v3, v29 offset:5284
	ds_write_b32 v3, v30 offset:5288
	ds_write_b32 v3, v31 offset:5292
	ds_write_b32 v3, v32 offset:6336
	ds_write_b32 v3, v33 offset:6340
	ds_write_b32 v3, v34 offset:6344
	ds_write_b32 v3, v35 offset:6348
	ds_write_b32 v3, v36 offset:7392
	ds_write_b32 v3, v37 offset:7396
	ds_write_b32 v3, v38 offset:7400
	ds_write_b32 v3, v39 offset:7404
	s_mov_b32 s32, s2
	s_mov_b32 s33, s3
	s_lshl_b32 s49, s7, 3
	s_lshl_b32 s41, s49, 1
	s_cmp_lg_u32 s45, 0
	s_cselect_b64 vcc, -1, 0
	s_cselect_b32 s49, s41, s49
	v_cndmask_b32_e32 v6, v1, v7, vcc
	v_mad_u32_u24 v6, v6, s7, v2
	s_waitcnt lgkmcnt(0)
	ds_read_b32 v104, v4 offset:0
	ds_read_b32 v105, v4 offset:132
	ds_read_b32 v106, v4 offset:264
	ds_read_b32 v107, v4 offset:396
	ds_read_b32 v108, v4 offset:528
	ds_read_b32 v109, v4 offset:660
	ds_read_b32 v110, v4 offset:792
	ds_read_b32 v111, v4 offset:924
	ds_read_b32 v112, v4 offset:32
	ds_read_b32 v113, v4 offset:164
	ds_read_b32 v114, v4 offset:296
	ds_read_b32 v115, v4 offset:428
	ds_read_b32 v116, v4 offset:560
	ds_read_b32 v117, v4 offset:692
	ds_read_b32 v118, v4 offset:824
	ds_read_b32 v119, v4 offset:956
	s_waitcnt lgkmcnt(8)
	v_cvt_pk_bf16_f32 v136, v104, v105
	v_cvt_pk_bf16_f32 v137, v106, v107
	v_cvt_pk_bf16_f32 v138, v108, v109
	v_cvt_pk_bf16_f32 v139, v110, v111
	global_store_dwordx4 v6, v[136:139], s[32:33] nt
	s_add_u32 s32, s32, s49
	s_addc_u32 s33, s33, 0
	ds_read_b32 v120, v4 offset:64
	ds_read_b32 v121, v4 offset:196
	ds_read_b32 v122, v4 offset:328
	ds_read_b32 v123, v4 offset:460
	ds_read_b32 v124, v4 offset:592
	ds_read_b32 v125, v4 offset:724
	ds_read_b32 v126, v4 offset:856
	ds_read_b32 v127, v4 offset:988
	s_waitcnt lgkmcnt(8)
	v_cvt_pk_bf16_f32 v140, v112, v113
	v_cvt_pk_bf16_f32 v141, v114, v115
	v_cvt_pk_bf16_f32 v142, v116, v117
	v_cvt_pk_bf16_f32 v143, v118, v119
	global_store_dwordx4 v6, v[140:143], s[32:33] nt
	s_add_u32 s32, s32, s49
	s_addc_u32 s33, s33, 0
	ds_read_b32 v128, v4 offset:96
	ds_read_b32 v129, v4 offset:228
	ds_read_b32 v130, v4 offset:360
	ds_read_b32 v131, v4 offset:492
	ds_read_b32 v132, v4 offset:624
	ds_read_b32 v133, v4 offset:756
	ds_read_b32 v134, v4 offset:888
	ds_read_b32 v135, v4 offset:1020
	s_waitcnt lgkmcnt(8)
	v_cvt_pk_bf16_f32 v136, v120, v121
	v_cvt_pk_bf16_f32 v137, v122, v123
	v_cvt_pk_bf16_f32 v138, v124, v125
	v_cvt_pk_bf16_f32 v139, v126, v127
	global_store_dwordx4 v6, v[136:139], s[32:33] nt
	s_add_u32 s32, s32, s49
	s_addc_u32 s33, s33, 0
	s_waitcnt lgkmcnt(0)
	v_cvt_pk_bf16_f32 v140, v128, v129
	v_cvt_pk_bf16_f32 v141, v130, v131
	v_cvt_pk_bf16_f32 v142, v132, v133
	v_cvt_pk_bf16_f32 v143, v134, v135
	global_store_dwordx4 v6, v[140:143], s[32:33] nt
	s_add_u32 s32, s32, s49
	s_addc_u32 s33, s33, 0
	s_branch .Ltp0_done

.Ltp0_done:
	v_mbcnt_hi_u32_b32 v7, -1, v212
	v_and_b32_e32 v65, 63, v7
	s_branch .LBB0_158
.Lp0_orig:
	s_cmpk_gt_i32 s20, 0x1fff
	s_cbranch_scc0 .LBB0_80
	s_cmpk_gt_u32 s20, 0x27ff
	s_cbranch_scc0 .LBB0_81
	s_cmpk_gt_u32 s20, 0x3fff
	s_cbranch_scc0 .LBB0_82
	s_cmpk_gt_u32 s20, 0x47ff
	s_cbranch_scc0 .LBB0_83
	s_cmpk_gt_u32 s20, 0x87ff
	s_cbranch_scc0 .LBB0_84
	v_readlane_b32 s36, v244, 19
	s_add_i32 s4, s20, 0xffff7800
	v_readlane_b32 s37, v244, 20
	s_lshr_b32 s0, s4, 13
	s_mov_b32 s1, 0
	v_readlane_b32 s38, v244, 21
	v_readlane_b32 s39, v244, 22
	v_readlane_b32 s40, v244, 23
	v_readlane_b32 s41, v244, 24
	v_readlane_b32 s42, v244, 25
	v_readlane_b32 s43, v244, 26
	s_mov_b64 s[12:13], s[36:37]
	s_lshl_b64 s[2:3], s[0:1], 26
	s_mov_b64 s[14:15], s[38:39]
	s_add_u32 s2, s14, s2
	s_addc_u32 s3, s15, s3
	s_lshl_b64 s[0:1], s[0:1], 25
	s_add_u32 s0, s76, s0
	s_addc_u32 s1, s77, s1
	s_add_u32 s0, s0, 0x8989000
	v_readlane_b32 s44, v244, 27
	v_readlane_b32 s45, v244, 28
	v_readlane_b32 s46, v244, 29
	v_readlane_b32 s47, v244, 30
	v_readlane_b32 s48, v244, 31
	v_readlane_b32 s49, v244, 32
	v_readlane_b32 s50, v244, 33
	v_readlane_b32 s51, v244, 34
	s_mov_b64 s[16:17], s[40:41]
	s_mov_b64 s[18:19], s[42:43]
	s_addc_u32 s1, s1, 0
	s_and_b32 s21, s4, 0x1fff
	s_mov_b64 s[4:5], 0
	s_branch .LBB0_85

.LBB0_363:
	s_waitcnt vmcnt(0)
	s_barrier
	s_cmp_lg_u32 s87, 0x100
	s_cbranch_scc1 .Ltt2_done
	s_cmp_lt_u32 s96, 128
	s_cbranch_scc1 .Ltt2_done
	s_sub_u32 s20, s96, 128
	s_lshl_b32 s20, s20, 3
	s_add_u32 s20, s20, s93
	s_movk_i32 s23, 1024
	v_mbcnt_hi_u32_b32 v0, -1, v212
	v_and_b32_e32 v0, 63, v0
	v_lshrrev_b32_e32 v1, 3, v0
	v_and_b32_e32 v2, 7, v0
	s_lshl_b32 s25, s93, 14
	v_mul_u32_u24_e32 v3, 0x84, v1
	v_mul_u32_u24_e32 v4, 0x420, v2
	v_lshlrev_b32_e32 v2, 4, v2
	v_add3_u32 v3, v3, v2, s25
	v_lshl_add_u32 v4, v1, 2, v4
	v_add_u32_e32 v4, s25, v4
	v_and_b32_e32 v7, 4, v1
	v_and_b32_e32 v5, 3, v1
	v_lshl_add_u32 v7, v7, 1, v5
	v_readlane_b32 s62, v245, 0
	v_readlane_b32 s63, v245, 1
	s_add_u32 s64, s76, 0x4989000
	s_addc_u32 s65, s77, 0
	v_readlane_b32 s66, v244, 21
	v_readlane_b32 s67, v244, 22
	s_add_u32 s68, s76, 0x8989000
	s_addc_u32 s69, s77, 0
	s_cmp_ge_u32 s20, 12288
	s_cbranch_scc1 .Ltt2_done
	s_cmp_lt_u32 s20, 8192
	s_cbranch_scc1 .Ltt2_r1_s0
	s_sub_u32 s25, s20, 8192
	s_lshr_b32 s27, s25, 6
	s_and_b32 s31, s25, 63
	s_mul_i32 s35, s27, 0x80000
	s_lshl_b32 s41, s31, 7
	s_add_u32 s35, s35, s41
	s_add_u32 s0, s66, s35
	s_addc_u32 s1, s67, 0
	s_mul_i32 s35, s31, 0x80000
	s_lshl_b32 s41, s27, 7
	s_add_u32 s35, s35, s41
	s_add_u32 s2, s68, s35
	s_addc_u32 s3, s69, 0
	s_mov_b32 s5, 0x2000
	s_mov_b32 s6, 0x10000
	s_mov_b32 s7, 0x4000
	s_branch .Ltt2_r1_e

.Ltt2_r2_e:
	v_mad_u32_u24 v5, v1, s5, v2
	global_load_dwordx4 v[40:43], v5, s[0:1] nt
	s_add_u32 s0, s0, s6
	s_addc_u32 s1, s1, 0
	global_load_dwordx4 v[44:47], v5, s[0:1] nt
	s_add_u32 s0, s0, s6
	s_addc_u32 s1, s1, 0
	global_load_dwordx4 v[48:51], v5, s[0:1] nt
	s_add_u32 s0, s0, s6
	s_addc_u32 s1, s1, 0
	global_load_dwordx4 v[52:55], v5, s[0:1] nt
	s_add_u32 s0, s0, s6
	s_addc_u32 s1, s1, 0
	global_load_dwordx4 v[56:59], v5, s[0:1] nt
	s_add_u32 s0, s0, s6
	s_addc_u32 s1, s1, 0
	global_load_dwordx4 v[60:63], v5, s[0:1] nt
	s_add_u32 s0, s0, s6
	s_addc_u32 s1, s1, 0
	global_load_dwordx4 v[64:67], v5, s[0:1] nt
	s_add_u32 s0, s0, s6
	s_addc_u32 s1, s1, 0
	global_load_dwordx4 v[68:71], v5, s[0:1] nt
	s_add_u32 s0, s0, s6
	s_addc_u32 s1, s1, 0
	s_add_u32 s20, s20, s23
	s_cmp_ge_u32 s20, 12288
	s_cbranch_scc1 .Ltt2_dr2
	s_cmp_lt_u32 s20, 8192
	s_cbranch_scc1 .Ltt2_r3_s0
	s_sub_u32 s25, s20, 8192
	s_lshr_b32 s27, s25, 6
	s_and_b32 s31, s25, 63
	s_mul_i32 s35, s27, 0x80000
	s_lshl_b32 s41, s31, 7
	s_add_u32 s35, s35, s41
	s_add_u32 s0, s66, s35
	s_addc_u32 s1, s67, 0
	s_mul_i32 s35, s31, 0x80000
	s_lshl_b32 s41, s27, 7
	s_add_u32 s35, s35, s41
	s_add_u32 s42, s68, s35
	s_addc_u32 s43, s69, 0
	s_mov_b32 s5, 0x2000
	s_mov_b32 s6, 0x10000
	s_mov_b32 s44, 0x4000
	s_branch .Ltt2_r3_e
.Ltt2_r3_s0:
	s_sub_u32 s25, s20, 0
	s_lshr_b32 s27, s25, 8
	s_and_b32 s31, s25, 255
	s_mul_i32 s35, s27, 0x200000
	s_lshl_b32 s41, s31, 7
	s_add_u32 s35, s35, s41
	s_add_u32 s0, s62, s35
	s_addc_u32 s1, s63, 0
	s_mul_i32 s35, s31, 0x20000
	s_lshl_b32 s41, s27, 7
	s_add_u32 s35, s35, s41
	s_add_u32 s42, s64, s35
	s_addc_u32 s43, s65, 0
	s_mov_b32 s5, 0x8000
	s_mov_b32 s6, 0x40000
	s_mov_b32 s44, 0x1000
.Ltt2_r3_e:
	v_mad_u32_u24 v5, v1, s5, v2
	global_load_dwordx4 v[72:75], v5, s[0:1] nt
	s_add_u32 s0, s0, s6
	s_addc_u32 s1, s1, 0
	global_load_dwordx4 v[76:79], v5, s[0:1] nt
	s_add_u32 s0, s0, s6
	s_addc_u32 s1, s1, 0
	global_load_dwordx4 v[80:83], v5, s[0:1] nt
	s_add_u32 s0, s0, s6
	s_addc_u32 s1, s1, 0
	global_load_dwordx4 v[84:87], v5, s[0:1] nt
	s_add_u32 s0, s0, s6
	s_addc_u32 s1, s1, 0
	global_load_dwordx4 v[88:91], v5, s[0:1] nt
	s_add_u32 s0, s0, s6
	s_addc_u32 s1, s1, 0
	global_load_dwordx4 v[92:95], v5, s[0:1] nt
	s_add_u32 s0, s0, s6
	s_addc_u32 s1, s1, 0
	global_load_dwordx4 v[96:99], v5, s[0:1] nt
	s_add_u32 s0, s0, s6
	s_addc_u32 s1, s1, 0
	global_load_dwordx4 v[100:103], v5, s[0:1] nt
	s_add_u32 s0, s0, s6
	s_addc_u32 s1, s1, 0
	s_add_u32 s20, s20, s23
	s_waitcnt vmcnt(16)
	ds_write_b32 v3, v8 offset:0
	ds_write_b32 v3, v9 offset:4
	ds_write_b32 v3, v10 offset:8
	ds_write_b32 v3, v11 offset:12
	ds_write_b32 v3, v12 offset:1056
	ds_write_b32 v3, v13 offset:1060
	ds_write_b32 v3, v14 offset:1064
	ds_write_b32 v3, v15 offset:1068
	ds_write_b32 v3, v16 offset:2112
	ds_write_b32 v3, v17 offset:2116
	ds_write_b32 v3, v18 offset:2120
	ds_write_b32 v3, v19 offset:2124
	ds_write_b32 v3, v20 offset:3168
	ds_write_b32 v3, v21 offset:3172
	ds_write_b32 v3, v22 offset:3176
	ds_write_b32 v3, v23 offset:3180
	ds_write_b32 v3, v24 offset:4224
	ds_write_b32 v3, v25 offset:4228
	ds_write_b32 v3, v26 offset:4232
	ds_write_b32 v3, v27 offset:4236
	ds_write_b32 v3, v28 offset:5280
	ds_write_b32 v3, v29 offset:5284
	ds_write_b32 v3, v30 offset:5288
	ds_write_b32 v3, v31 offset:5292
	ds_write_b32 v3, v32 offset:6336
	ds_write_b32 v3, v33 offset:6340
	ds_write_b32 v3, v34 offset:6344
	ds_write_b32 v3, v35 offset:6348
	ds_write_b32 v3, v36 offset:7392
	ds_write_b32 v3, v37 offset:7396
	ds_write_b32 v3, v38 offset:7400
	ds_write_b32 v3, v39 offset:7404
	s_mov_b32 s32, s2
	s_mov_b32 s33, s3
	s_lshl_b32 s49, s7, 3
	v_mad_u32_u24 v6, v1, s7, v2
	s_waitcnt lgkmcnt(0)
	ds_read_b32 v104, v4 offset:0
	ds_read_b32 v105, v4 offset:132
	ds_read_b32 v106, v4 offset:264
	ds_read_b32 v107, v4 offset:396
	ds_read_b32 v108, v4 offset:528
	ds_read_b32 v109, v4 offset:660
	ds_read_b32 v110, v4 offset:792
	ds_read_b32 v111, v4 offset:924
	ds_read_b32 v112, v4 offset:32
	ds_read_b32 v113, v4 offset:164
	ds_read_b32 v114, v4 offset:296
	ds_read_b32 v115, v4 offset:428
	ds_read_b32 v116, v4 offset:560
	ds_read_b32 v117, v4 offset:692
	ds_read_b32 v118, v4 offset:824
	ds_read_b32 v119, v4 offset:956
	s_waitcnt lgkmcnt(8)
	v_cvt_pk_bf16_f32 v136, v104, v105
	v_cvt_pk_bf16_f32 v137, v106, v107
	v_cvt_pk_bf16_f32 v138, v108, v109
	v_cvt_pk_bf16_f32 v139, v110, v111
	global_store_dwordx4 v6, v[136:139], s[32:33] nt
	s_add_u32 s32, s32, s49
	s_addc_u32 s33, s33, 0
	ds_read_b32 v120, v4 offset:64
	ds_read_b32 v121, v4 offset:196
	ds_read_b32 v122, v4 offset:328
	ds_read_b32 v123, v4 offset:460
	ds_read_b32 v124, v4 offset:592
	ds_read_b32 v125, v4 offset:724
	ds_read_b32 v126, v4 offset:856
	ds_read_b32 v127, v4 offset:988
	s_waitcnt lgkmcnt(8)
	v_cvt_pk_bf16_f32 v140, v112, v113
	v_cvt_pk_bf16_f32 v141, v114, v115
	v_cvt_pk_bf16_f32 v142, v116, v117
	v_cvt_pk_bf16_f32 v143, v118, v119
	global_store_dwordx4 v6, v[140:143], s[32:33] nt
	s_add_u32 s32, s32, s49
	s_addc_u32 s33, s33, 0
	ds_read_b32 v128, v4 offset:96
	ds_read_b32 v129, v4 offset:228
	ds_read_b32 v130, v4 offset:360
	ds_read_b32 v131, v4 offset:492
	ds_read_b32 v132, v4 offset:624
	ds_read_b32 v133, v4 offset:756
	ds_read_b32 v134, v4 offset:888
	ds_read_b32 v135, v4 offset:1020
	s_waitcnt lgkmcnt(8)
	v_cvt_pk_bf16_f32 v136, v120, v121
	v_cvt_pk_bf16_f32 v137, v122, v123
	v_cvt_pk_bf16_f32 v138, v124, v125
	v_cvt_pk_bf16_f32 v139, v126, v127
	global_store_dwordx4 v6, v[136:139], s[32:33] nt
	s_add_u32 s32, s32, s49
	s_addc_u32 s33, s33, 0
	s_waitcnt lgkmcnt(0)
	v_cvt_pk_bf16_f32 v140, v128, v129
	v_cvt_pk_bf16_f32 v141, v130, v131
	v_cvt_pk_bf16_f32 v142, v132, v133
	v_cvt_pk_bf16_f32 v143, v134, v135
	global_store_dwordx4 v6, v[140:143], s[32:33] nt
	s_add_u32 s32, s32, s49
	s_addc_u32 s33, s33, 0
	s_cmp_ge_u32 s20, 12288
	s_cbranch_scc1 .Ltt2_dr3
	s_cmp_lt_u32 s20, 8192
	s_cbranch_scc1 .Ltt2_r4_s0
	s_sub_u32 s25, s20, 8192
	s_lshr_b32 s27, s25, 6
	s_and_b32 s31, s25, 63
	s_mul_i32 s35, s27, 0x80000
	s_lshl_b32 s41, s31, 7
	s_add_u32 s35, s35, s41
	s_add_u32 s0, s66, s35
	s_addc_u32 s1, s67, 0
	s_mul_i32 s35, s31, 0x80000
	s_lshl_b32 s41, s27, 7
	s_add_u32 s35, s35, s41
	s_add_u32 s2, s68, s35
	s_addc_u32 s3, s69, 0
	s_mov_b32 s5, 0x2000
	s_mov_b32 s6, 0x10000
	s_mov_b32 s7, 0x4000
	s_branch .Ltt2_r4_e

.Ltt2_r4_e:
	v_mad_u32_u24 v5, v1, s5, v2
	global_load_dwordx4 v[8:11], v5, s[0:1] nt
	s_add_u32 s0, s0, s6
	s_addc_u32 s1, s1, 0
	global_load_dwordx4 v[12:15], v5, s[0:1] nt
	s_add_u32 s0, s0, s6
	s_addc_u32 s1, s1, 0
	global_load_dwordx4 v[16:19], v5, s[0:1] nt
	s_add_u32 s0, s0, s6
	s_addc_u32 s1, s1, 0
	global_load_dwordx4 v[20:23], v5, s[0:1] nt
	s_add_u32 s0, s0, s6
	s_addc_u32 s1, s1, 0
	global_load_dwordx4 v[24:27], v5, s[0:1] nt
	s_add_u32 s0, s0, s6
	s_addc_u32 s1, s1, 0
	global_load_dwordx4 v[28:31], v5, s[0:1] nt
	s_add_u32 s0, s0, s6
	s_addc_u32 s1, s1, 0
	global_load_dwordx4 v[32:35], v5, s[0:1] nt
	s_add_u32 s0, s0, s6
	s_addc_u32 s1, s1, 0
	global_load_dwordx4 v[36:39], v5, s[0:1] nt
	s_add_u32 s0, s0, s6
	s_addc_u32 s1, s1, 0
	s_add_u32 s20, s20, s23
	s_waitcnt vmcnt(16)
	ds_write_b32 v3, v40 offset:0
	ds_write_b32 v3, v41 offset:4
	ds_write_b32 v3, v42 offset:8
	ds_write_b32 v3, v43 offset:12
	ds_write_b32 v3, v44 offset:1056
	ds_write_b32 v3, v45 offset:1060
	ds_write_b32 v3, v46 offset:1064
	ds_write_b32 v3, v47 offset:1068
	ds_write_b32 v3, v48 offset:2112
	ds_write_b32 v3, v49 offset:2116
	ds_write_b32 v3, v50 offset:2120
	ds_write_b32 v3, v51 offset:2124
	ds_write_b32 v3, v52 offset:3168
	ds_write_b32 v3, v53 offset:3172
	ds_write_b32 v3, v54 offset:3176
	ds_write_b32 v3, v55 offset:3180
	ds_write_b32 v3, v56 offset:4224
	ds_write_b32 v3, v57 offset:4228
	ds_write_b32 v3, v58 offset:4232
	ds_write_b32 v3, v59 offset:4236
	ds_write_b32 v3, v60 offset:5280
	ds_write_b32 v3, v61 offset:5284
	ds_write_b32 v3, v62 offset:5288
	ds_write_b32 v3, v63 offset:5292
	ds_write_b32 v3, v64 offset:6336
	ds_write_b32 v3, v65 offset:6340
	ds_write_b32 v3, v66 offset:6344
	ds_write_b32 v3, v67 offset:6348
	ds_write_b32 v3, v68 offset:7392
	ds_write_b32 v3, v69 offset:7396
	ds_write_b32 v3, v70 offset:7400
	ds_write_b32 v3, v71 offset:7404
	s_mov_b32 s32, s10
	s_mov_b32 s33, s11
	s_lshl_b32 s49, s47, 3
	v_mad_u32_u24 v6, v1, s47, v2
	s_waitcnt lgkmcnt(0)
	ds_read_b32 v104, v4 offset:0
	ds_read_b32 v105, v4 offset:132
	ds_read_b32 v106, v4 offset:264
	ds_read_b32 v107, v4 offset:396
	ds_read_b32 v108, v4 offset:528
	ds_read_b32 v109, v4 offset:660
	ds_read_b32 v110, v4 offset:792
	ds_read_b32 v111, v4 offset:924
	ds_read_b32 v112, v4 offset:32
	ds_read_b32 v113, v4 offset:164
	ds_read_b32 v114, v4 offset:296
	ds_read_b32 v115, v4 offset:428
	ds_read_b32 v116, v4 offset:560
	ds_read_b32 v117, v4 offset:692
	ds_read_b32 v118, v4 offset:824
	ds_read_b32 v119, v4 offset:956
	s_waitcnt lgkmcnt(8)
	v_cvt_pk_bf16_f32 v136, v104, v105
	v_cvt_pk_bf16_f32 v137, v106, v107
	v_cvt_pk_bf16_f32 v138, v108, v109
	v_cvt_pk_bf16_f32 v139, v110, v111
	global_store_dwordx4 v6, v[136:139], s[32:33] nt
	s_add_u32 s32, s32, s49
	s_addc_u32 s33, s33, 0
	ds_read_b32 v120, v4 offset:64
	ds_read_b32 v121, v4 offset:196
	ds_read_b32 v122, v4 offset:328
	ds_read_b32 v123, v4 offset:460
	ds_read_b32 v124, v4 offset:592
	ds_read_b32 v125, v4 offset:724
	ds_read_b32 v126, v4 offset:856
	ds_read_b32 v127, v4 offset:988
	s_waitcnt lgkmcnt(8)
	v_cvt_pk_bf16_f32 v140, v112, v113
	v_cvt_pk_bf16_f32 v141, v114, v115
	v_cvt_pk_bf16_f32 v142, v116, v117
	v_cvt_pk_bf16_f32 v143, v118, v119
	global_store_dwordx4 v6, v[140:143], s[32:33] nt
	s_add_u32 s32, s32, s49
	s_addc_u32 s33, s33, 0
	ds_read_b32 v128, v4 offset:96
	ds_read_b32 v129, v4 offset:228
	ds_read_b32 v130, v4 offset:360
	ds_read_b32 v131, v4 offset:492
	ds_read_b32 v132, v4 offset:624
	ds_read_b32 v133, v4 offset:756
	ds_read_b32 v134, v4 offset:888
	ds_read_b32 v135, v4 offset:1020
	s_waitcnt lgkmcnt(8)
	v_cvt_pk_bf16_f32 v136, v120, v121
	v_cvt_pk_bf16_f32 v137, v122, v123
	v_cvt_pk_bf16_f32 v138, v124, v125
	v_cvt_pk_bf16_f32 v139, v126, v127
	global_store_dwordx4 v6, v[136:139], s[32:33] nt
	s_add_u32 s32, s32, s49
	s_addc_u32 s33, s33, 0
	s_waitcnt lgkmcnt(0)
	v_cvt_pk_bf16_f32 v140, v128, v129
	v_cvt_pk_bf16_f32 v141, v130, v131
	v_cvt_pk_bf16_f32 v142, v132, v133
	v_cvt_pk_bf16_f32 v143, v134, v135
	global_store_dwordx4 v6, v[140:143], s[32:33] nt
	s_add_u32 s32, s32, s49
	s_addc_u32 s33, s33, 0
.Ltt2_loop:
	s_cmp_ge_u32 s20, 12288
	s_cbranch_scc1 .Ltt2_dr4
	s_cmp_lt_u32 s20, 8192
	s_cbranch_scc1 .Ltt2_r5_s0
	s_sub_u32 s25, s20, 8192
	s_lshr_b32 s27, s25, 6
	s_and_b32 s31, s25, 63
	s_mul_i32 s35, s27, 0x80000
	s_lshl_b32 s41, s31, 7
	s_add_u32 s35, s35, s41
	s_add_u32 s0, s66, s35
	s_addc_u32 s1, s67, 0
	s_mul_i32 s35, s31, 0x80000
	s_lshl_b32 s41, s27, 7
	s_add_u32 s35, s35, s41
	s_add_u32 s10, s68, s35
	s_addc_u32 s11, s69, 0
	s_mov_b32 s5, 0x2000
	s_mov_b32 s6, 0x10000
	s_mov_b32 s47, 0x4000
	s_branch .Ltt2_r5_e

.Ltt2_r5_e:
	v_mad_u32_u24 v5, v1, s5, v2
	global_load_dwordx4 v[40:43], v5, s[0:1] nt
	s_add_u32 s0, s0, s6
	s_addc_u32 s1, s1, 0
	global_load_dwordx4 v[44:47], v5, s[0:1] nt
	s_add_u32 s0, s0, s6
	s_addc_u32 s1, s1, 0
	global_load_dwordx4 v[48:51], v5, s[0:1] nt
	s_add_u32 s0, s0, s6
	s_addc_u32 s1, s1, 0
	global_load_dwordx4 v[52:55], v5, s[0:1] nt
	s_add_u32 s0, s0, s6
	s_addc_u32 s1, s1, 0
	global_load_dwordx4 v[56:59], v5, s[0:1] nt
	s_add_u32 s0, s0, s6
	s_addc_u32 s1, s1, 0
	global_load_dwordx4 v[60:63], v5, s[0:1] nt
	s_add_u32 s0, s0, s6
	s_addc_u32 s1, s1, 0
	global_load_dwordx4 v[64:67], v5, s[0:1] nt
	s_add_u32 s0, s0, s6
	s_addc_u32 s1, s1, 0
	global_load_dwordx4 v[68:71], v5, s[0:1] nt
	s_add_u32 s0, s0, s6
	s_addc_u32 s1, s1, 0
	s_add_u32 s20, s20, s23
	s_waitcnt vmcnt(24)
	ds_write_b32 v3, v72 offset:0
	ds_write_b32 v3, v73 offset:4
	ds_write_b32 v3, v74 offset:8
	ds_write_b32 v3, v75 offset:12
	ds_write_b32 v3, v76 offset:1056
	ds_write_b32 v3, v77 offset:1060
	ds_write_b32 v3, v78 offset:1064
	ds_write_b32 v3, v79 offset:1068
	ds_write_b32 v3, v80 offset:2112
	ds_write_b32 v3, v81 offset:2116
	ds_write_b32 v3, v82 offset:2120
	ds_write_b32 v3, v83 offset:2124
	ds_write_b32 v3, v84 offset:3168
	ds_write_b32 v3, v85 offset:3172
	ds_write_b32 v3, v86 offset:3176
	ds_write_b32 v3, v87 offset:3180
	ds_write_b32 v3, v88 offset:4224
	ds_write_b32 v3, v89 offset:4228
	ds_write_b32 v3, v90 offset:4232
	ds_write_b32 v3, v91 offset:4236
	ds_write_b32 v3, v92 offset:5280
	ds_write_b32 v3, v93 offset:5284
	ds_write_b32 v3, v94 offset:5288
	ds_write_b32 v3, v95 offset:5292
	ds_write_b32 v3, v96 offset:6336
	ds_write_b32 v3, v97 offset:6340
	ds_write_b32 v3, v98 offset:6344
	ds_write_b32 v3, v99 offset:6348
	ds_write_b32 v3, v100 offset:7392
	ds_write_b32 v3, v101 offset:7396
	ds_write_b32 v3, v102 offset:7400
	ds_write_b32 v3, v103 offset:7404
	s_mov_b32 s32, s42
	s_mov_b32 s33, s43
	s_lshl_b32 s49, s44, 3
	v_mad_u32_u24 v6, v1, s44, v2
	s_waitcnt lgkmcnt(0)
	ds_read_b32 v104, v4 offset:0
	ds_read_b32 v105, v4 offset:132
	ds_read_b32 v106, v4 offset:264
	ds_read_b32 v107, v4 offset:396
	ds_read_b32 v108, v4 offset:528
	ds_read_b32 v109, v4 offset:660
	ds_read_b32 v110, v4 offset:792
	ds_read_b32 v111, v4 offset:924
	ds_read_b32 v112, v4 offset:32
	ds_read_b32 v113, v4 offset:164
	ds_read_b32 v114, v4 offset:296
	ds_read_b32 v115, v4 offset:428
	ds_read_b32 v116, v4 offset:560
	ds_read_b32 v117, v4 offset:692
	ds_read_b32 v118, v4 offset:824
	ds_read_b32 v119, v4 offset:956
	s_waitcnt lgkmcnt(8)
	v_cvt_pk_bf16_f32 v136, v104, v105
	v_cvt_pk_bf16_f32 v137, v106, v107
	v_cvt_pk_bf16_f32 v138, v108, v109
	v_cvt_pk_bf16_f32 v139, v110, v111
	global_store_dwordx4 v6, v[136:139], s[32:33] nt
	s_add_u32 s32, s32, s49
	s_addc_u32 s33, s33, 0
	ds_read_b32 v120, v4 offset:64
	ds_read_b32 v121, v4 offset:196
	ds_read_b32 v122, v4 offset:328
	ds_read_b32 v123, v4 offset:460
	ds_read_b32 v124, v4 offset:592
	ds_read_b32 v125, v4 offset:724
	ds_read_b32 v126, v4 offset:856
	ds_read_b32 v127, v4 offset:988
	s_waitcnt lgkmcnt(8)
	v_cvt_pk_bf16_f32 v140, v112, v113
	v_cvt_pk_bf16_f32 v141, v114, v115
	v_cvt_pk_bf16_f32 v142, v116, v117
	v_cvt_pk_bf16_f32 v143, v118, v119
	global_store_dwordx4 v6, v[140:143], s[32:33] nt
	s_add_u32 s32, s32, s49
	s_addc_u32 s33, s33, 0
	ds_read_b32 v128, v4 offset:96
	ds_read_b32 v129, v4 offset:228
	ds_read_b32 v130, v4 offset:360
	ds_read_b32 v131, v4 offset:492
	ds_read_b32 v132, v4 offset:624
	ds_read_b32 v133, v4 offset:756
	ds_read_b32 v134, v4 offset:888
	ds_read_b32 v135, v4 offset:1020
	s_waitcnt lgkmcnt(8)
	v_cvt_pk_bf16_f32 v136, v120, v121
	v_cvt_pk_bf16_f32 v137, v122, v123
	v_cvt_pk_bf16_f32 v138, v124, v125
	v_cvt_pk_bf16_f32 v139, v126, v127
	global_store_dwordx4 v6, v[136:139], s[32:33] nt
	s_add_u32 s32, s32, s49
	s_addc_u32 s33, s33, 0
	s_waitcnt lgkmcnt(0)
	v_cvt_pk_bf16_f32 v140, v128, v129
	v_cvt_pk_bf16_f32 v141, v130, v131
	v_cvt_pk_bf16_f32 v142, v132, v133
	v_cvt_pk_bf16_f32 v143, v134, v135
	global_store_dwordx4 v6, v[140:143], s[32:33] nt
	s_add_u32 s32, s32, s49
	s_addc_u32 s33, s33, 0
	s_cmp_ge_u32 s20, 12288
	s_cbranch_scc1 .Ltt2_dr5
	s_cmp_lt_u32 s20, 8192
	s_cbranch_scc1 .Ltt2_r6_s0
	s_sub_u32 s25, s20, 8192
	s_lshr_b32 s27, s25, 6
	s_and_b32 s31, s25, 63
	s_mul_i32 s35, s27, 0x80000
	s_lshl_b32 s41, s31, 7
	s_add_u32 s35, s35, s41
	s_add_u32 s0, s66, s35
	s_addc_u32 s1, s67, 0
	s_mul_i32 s35, s31, 0x80000
	s_lshl_b32 s41, s27, 7
	s_add_u32 s35, s35, s41
	s_add_u32 s42, s68, s35
	s_addc_u32 s43, s69, 0
	s_mov_b32 s5, 0x2000
	s_mov_b32 s6, 0x10000
	s_mov_b32 s44, 0x4000
	s_branch .Ltt2_r6_e

.Ltt2_r6_e:
	v_mad_u32_u24 v5, v1, s5, v2
	global_load_dwordx4 v[72:75], v5, s[0:1] nt
	s_add_u32 s0, s0, s6
	s_addc_u32 s1, s1, 0
	global_load_dwordx4 v[76:79], v5, s[0:1] nt
	s_add_u32 s0, s0, s6
	s_addc_u32 s1, s1, 0
	global_load_dwordx4 v[80:83], v5, s[0:1] nt
	s_add_u32 s0, s0, s6
	s_addc_u32 s1, s1, 0
	global_load_dwordx4 v[84:87], v5, s[0:1] nt
	s_add_u32 s0, s0, s6
	s_addc_u32 s1, s1, 0
	global_load_dwordx4 v[88:91], v5, s[0:1] nt
	s_add_u32 s0, s0, s6
	s_addc_u32 s1, s1, 0
	global_load_dwordx4 v[92:95], v5, s[0:1] nt
	s_add_u32 s0, s0, s6
	s_addc_u32 s1, s1, 0
	global_load_dwordx4 v[96:99], v5, s[0:1] nt
	s_add_u32 s0, s0, s6
	s_addc_u32 s1, s1, 0
	global_load_dwordx4 v[100:103], v5, s[0:1] nt
	s_add_u32 s0, s0, s6
	s_addc_u32 s1, s1, 0
	s_add_u32 s20, s20, s23
	s_waitcnt vmcnt(24)
	ds_write_b32 v3, v8 offset:0
	ds_write_b32 v3, v9 offset:4
	ds_write_b32 v3, v10 offset:8
	ds_write_b32 v3, v11 offset:12
	ds_write_b32 v3, v12 offset:1056
	ds_write_b32 v3, v13 offset:1060
	ds_write_b32 v3, v14 offset:1064
	ds_write_b32 v3, v15 offset:1068
	ds_write_b32 v3, v16 offset:2112
	ds_write_b32 v3, v17 offset:2116
	ds_write_b32 v3, v18 offset:2120
	ds_write_b32 v3, v19 offset:2124
	ds_write_b32 v3, v20 offset:3168
	ds_write_b32 v3, v21 offset:3172
	ds_write_b32 v3, v22 offset:3176
	ds_write_b32 v3, v23 offset:3180
	ds_write_b32 v3, v24 offset:4224
	ds_write_b32 v3, v25 offset:4228
	ds_write_b32 v3, v26 offset:4232
	ds_write_b32 v3, v27 offset:4236
	ds_write_b32 v3, v28 offset:5280
	ds_write_b32 v3, v29 offset:5284
	ds_write_b32 v3, v30 offset:5288
	ds_write_b32 v3, v31 offset:5292
	ds_write_b32 v3, v32 offset:6336
	ds_write_b32 v3, v33 offset:6340
	ds_write_b32 v3, v34 offset:6344
	ds_write_b32 v3, v35 offset:6348
	ds_write_b32 v3, v36 offset:7392
	ds_write_b32 v3, v37 offset:7396
	ds_write_b32 v3, v38 offset:7400
	ds_write_b32 v3, v39 offset:7404
	s_mov_b32 s32, s2
	s_mov_b32 s33, s3
	s_lshl_b32 s49, s7, 3
	v_mad_u32_u24 v6, v1, s7, v2
	s_waitcnt lgkmcnt(0)
	ds_read_b32 v104, v4 offset:0
	ds_read_b32 v105, v4 offset:132
	ds_read_b32 v106, v4 offset:264
	ds_read_b32 v107, v4 offset:396
	ds_read_b32 v108, v4 offset:528
	ds_read_b32 v109, v4 offset:660
	ds_read_b32 v110, v4 offset:792
	ds_read_b32 v111, v4 offset:924
	ds_read_b32 v112, v4 offset:32
	ds_read_b32 v113, v4 offset:164
	ds_read_b32 v114, v4 offset:296
	ds_read_b32 v115, v4 offset:428
	ds_read_b32 v116, v4 offset:560
	ds_read_b32 v117, v4 offset:692
	ds_read_b32 v118, v4 offset:824
	ds_read_b32 v119, v4 offset:956
	s_waitcnt lgkmcnt(8)
	v_cvt_pk_bf16_f32 v136, v104, v105
	v_cvt_pk_bf16_f32 v137, v106, v107
	v_cvt_pk_bf16_f32 v138, v108, v109
	v_cvt_pk_bf16_f32 v139, v110, v111
	global_store_dwordx4 v6, v[136:139], s[32:33] nt
	s_add_u32 s32, s32, s49
	s_addc_u32 s33, s33, 0
	ds_read_b32 v120, v4 offset:64
	ds_read_b32 v121, v4 offset:196
	ds_read_b32 v122, v4 offset:328
	ds_read_b32 v123, v4 offset:460
	ds_read_b32 v124, v4 offset:592
	ds_read_b32 v125, v4 offset:724
	ds_read_b32 v126, v4 offset:856
	ds_read_b32 v127, v4 offset:988
	s_waitcnt lgkmcnt(8)
	v_cvt_pk_bf16_f32 v140, v112, v113
	v_cvt_pk_bf16_f32 v141, v114, v115
	v_cvt_pk_bf16_f32 v142, v116, v117
	v_cvt_pk_bf16_f32 v143, v118, v119
	global_store_dwordx4 v6, v[140:143], s[32:33] nt
	s_add_u32 s32, s32, s49
	s_addc_u32 s33, s33, 0
	ds_read_b32 v128, v4 offset:96
	ds_read_b32 v129, v4 offset:228
	ds_read_b32 v130, v4 offset:360
	ds_read_b32 v131, v4 offset:492
	ds_read_b32 v132, v4 offset:624
	ds_read_b32 v133, v4 offset:756
	ds_read_b32 v134, v4 offset:888
	ds_read_b32 v135, v4 offset:1020
	s_waitcnt lgkmcnt(8)
	v_cvt_pk_bf16_f32 v136, v120, v121
	v_cvt_pk_bf16_f32 v137, v122, v123
	v_cvt_pk_bf16_f32 v138, v124, v125
	v_cvt_pk_bf16_f32 v139, v126, v127
	global_store_dwordx4 v6, v[136:139], s[32:33] nt
	s_add_u32 s32, s32, s49
	s_addc_u32 s33, s33, 0
	s_waitcnt lgkmcnt(0)
	v_cvt_pk_bf16_f32 v140, v128, v129
	v_cvt_pk_bf16_f32 v141, v130, v131
	v_cvt_pk_bf16_f32 v142, v132, v133
	v_cvt_pk_bf16_f32 v143, v134, v135
	global_store_dwordx4 v6, v[140:143], s[32:33] nt
	s_add_u32 s32, s32, s49
	s_addc_u32 s33, s33, 0
	s_cmp_ge_u32 s20, 12288
	s_cbranch_scc1 .Ltt2_dr6
	s_cmp_lt_u32 s20, 8192
	s_cbranch_scc1 .Ltt2_r7_s0
	s_sub_u32 s25, s20, 8192
	s_lshr_b32 s27, s25, 6
	s_and_b32 s31, s25, 63
	s_mul_i32 s35, s27, 0x80000
	s_lshl_b32 s41, s31, 7
	s_add_u32 s35, s35, s41
	s_add_u32 s0, s66, s35
	s_addc_u32 s1, s67, 0
	s_mul_i32 s35, s31, 0x80000
	s_lshl_b32 s41, s27, 7
	s_add_u32 s35, s35, s41
	s_add_u32 s2, s68, s35
	s_addc_u32 s3, s69, 0
	s_mov_b32 s5, 0x2000
	s_mov_b32 s6, 0x10000
	s_mov_b32 s7, 0x4000
	s_branch .Ltt2_r7_e

.Ltt2_r7_e:
	v_mad_u32_u24 v5, v1, s5, v2
	global_load_dwordx4 v[8:11], v5, s[0:1] nt
	s_add_u32 s0, s0, s6
	s_addc_u32 s1, s1, 0
	global_load_dwordx4 v[12:15], v5, s[0:1] nt
	s_add_u32 s0, s0, s6
	s_addc_u32 s1, s1, 0
	global_load_dwordx4 v[16:19], v5, s[0:1] nt
	s_add_u32 s0, s0, s6
	s_addc_u32 s1, s1, 0
	global_load_dwordx4 v[20:23], v5, s[0:1] nt
	s_add_u32 s0, s0, s6
	s_addc_u32 s1, s1, 0
	global_load_dwordx4 v[24:27], v5, s[0:1] nt
	s_add_u32 s0, s0, s6
	s_addc_u32 s1, s1, 0
	global_load_dwordx4 v[28:31], v5, s[0:1] nt
	s_add_u32 s0, s0, s6
	s_addc_u32 s1, s1, 0
	global_load_dwordx4 v[32:35], v5, s[0:1] nt
	s_add_u32 s0, s0, s6
	s_addc_u32 s1, s1, 0
	global_load_dwordx4 v[36:39], v5, s[0:1] nt
	s_add_u32 s0, s0, s6
	s_addc_u32 s1, s1, 0
	s_add_u32 s20, s20, s23
	s_waitcnt vmcnt(24)
	ds_write_b32 v3, v40 offset:0
	ds_write_b32 v3, v41 offset:4
	ds_write_b32 v3, v42 offset:8
	ds_write_b32 v3, v43 offset:12
	ds_write_b32 v3, v44 offset:1056
	ds_write_b32 v3, v45 offset:1060
	ds_write_b32 v3, v46 offset:1064
	ds_write_b32 v3, v47 offset:1068
	ds_write_b32 v3, v48 offset:2112
	ds_write_b32 v3, v49 offset:2116
	ds_write_b32 v3, v50 offset:2120
	ds_write_b32 v3, v51 offset:2124
	ds_write_b32 v3, v52 offset:3168
	ds_write_b32 v3, v53 offset:3172
	ds_write_b32 v3, v54 offset:3176
	ds_write_b32 v3, v55 offset:3180
	ds_write_b32 v3, v56 offset:4224
	ds_write_b32 v3, v57 offset:4228
	ds_write_b32 v3, v58 offset:4232
	ds_write_b32 v3, v59 offset:4236
	ds_write_b32 v3, v60 offset:5280
	ds_write_b32 v3, v61 offset:5284
	ds_write_b32 v3, v62 offset:5288
	ds_write_b32 v3, v63 offset:5292
	ds_write_b32 v3, v64 offset:6336
	ds_write_b32 v3, v65 offset:6340
	ds_write_b32 v3, v66 offset:6344
	ds_write_b32 v3, v67 offset:6348
	ds_write_b32 v3, v68 offset:7392
	ds_write_b32 v3, v69 offset:7396
	ds_write_b32 v3, v70 offset:7400
	ds_write_b32 v3, v71 offset:7404
	s_mov_b32 s32, s10
	s_mov_b32 s33, s11
	s_lshl_b32 s49, s47, 3
	v_mad_u32_u24 v6, v1, s47, v2
	s_waitcnt lgkmcnt(0)
	ds_read_b32 v104, v4 offset:0
	ds_read_b32 v105, v4 offset:132
	ds_read_b32 v106, v4 offset:264
	ds_read_b32 v107, v4 offset:396
	ds_read_b32 v108, v4 offset:528
	ds_read_b32 v109, v4 offset:660
	ds_read_b32 v110, v4 offset:792
	ds_read_b32 v111, v4 offset:924
	ds_read_b32 v112, v4 offset:32
	ds_read_b32 v113, v4 offset:164
	ds_read_b32 v114, v4 offset:296
	ds_read_b32 v115, v4 offset:428
	ds_read_b32 v116, v4 offset:560
	ds_read_b32 v117, v4 offset:692
	ds_read_b32 v118, v4 offset:824
	ds_read_b32 v119, v4 offset:956
	s_waitcnt lgkmcnt(8)
	v_cvt_pk_bf16_f32 v136, v104, v105
	v_cvt_pk_bf16_f32 v137, v106, v107
	v_cvt_pk_bf16_f32 v138, v108, v109
	v_cvt_pk_bf16_f32 v139, v110, v111
	global_store_dwordx4 v6, v[136:139], s[32:33] nt
	s_add_u32 s32, s32, s49
	s_addc_u32 s33, s33, 0
	ds_read_b32 v120, v4 offset:64
	ds_read_b32 v121, v4 offset:196
	ds_read_b32 v122, v4 offset:328
	ds_read_b32 v123, v4 offset:460
	ds_read_b32 v124, v4 offset:592
	ds_read_b32 v125, v4 offset:724
	ds_read_b32 v126, v4 offset:856
	ds_read_b32 v127, v4 offset:988
	s_waitcnt lgkmcnt(8)
	v_cvt_pk_bf16_f32 v140, v112, v113
	v_cvt_pk_bf16_f32 v141, v114, v115
	v_cvt_pk_bf16_f32 v142, v116, v117
	v_cvt_pk_bf16_f32 v143, v118, v119
	global_store_dwordx4 v6, v[140:143], s[32:33] nt
	s_add_u32 s32, s32, s49
	s_addc_u32 s33, s33, 0
	ds_read_b32 v128, v4 offset:96
	ds_read_b32 v129, v4 offset:228
	ds_read_b32 v130, v4 offset:360
	ds_read_b32 v131, v4 offset:492
	ds_read_b32 v132, v4 offset:624
	ds_read_b32 v133, v4 offset:756
	ds_read_b32 v134, v4 offset:888
	ds_read_b32 v135, v4 offset:1020
	s_waitcnt lgkmcnt(8)
	v_cvt_pk_bf16_f32 v136, v120, v121
	v_cvt_pk_bf16_f32 v137, v122, v123
	v_cvt_pk_bf16_f32 v138, v124, v125
	v_cvt_pk_bf16_f32 v139, v126, v127
	global_store_dwordx4 v6, v[136:139], s[32:33] nt
	s_add_u32 s32, s32, s49
	s_addc_u32 s33, s33, 0
	s_waitcnt lgkmcnt(0)
	v_cvt_pk_bf16_f32 v140, v128, v129
	v_cvt_pk_bf16_f32 v141, v130, v131
	v_cvt_pk_bf16_f32 v142, v132, v133
	v_cvt_pk_bf16_f32 v143, v134, v135
	global_store_dwordx4 v6, v[140:143], s[32:33] nt
	s_add_u32 s32, s32, s49
	s_addc_u32 s33, s33, 0
	s_branch .Ltt2_loop
.Ltt2_dr1:
	s_waitcnt vmcnt(0)
	ds_write_b32 v3, v8 offset:0
	ds_write_b32 v3, v9 offset:4
	ds_write_b32 v3, v10 offset:8
	ds_write_b32 v3, v11 offset:12
	ds_write_b32 v3, v12 offset:1056
	ds_write_b32 v3, v13 offset:1060
	ds_write_b32 v3, v14 offset:1064
	ds_write_b32 v3, v15 offset:1068
	ds_write_b32 v3, v16 offset:2112
	ds_write_b32 v3, v17 offset:2116
	ds_write_b32 v3, v18 offset:2120
	ds_write_b32 v3, v19 offset:2124
	ds_write_b32 v3, v20 offset:3168
	ds_write_b32 v3, v21 offset:3172
	ds_write_b32 v3, v22 offset:3176
	ds_write_b32 v3, v23 offset:3180
	ds_write_b32 v3, v24 offset:4224
	ds_write_b32 v3, v25 offset:4228
	ds_write_b32 v3, v26 offset:4232
	ds_write_b32 v3, v27 offset:4236
	ds_write_b32 v3, v28 offset:5280
	ds_write_b32 v3, v29 offset:5284
	ds_write_b32 v3, v30 offset:5288
	ds_write_b32 v3, v31 offset:5292
	ds_write_b32 v3, v32 offset:6336
	ds_write_b32 v3, v33 offset:6340
	ds_write_b32 v3, v34 offset:6344
	ds_write_b32 v3, v35 offset:6348
	ds_write_b32 v3, v36 offset:7392
	ds_write_b32 v3, v37 offset:7396
	ds_write_b32 v3, v38 offset:7400
	ds_write_b32 v3, v39 offset:7404
	s_mov_b32 s32, s2
	s_mov_b32 s33, s3
	s_lshl_b32 s49, s7, 3
	v_mad_u32_u24 v6, v1, s7, v2
	s_waitcnt lgkmcnt(0)
	ds_read_b32 v104, v4 offset:0
	ds_read_b32 v105, v4 offset:132
	ds_read_b32 v106, v4 offset:264
	ds_read_b32 v107, v4 offset:396
	ds_read_b32 v108, v4 offset:528
	ds_read_b32 v109, v4 offset:660
	ds_read_b32 v110, v4 offset:792
	ds_read_b32 v111, v4 offset:924
	ds_read_b32 v112, v4 offset:32
	ds_read_b32 v113, v4 offset:164
	ds_read_b32 v114, v4 offset:296
	ds_read_b32 v115, v4 offset:428
	ds_read_b32 v116, v4 offset:560
	ds_read_b32 v117, v4 offset:692
	ds_read_b32 v118, v4 offset:824
	ds_read_b32 v119, v4 offset:956
	s_waitcnt lgkmcnt(8)
	v_cvt_pk_bf16_f32 v136, v104, v105
	v_cvt_pk_bf16_f32 v137, v106, v107
	v_cvt_pk_bf16_f32 v138, v108, v109
	v_cvt_pk_bf16_f32 v139, v110, v111
	global_store_dwordx4 v6, v[136:139], s[32:33] nt
	s_add_u32 s32, s32, s49
	s_addc_u32 s33, s33, 0
	ds_read_b32 v120, v4 offset:64
	ds_read_b32 v121, v4 offset:196
	ds_read_b32 v122, v4 offset:328
	ds_read_b32 v123, v4 offset:460
	ds_read_b32 v124, v4 offset:592
	ds_read_b32 v125, v4 offset:724
	ds_read_b32 v126, v4 offset:856
	ds_read_b32 v127, v4 offset:988
	s_waitcnt lgkmcnt(8)
	v_cvt_pk_bf16_f32 v140, v112, v113
	v_cvt_pk_bf16_f32 v141, v114, v115
	v_cvt_pk_bf16_f32 v142, v116, v117
	v_cvt_pk_bf16_f32 v143, v118, v119
	global_store_dwordx4 v6, v[140:143], s[32:33] nt
	s_add_u32 s32, s32, s49
	s_addc_u32 s33, s33, 0
	ds_read_b32 v128, v4 offset:96
	ds_read_b32 v129, v4 offset:228
	ds_read_b32 v130, v4 offset:360
	ds_read_b32 v131, v4 offset:492
	ds_read_b32 v132, v4 offset:624
	ds_read_b32 v133, v4 offset:756
	ds_read_b32 v134, v4 offset:888
	ds_read_b32 v135, v4 offset:1020
	s_waitcnt lgkmcnt(8)
	v_cvt_pk_bf16_f32 v136, v120, v121
	v_cvt_pk_bf16_f32 v137, v122, v123
	v_cvt_pk_bf16_f32 v138, v124, v125
	v_cvt_pk_bf16_f32 v139, v126, v127
	global_store_dwordx4 v6, v[136:139], s[32:33] nt
	s_add_u32 s32, s32, s49
	s_addc_u32 s33, s33, 0
	s_waitcnt lgkmcnt(0)
	v_cvt_pk_bf16_f32 v140, v128, v129
	v_cvt_pk_bf16_f32 v141, v130, v131
	v_cvt_pk_bf16_f32 v142, v132, v133
	v_cvt_pk_bf16_f32 v143, v134, v135
	global_store_dwordx4 v6, v[140:143], s[32:33] nt
	s_add_u32 s32, s32, s49
	s_addc_u32 s33, s33, 0
	s_branch .Ltt2_done
.Ltt2_dr2:
	s_waitcnt vmcnt(8)
	ds_write_b32 v3, v8 offset:0
	ds_write_b32 v3, v9 offset:4
	ds_write_b32 v3, v10 offset:8
	ds_write_b32 v3, v11 offset:12
	ds_write_b32 v3, v12 offset:1056
	ds_write_b32 v3, v13 offset:1060
	ds_write_b32 v3, v14 offset:1064
	ds_write_b32 v3, v15 offset:1068
	ds_write_b32 v3, v16 offset:2112
	ds_write_b32 v3, v17 offset:2116
	ds_write_b32 v3, v18 offset:2120
	ds_write_b32 v3, v19 offset:2124
	ds_write_b32 v3, v20 offset:3168
	ds_write_b32 v3, v21 offset:3172
	ds_write_b32 v3, v22 offset:3176
	ds_write_b32 v3, v23 offset:3180
	ds_write_b32 v3, v24 offset:4224
	ds_write_b32 v3, v25 offset:4228
	ds_write_b32 v3, v26 offset:4232
	ds_write_b32 v3, v27 offset:4236
	ds_write_b32 v3, v28 offset:5280
	ds_write_b32 v3, v29 offset:5284
	ds_write_b32 v3, v30 offset:5288
	ds_write_b32 v3, v31 offset:5292
	ds_write_b32 v3, v32 offset:6336
	ds_write_b32 v3, v33 offset:6340
	ds_write_b32 v3, v34 offset:6344
	ds_write_b32 v3, v35 offset:6348
	ds_write_b32 v3, v36 offset:7392
	ds_write_b32 v3, v37 offset:7396
	ds_write_b32 v3, v38 offset:7400
	ds_write_b32 v3, v39 offset:7404
	s_mov_b32 s32, s2
	s_mov_b32 s33, s3
	s_lshl_b32 s49, s7, 3
	v_mad_u32_u24 v6, v1, s7, v2
	s_waitcnt lgkmcnt(0)
	ds_read_b32 v104, v4 offset:0
	ds_read_b32 v105, v4 offset:132
	ds_read_b32 v106, v4 offset:264
	ds_read_b32 v107, v4 offset:396
	ds_read_b32 v108, v4 offset:528
	ds_read_b32 v109, v4 offset:660
	ds_read_b32 v110, v4 offset:792
	ds_read_b32 v111, v4 offset:924
	ds_read_b32 v112, v4 offset:32
	ds_read_b32 v113, v4 offset:164
	ds_read_b32 v114, v4 offset:296
	ds_read_b32 v115, v4 offset:428
	ds_read_b32 v116, v4 offset:560
	ds_read_b32 v117, v4 offset:692
	ds_read_b32 v118, v4 offset:824
	ds_read_b32 v119, v4 offset:956
	s_waitcnt lgkmcnt(8)
	v_cvt_pk_bf16_f32 v136, v104, v105
	v_cvt_pk_bf16_f32 v137, v106, v107
	v_cvt_pk_bf16_f32 v138, v108, v109
	v_cvt_pk_bf16_f32 v139, v110, v111
	global_store_dwordx4 v6, v[136:139], s[32:33] nt
	s_add_u32 s32, s32, s49
	s_addc_u32 s33, s33, 0
	ds_read_b32 v120, v4 offset:64
	ds_read_b32 v121, v4 offset:196
	ds_read_b32 v122, v4 offset:328
	ds_read_b32 v123, v4 offset:460
	ds_read_b32 v124, v4 offset:592
	ds_read_b32 v125, v4 offset:724
	ds_read_b32 v126, v4 offset:856
	ds_read_b32 v127, v4 offset:988
	s_waitcnt lgkmcnt(8)
	v_cvt_pk_bf16_f32 v140, v112, v113
	v_cvt_pk_bf16_f32 v141, v114, v115
	v_cvt_pk_bf16_f32 v142, v116, v117
	v_cvt_pk_bf16_f32 v143, v118, v119
	global_store_dwordx4 v6, v[140:143], s[32:33] nt
	s_add_u32 s32, s32, s49
	s_addc_u32 s33, s33, 0
	ds_read_b32 v128, v4 offset:96
	ds_read_b32 v129, v4 offset:228
	ds_read_b32 v130, v4 offset:360
	ds_read_b32 v131, v4 offset:492
	ds_read_b32 v132, v4 offset:624
	ds_read_b32 v133, v4 offset:756
	ds_read_b32 v134, v4 offset:888
	ds_read_b32 v135, v4 offset:1020
	s_waitcnt lgkmcnt(8)
	v_cvt_pk_bf16_f32 v136, v120, v121
	v_cvt_pk_bf16_f32 v137, v122, v123
	v_cvt_pk_bf16_f32 v138, v124, v125
	v_cvt_pk_bf16_f32 v139, v126, v127
	global_store_dwordx4 v6, v[136:139], s[32:33] nt
	s_add_u32 s32, s32, s49
	s_addc_u32 s33, s33, 0
	s_waitcnt lgkmcnt(0)
	v_cvt_pk_bf16_f32 v140, v128, v129
	v_cvt_pk_bf16_f32 v141, v130, v131
	v_cvt_pk_bf16_f32 v142, v132, v133
	v_cvt_pk_bf16_f32 v143, v134, v135
	global_store_dwordx4 v6, v[140:143], s[32:33] nt
	s_add_u32 s32, s32, s49
	s_addc_u32 s33, s33, 0
	s_waitcnt vmcnt(0)
	ds_write_b32 v3, v40 offset:0
	ds_write_b32 v3, v41 offset:4
	ds_write_b32 v3, v42 offset:8
	ds_write_b32 v3, v43 offset:12
	ds_write_b32 v3, v44 offset:1056
	ds_write_b32 v3, v45 offset:1060
	ds_write_b32 v3, v46 offset:1064
	ds_write_b32 v3, v47 offset:1068
	ds_write_b32 v3, v48 offset:2112
	ds_write_b32 v3, v49 offset:2116
	ds_write_b32 v3, v50 offset:2120
	ds_write_b32 v3, v51 offset:2124
	ds_write_b32 v3, v52 offset:3168
	ds_write_b32 v3, v53 offset:3172
	ds_write_b32 v3, v54 offset:3176
	ds_write_b32 v3, v55 offset:3180
	ds_write_b32 v3, v56 offset:4224
	ds_write_b32 v3, v57 offset:4228
	ds_write_b32 v3, v58 offset:4232
	ds_write_b32 v3, v59 offset:4236
	ds_write_b32 v3, v60 offset:5280
	ds_write_b32 v3, v61 offset:5284
	ds_write_b32 v3, v62 offset:5288
	ds_write_b32 v3, v63 offset:5292
	ds_write_b32 v3, v64 offset:6336
	ds_write_b32 v3, v65 offset:6340
	ds_write_b32 v3, v66 offset:6344
	ds_write_b32 v3, v67 offset:6348
	ds_write_b32 v3, v68 offset:7392
	ds_write_b32 v3, v69 offset:7396
	ds_write_b32 v3, v70 offset:7400
	ds_write_b32 v3, v71 offset:7404
	s_mov_b32 s32, s10
	s_mov_b32 s33, s11
	s_lshl_b32 s49, s47, 3
	v_mad_u32_u24 v6, v1, s47, v2
	s_waitcnt lgkmcnt(0)
	ds_read_b32 v104, v4 offset:0
	ds_read_b32 v105, v4 offset:132
	ds_read_b32 v106, v4 offset:264
	ds_read_b32 v107, v4 offset:396
	ds_read_b32 v108, v4 offset:528
	ds_read_b32 v109, v4 offset:660
	ds_read_b32 v110, v4 offset:792
	ds_read_b32 v111, v4 offset:924
	ds_read_b32 v112, v4 offset:32
	ds_read_b32 v113, v4 offset:164
	ds_read_b32 v114, v4 offset:296
	ds_read_b32 v115, v4 offset:428
	ds_read_b32 v116, v4 offset:560
	ds_read_b32 v117, v4 offset:692
	ds_read_b32 v118, v4 offset:824
	ds_read_b32 v119, v4 offset:956
	s_waitcnt lgkmcnt(8)
	v_cvt_pk_bf16_f32 v136, v104, v105
	v_cvt_pk_bf16_f32 v137, v106, v107
	v_cvt_pk_bf16_f32 v138, v108, v109
	v_cvt_pk_bf16_f32 v139, v110, v111
	global_store_dwordx4 v6, v[136:139], s[32:33] nt
	s_add_u32 s32, s32, s49
	s_addc_u32 s33, s33, 0
	ds_read_b32 v120, v4 offset:64
	ds_read_b32 v121, v4 offset:196
	ds_read_b32 v122, v4 offset:328
	ds_read_b32 v123, v4 offset:460
	ds_read_b32 v124, v4 offset:592
	ds_read_b32 v125, v4 offset:724
	ds_read_b32 v126, v4 offset:856
	ds_read_b32 v127, v4 offset:988
	s_waitcnt lgkmcnt(8)
	v_cvt_pk_bf16_f32 v140, v112, v113
	v_cvt_pk_bf16_f32 v141, v114, v115
	v_cvt_pk_bf16_f32 v142, v116, v117
	v_cvt_pk_bf16_f32 v143, v118, v119
	global_store_dwordx4 v6, v[140:143], s[32:33] nt
	s_add_u32 s32, s32, s49
	s_addc_u32 s33, s33, 0
	ds_read_b32 v128, v4 offset:96
	ds_read_b32 v129, v4 offset:228
	ds_read_b32 v130, v4 offset:360
	ds_read_b32 v131, v4 offset:492
	ds_read_b32 v132, v4 offset:624
	ds_read_b32 v133, v4 offset:756
	ds_read_b32 v134, v4 offset:888
	ds_read_b32 v135, v4 offset:1020
	s_waitcnt lgkmcnt(8)
	v_cvt_pk_bf16_f32 v136, v120, v121
	v_cvt_pk_bf16_f32 v137, v122, v123
	v_cvt_pk_bf16_f32 v138, v124, v125
	v_cvt_pk_bf16_f32 v139, v126, v127
	global_store_dwordx4 v6, v[136:139], s[32:33] nt
	s_add_u32 s32, s32, s49
	s_addc_u32 s33, s33, 0
	s_waitcnt lgkmcnt(0)
	v_cvt_pk_bf16_f32 v140, v128, v129
	v_cvt_pk_bf16_f32 v141, v130, v131
	v_cvt_pk_bf16_f32 v142, v132, v133
	v_cvt_pk_bf16_f32 v143, v134, v135
	global_store_dwordx4 v6, v[140:143], s[32:33] nt
	s_add_u32 s32, s32, s49
	s_addc_u32 s33, s33, 0
	s_branch .Ltt2_done
.Ltt2_dr3:
	s_waitcnt vmcnt(8)
	ds_write_b32 v3, v40 offset:0
	ds_write_b32 v3, v41 offset:4
	ds_write_b32 v3, v42 offset:8
	ds_write_b32 v3, v43 offset:12
	ds_write_b32 v3, v44 offset:1056
	ds_write_b32 v3, v45 offset:1060
	ds_write_b32 v3, v46 offset:1064
	ds_write_b32 v3, v47 offset:1068
	ds_write_b32 v3, v48 offset:2112
	ds_write_b32 v3, v49 offset:2116
	ds_write_b32 v3, v50 offset:2120
	ds_write_b32 v3, v51 offset:2124
	ds_write_b32 v3, v52 offset:3168
	ds_write_b32 v3, v53 offset:3172
	ds_write_b32 v3, v54 offset:3176
	ds_write_b32 v3, v55 offset:3180
	ds_write_b32 v3, v56 offset:4224
	ds_write_b32 v3, v57 offset:4228
	ds_write_b32 v3, v58 offset:4232
	ds_write_b32 v3, v59 offset:4236
	ds_write_b32 v3, v60 offset:5280
	ds_write_b32 v3, v61 offset:5284
	ds_write_b32 v3, v62 offset:5288
	ds_write_b32 v3, v63 offset:5292
	ds_write_b32 v3, v64 offset:6336
	ds_write_b32 v3, v65 offset:6340
	ds_write_b32 v3, v66 offset:6344
	ds_write_b32 v3, v67 offset:6348
	ds_write_b32 v3, v68 offset:7392
	ds_write_b32 v3, v69 offset:7396
	ds_write_b32 v3, v70 offset:7400
	ds_write_b32 v3, v71 offset:7404
	s_mov_b32 s32, s10
	s_mov_b32 s33, s11
	s_lshl_b32 s49, s47, 3
	v_mad_u32_u24 v6, v1, s47, v2
	s_waitcnt lgkmcnt(0)
	ds_read_b32 v104, v4 offset:0
	ds_read_b32 v105, v4 offset:132
	ds_read_b32 v106, v4 offset:264
	ds_read_b32 v107, v4 offset:396
	ds_read_b32 v108, v4 offset:528
	ds_read_b32 v109, v4 offset:660
	ds_read_b32 v110, v4 offset:792
	ds_read_b32 v111, v4 offset:924
	ds_read_b32 v112, v4 offset:32
	ds_read_b32 v113, v4 offset:164
	ds_read_b32 v114, v4 offset:296
	ds_read_b32 v115, v4 offset:428
	ds_read_b32 v116, v4 offset:560
	ds_read_b32 v117, v4 offset:692
	ds_read_b32 v118, v4 offset:824
	ds_read_b32 v119, v4 offset:956
	s_waitcnt lgkmcnt(8)
	v_cvt_pk_bf16_f32 v136, v104, v105
	v_cvt_pk_bf16_f32 v137, v106, v107
	v_cvt_pk_bf16_f32 v138, v108, v109
	v_cvt_pk_bf16_f32 v139, v110, v111
	global_store_dwordx4 v6, v[136:139], s[32:33] nt
	s_add_u32 s32, s32, s49
	s_addc_u32 s33, s33, 0
	ds_read_b32 v120, v4 offset:64
	ds_read_b32 v121, v4 offset:196
	ds_read_b32 v122, v4 offset:328
	ds_read_b32 v123, v4 offset:460
	ds_read_b32 v124, v4 offset:592
	ds_read_b32 v125, v4 offset:724
	ds_read_b32 v126, v4 offset:856
	ds_read_b32 v127, v4 offset:988
	s_waitcnt lgkmcnt(8)
	v_cvt_pk_bf16_f32 v140, v112, v113
	v_cvt_pk_bf16_f32 v141, v114, v115
	v_cvt_pk_bf16_f32 v142, v116, v117
	v_cvt_pk_bf16_f32 v143, v118, v119
	global_store_dwordx4 v6, v[140:143], s[32:33] nt
	s_add_u32 s32, s32, s49
	s_addc_u32 s33, s33, 0
	ds_read_b32 v128, v4 offset:96
	ds_read_b32 v129, v4 offset:228
	ds_read_b32 v130, v4 offset:360
	ds_read_b32 v131, v4 offset:492
	ds_read_b32 v132, v4 offset:624
	ds_read_b32 v133, v4 offset:756
	ds_read_b32 v134, v4 offset:888
	ds_read_b32 v135, v4 offset:1020
	s_waitcnt lgkmcnt(8)
	v_cvt_pk_bf16_f32 v136, v120, v121
	v_cvt_pk_bf16_f32 v137, v122, v123
	v_cvt_pk_bf16_f32 v138, v124, v125
	v_cvt_pk_bf16_f32 v139, v126, v127
	global_store_dwordx4 v6, v[136:139], s[32:33] nt
	s_add_u32 s32, s32, s49
	s_addc_u32 s33, s33, 0
	s_waitcnt lgkmcnt(0)
	v_cvt_pk_bf16_f32 v140, v128, v129
	v_cvt_pk_bf16_f32 v141, v130, v131
	v_cvt_pk_bf16_f32 v142, v132, v133
	v_cvt_pk_bf16_f32 v143, v134, v135
	global_store_dwordx4 v6, v[140:143], s[32:33] nt
	s_add_u32 s32, s32, s49
	s_addc_u32 s33, s33, 0
	s_waitcnt vmcnt(0)
	ds_write_b32 v3, v72 offset:0
	ds_write_b32 v3, v73 offset:4
	ds_write_b32 v3, v74 offset:8
	ds_write_b32 v3, v75 offset:12
	ds_write_b32 v3, v76 offset:1056
	ds_write_b32 v3, v77 offset:1060
	ds_write_b32 v3, v78 offset:1064
	ds_write_b32 v3, v79 offset:1068
	ds_write_b32 v3, v80 offset:2112
	ds_write_b32 v3, v81 offset:2116
	ds_write_b32 v3, v82 offset:2120
	ds_write_b32 v3, v83 offset:2124
	ds_write_b32 v3, v84 offset:3168
	ds_write_b32 v3, v85 offset:3172
	ds_write_b32 v3, v86 offset:3176
	ds_write_b32 v3, v87 offset:3180
	ds_write_b32 v3, v88 offset:4224
	ds_write_b32 v3, v89 offset:4228
	ds_write_b32 v3, v90 offset:4232
	ds_write_b32 v3, v91 offset:4236
	ds_write_b32 v3, v92 offset:5280
	ds_write_b32 v3, v93 offset:5284
	ds_write_b32 v3, v94 offset:5288
	ds_write_b32 v3, v95 offset:5292
	ds_write_b32 v3, v96 offset:6336
	ds_write_b32 v3, v97 offset:6340
	ds_write_b32 v3, v98 offset:6344
	ds_write_b32 v3, v99 offset:6348
	ds_write_b32 v3, v100 offset:7392
	ds_write_b32 v3, v101 offset:7396
	ds_write_b32 v3, v102 offset:7400
	ds_write_b32 v3, v103 offset:7404
	s_mov_b32 s32, s42
	s_mov_b32 s33, s43
	s_lshl_b32 s49, s44, 3
	v_mad_u32_u24 v6, v1, s44, v2
	s_waitcnt lgkmcnt(0)
	ds_read_b32 v104, v4 offset:0
	ds_read_b32 v105, v4 offset:132
	ds_read_b32 v106, v4 offset:264
	ds_read_b32 v107, v4 offset:396
	ds_read_b32 v108, v4 offset:528
	ds_read_b32 v109, v4 offset:660
	ds_read_b32 v110, v4 offset:792
	ds_read_b32 v111, v4 offset:924
	ds_read_b32 v112, v4 offset:32
	ds_read_b32 v113, v4 offset:164
	ds_read_b32 v114, v4 offset:296
	ds_read_b32 v115, v4 offset:428
	ds_read_b32 v116, v4 offset:560
	ds_read_b32 v117, v4 offset:692
	ds_read_b32 v118, v4 offset:824
	ds_read_b32 v119, v4 offset:956
	s_waitcnt lgkmcnt(8)
	v_cvt_pk_bf16_f32 v136, v104, v105
	v_cvt_pk_bf16_f32 v137, v106, v107
	v_cvt_pk_bf16_f32 v138, v108, v109
	v_cvt_pk_bf16_f32 v139, v110, v111
	global_store_dwordx4 v6, v[136:139], s[32:33] nt
	s_add_u32 s32, s32, s49
	s_addc_u32 s33, s33, 0
	ds_read_b32 v120, v4 offset:64
	ds_read_b32 v121, v4 offset:196
	ds_read_b32 v122, v4 offset:328
	ds_read_b32 v123, v4 offset:460
	ds_read_b32 v124, v4 offset:592
	ds_read_b32 v125, v4 offset:724
	ds_read_b32 v126, v4 offset:856
	ds_read_b32 v127, v4 offset:988
	s_waitcnt lgkmcnt(8)
	v_cvt_pk_bf16_f32 v140, v112, v113
	v_cvt_pk_bf16_f32 v141, v114, v115
	v_cvt_pk_bf16_f32 v142, v116, v117
	v_cvt_pk_bf16_f32 v143, v118, v119
	global_store_dwordx4 v6, v[140:143], s[32:33] nt
	s_add_u32 s32, s32, s49
	s_addc_u32 s33, s33, 0
	ds_read_b32 v128, v4 offset:96
	ds_read_b32 v129, v4 offset:228
	ds_read_b32 v130, v4 offset:360
	ds_read_b32 v131, v4 offset:492
	ds_read_b32 v132, v4 offset:624
	ds_read_b32 v133, v4 offset:756
	ds_read_b32 v134, v4 offset:888
	ds_read_b32 v135, v4 offset:1020
	s_waitcnt lgkmcnt(8)
	v_cvt_pk_bf16_f32 v136, v120, v121
	v_cvt_pk_bf16_f32 v137, v122, v123
	v_cvt_pk_bf16_f32 v138, v124, v125
	v_cvt_pk_bf16_f32 v139, v126, v127
	global_store_dwordx4 v6, v[136:139], s[32:33] nt
	s_add_u32 s32, s32, s49
	s_addc_u32 s33, s33, 0
	s_waitcnt lgkmcnt(0)
	v_cvt_pk_bf16_f32 v140, v128, v129
	v_cvt_pk_bf16_f32 v141, v130, v131
	v_cvt_pk_bf16_f32 v142, v132, v133
	v_cvt_pk_bf16_f32 v143, v134, v135
	global_store_dwordx4 v6, v[140:143], s[32:33] nt
	s_add_u32 s32, s32, s49
	s_addc_u32 s33, s33, 0
	s_branch .Ltt2_done
.Ltt2_dr4:
	s_waitcnt vmcnt(8)
	ds_write_b32 v3, v72 offset:0
	ds_write_b32 v3, v73 offset:4
	ds_write_b32 v3, v74 offset:8
	ds_write_b32 v3, v75 offset:12
	ds_write_b32 v3, v76 offset:1056
	ds_write_b32 v3, v77 offset:1060
	ds_write_b32 v3, v78 offset:1064
	ds_write_b32 v3, v79 offset:1068
	ds_write_b32 v3, v80 offset:2112
	ds_write_b32 v3, v81 offset:2116
	ds_write_b32 v3, v82 offset:2120
	ds_write_b32 v3, v83 offset:2124
	ds_write_b32 v3, v84 offset:3168
	ds_write_b32 v3, v85 offset:3172
	ds_write_b32 v3, v86 offset:3176
	ds_write_b32 v3, v87 offset:3180
	ds_write_b32 v3, v88 offset:4224
	ds_write_b32 v3, v89 offset:4228
	ds_write_b32 v3, v90 offset:4232
	ds_write_b32 v3, v91 offset:4236
	ds_write_b32 v3, v92 offset:5280
	ds_write_b32 v3, v93 offset:5284
	ds_write_b32 v3, v94 offset:5288
	ds_write_b32 v3, v95 offset:5292
	ds_write_b32 v3, v96 offset:6336
	ds_write_b32 v3, v97 offset:6340
	ds_write_b32 v3, v98 offset:6344
	ds_write_b32 v3, v99 offset:6348
	ds_write_b32 v3, v100 offset:7392
	ds_write_b32 v3, v101 offset:7396
	ds_write_b32 v3, v102 offset:7400
	ds_write_b32 v3, v103 offset:7404
	s_mov_b32 s32, s42
	s_mov_b32 s33, s43
	s_lshl_b32 s49, s44, 3
	v_mad_u32_u24 v6, v1, s44, v2
	s_waitcnt lgkmcnt(0)
	ds_read_b32 v104, v4 offset:0
	ds_read_b32 v105, v4 offset:132
	ds_read_b32 v106, v4 offset:264
	ds_read_b32 v107, v4 offset:396
	ds_read_b32 v108, v4 offset:528
	ds_read_b32 v109, v4 offset:660
	ds_read_b32 v110, v4 offset:792
	ds_read_b32 v111, v4 offset:924
	ds_read_b32 v112, v4 offset:32
	ds_read_b32 v113, v4 offset:164
	ds_read_b32 v114, v4 offset:296
	ds_read_b32 v115, v4 offset:428
	ds_read_b32 v116, v4 offset:560
	ds_read_b32 v117, v4 offset:692
	ds_read_b32 v118, v4 offset:824
	ds_read_b32 v119, v4 offset:956
	s_waitcnt lgkmcnt(8)
	v_cvt_pk_bf16_f32 v136, v104, v105
	v_cvt_pk_bf16_f32 v137, v106, v107
	v_cvt_pk_bf16_f32 v138, v108, v109
	v_cvt_pk_bf16_f32 v139, v110, v111
	global_store_dwordx4 v6, v[136:139], s[32:33] nt
	s_add_u32 s32, s32, s49
	s_addc_u32 s33, s33, 0
	ds_read_b32 v120, v4 offset:64
	ds_read_b32 v121, v4 offset:196
	ds_read_b32 v122, v4 offset:328
	ds_read_b32 v123, v4 offset:460
	ds_read_b32 v124, v4 offset:592
	ds_read_b32 v125, v4 offset:724
	ds_read_b32 v126, v4 offset:856
	ds_read_b32 v127, v4 offset:988
	s_waitcnt lgkmcnt(8)
	v_cvt_pk_bf16_f32 v140, v112, v113
	v_cvt_pk_bf16_f32 v141, v114, v115
	v_cvt_pk_bf16_f32 v142, v116, v117
	v_cvt_pk_bf16_f32 v143, v118, v119
	global_store_dwordx4 v6, v[140:143], s[32:33] nt
	s_add_u32 s32, s32, s49
	s_addc_u32 s33, s33, 0
	ds_read_b32 v128, v4 offset:96
	ds_read_b32 v129, v4 offset:228
	ds_read_b32 v130, v4 offset:360
	ds_read_b32 v131, v4 offset:492
	ds_read_b32 v132, v4 offset:624
	ds_read_b32 v133, v4 offset:756
	ds_read_b32 v134, v4 offset:888
	ds_read_b32 v135, v4 offset:1020
	s_waitcnt lgkmcnt(8)
	v_cvt_pk_bf16_f32 v136, v120, v121
	v_cvt_pk_bf16_f32 v137, v122, v123
	v_cvt_pk_bf16_f32 v138, v124, v125
	v_cvt_pk_bf16_f32 v139, v126, v127
	global_store_dwordx4 v6, v[136:139], s[32:33] nt
	s_add_u32 s32, s32, s49
	s_addc_u32 s33, s33, 0
	s_waitcnt lgkmcnt(0)
	v_cvt_pk_bf16_f32 v140, v128, v129
	v_cvt_pk_bf16_f32 v141, v130, v131
	v_cvt_pk_bf16_f32 v142, v132, v133
	v_cvt_pk_bf16_f32 v143, v134, v135
	global_store_dwordx4 v6, v[140:143], s[32:33] nt
	s_add_u32 s32, s32, s49
	s_addc_u32 s33, s33, 0
	s_waitcnt vmcnt(0)
	ds_write_b32 v3, v8 offset:0
	ds_write_b32 v3, v9 offset:4
	ds_write_b32 v3, v10 offset:8
	ds_write_b32 v3, v11 offset:12
	ds_write_b32 v3, v12 offset:1056
	ds_write_b32 v3, v13 offset:1060
	ds_write_b32 v3, v14 offset:1064
	ds_write_b32 v3, v15 offset:1068
	ds_write_b32 v3, v16 offset:2112
	ds_write_b32 v3, v17 offset:2116
	ds_write_b32 v3, v18 offset:2120
	ds_write_b32 v3, v19 offset:2124
	ds_write_b32 v3, v20 offset:3168
	ds_write_b32 v3, v21 offset:3172
	ds_write_b32 v3, v22 offset:3176
	ds_write_b32 v3, v23 offset:3180
	ds_write_b32 v3, v24 offset:4224
	ds_write_b32 v3, v25 offset:4228
	ds_write_b32 v3, v26 offset:4232
	ds_write_b32 v3, v27 offset:4236
	ds_write_b32 v3, v28 offset:5280
	ds_write_b32 v3, v29 offset:5284
	ds_write_b32 v3, v30 offset:5288
	ds_write_b32 v3, v31 offset:5292
	ds_write_b32 v3, v32 offset:6336
	ds_write_b32 v3, v33 offset:6340
	ds_write_b32 v3, v34 offset:6344
	ds_write_b32 v3, v35 offset:6348
	ds_write_b32 v3, v36 offset:7392
	ds_write_b32 v3, v37 offset:7396
	ds_write_b32 v3, v38 offset:7400
	ds_write_b32 v3, v39 offset:7404
	s_mov_b32 s32, s2
	s_mov_b32 s33, s3
	s_lshl_b32 s49, s7, 3
	v_mad_u32_u24 v6, v1, s7, v2
	s_waitcnt lgkmcnt(0)
	ds_read_b32 v104, v4 offset:0
	ds_read_b32 v105, v4 offset:132
	ds_read_b32 v106, v4 offset:264
	ds_read_b32 v107, v4 offset:396
	ds_read_b32 v108, v4 offset:528
	ds_read_b32 v109, v4 offset:660
	ds_read_b32 v110, v4 offset:792
	ds_read_b32 v111, v4 offset:924
	ds_read_b32 v112, v4 offset:32
	ds_read_b32 v113, v4 offset:164
	ds_read_b32 v114, v4 offset:296
	ds_read_b32 v115, v4 offset:428
	ds_read_b32 v116, v4 offset:560
	ds_read_b32 v117, v4 offset:692
	ds_read_b32 v118, v4 offset:824
	ds_read_b32 v119, v4 offset:956
	s_waitcnt lgkmcnt(8)
	v_cvt_pk_bf16_f32 v136, v104, v105
	v_cvt_pk_bf16_f32 v137, v106, v107
	v_cvt_pk_bf16_f32 v138, v108, v109
	v_cvt_pk_bf16_f32 v139, v110, v111
	global_store_dwordx4 v6, v[136:139], s[32:33] nt
	s_add_u32 s32, s32, s49
	s_addc_u32 s33, s33, 0
	ds_read_b32 v120, v4 offset:64
	ds_read_b32 v121, v4 offset:196
	ds_read_b32 v122, v4 offset:328
	ds_read_b32 v123, v4 offset:460
	ds_read_b32 v124, v4 offset:592
	ds_read_b32 v125, v4 offset:724
	ds_read_b32 v126, v4 offset:856
	ds_read_b32 v127, v4 offset:988
	s_waitcnt lgkmcnt(8)
	v_cvt_pk_bf16_f32 v140, v112, v113
	v_cvt_pk_bf16_f32 v141, v114, v115
	v_cvt_pk_bf16_f32 v142, v116, v117
	v_cvt_pk_bf16_f32 v143, v118, v119
	global_store_dwordx4 v6, v[140:143], s[32:33] nt
	s_add_u32 s32, s32, s49
	s_addc_u32 s33, s33, 0
	ds_read_b32 v128, v4 offset:96
	ds_read_b32 v129, v4 offset:228
	ds_read_b32 v130, v4 offset:360
	ds_read_b32 v131, v4 offset:492
	ds_read_b32 v132, v4 offset:624
	ds_read_b32 v133, v4 offset:756
	ds_read_b32 v134, v4 offset:888
	ds_read_b32 v135, v4 offset:1020
	s_waitcnt lgkmcnt(8)
	v_cvt_pk_bf16_f32 v136, v120, v121
	v_cvt_pk_bf16_f32 v137, v122, v123
	v_cvt_pk_bf16_f32 v138, v124, v125
	v_cvt_pk_bf16_f32 v139, v126, v127
	global_store_dwordx4 v6, v[136:139], s[32:33] nt
	s_add_u32 s32, s32, s49
	s_addc_u32 s33, s33, 0
	s_waitcnt lgkmcnt(0)
	v_cvt_pk_bf16_f32 v140, v128, v129
	v_cvt_pk_bf16_f32 v141, v130, v131
	v_cvt_pk_bf16_f32 v142, v132, v133
	v_cvt_pk_bf16_f32 v143, v134, v135
	global_store_dwordx4 v6, v[140:143], s[32:33] nt
	s_add_u32 s32, s32, s49
	s_addc_u32 s33, s33, 0
	s_branch .Ltt2_done

.LBB0_832:
	s_waitcnt vmcnt(0)
	s_barrier
	s_cmp_lg_u32 s87, 0x100
	s_cbranch_scc1 .Ltt7_done
	s_cmp_lt_u32 s96, 128
	s_cbranch_scc1 .Ltt7_done
	s_sub_u32 s20, s96, 128
	s_lshl_b32 s20, s20, 3
	s_add_u32 s20, s20, s93
	s_movk_i32 s23, 1024
	v_mbcnt_hi_u32_b32 v0, -1, v212
	v_and_b32_e32 v0, 63, v0
	v_lshrrev_b32_e32 v1, 3, v0
	v_and_b32_e32 v2, 7, v0
	s_lshl_b32 s25, s93, 14
	v_mul_u32_u24_e32 v3, 0x84, v1
	v_mul_u32_u24_e32 v4, 0x420, v2
	v_lshlrev_b32_e32 v2, 4, v2
	v_add3_u32 v3, v3, v2, s25
	v_lshl_add_u32 v4, v1, 2, v4
	v_add_u32_e32 v4, s25, v4
	v_and_b32_e32 v7, 4, v1
	v_and_b32_e32 v5, 3, v1
	v_lshl_add_u32 v7, v7, 1, v5
	v_readlane_b32 s62, v244, 21
	v_readlane_b32 s63, v244, 22
	s_add_u32 s64, s76, 0x8989000
	s_addc_u32 s65, s77, 0
	v_readlane_b32 s66, v245, 0
	v_readlane_b32 s67, v245, 1
	s_add_u32 s68, s76, 0x6989000
	s_addc_u32 s69, s77, 0
	s_nop 0
	s_add_u32 s66, s66, 0x4000000
	s_addc_u32 s67, s67, 0
	s_cmp_ge_u32 s20, 12288
	s_cbranch_scc1 .Ltt7_done
	s_cmp_lt_u32 s20, 4096
	s_cbranch_scc1 .Ltt7_r1_s0
	s_sub_u32 s25, s20, 4096
	s_lshr_b32 s27, s25, 8
	s_and_b32 s31, s25, 255
	s_mul_i32 s35, s27, 0x200000
	s_lshl_b32 s41, s31, 7
	s_add_u32 s35, s35, s41
	s_add_u32 s0, s66, s35
	s_addc_u32 s1, s67, 0
	s_mul_i32 s35, s31, 0x20000
	s_lshl_b32 s41, s27, 7
	s_add_u32 s35, s35, s41
	s_add_u32 s2, s68, s35
	s_addc_u32 s3, s69, 0
	s_mov_b32 s5, 0x8000
	s_mov_b32 s6, 0x40000
	s_mov_b32 s7, 0x1000
	s_branch .Ltt7_r1_e

.Ltt7_r2_e:
	v_mad_u32_u24 v5, v1, s5, v2
	global_load_dwordx4 v[40:43], v5, s[0:1] nt
	s_add_u32 s0, s0, s6
	s_addc_u32 s1, s1, 0
	global_load_dwordx4 v[44:47], v5, s[0:1] nt
	s_add_u32 s0, s0, s6
	s_addc_u32 s1, s1, 0
	global_load_dwordx4 v[48:51], v5, s[0:1] nt
	s_add_u32 s0, s0, s6
	s_addc_u32 s1, s1, 0
	global_load_dwordx4 v[52:55], v5, s[0:1] nt
	s_add_u32 s0, s0, s6
	s_addc_u32 s1, s1, 0
	global_load_dwordx4 v[56:59], v5, s[0:1] nt
	s_add_u32 s0, s0, s6
	s_addc_u32 s1, s1, 0
	global_load_dwordx4 v[60:63], v5, s[0:1] nt
	s_add_u32 s0, s0, s6
	s_addc_u32 s1, s1, 0
	global_load_dwordx4 v[64:67], v5, s[0:1] nt
	s_add_u32 s0, s0, s6
	s_addc_u32 s1, s1, 0
	global_load_dwordx4 v[68:71], v5, s[0:1] nt
	s_add_u32 s0, s0, s6
	s_addc_u32 s1, s1, 0
	s_add_u32 s20, s20, s23
	s_cmp_ge_u32 s20, 12288
	s_cbranch_scc1 .Ltt7_dr2
	s_cmp_lt_u32 s20, 4096
	s_cbranch_scc1 .Ltt7_r3_s0
	s_sub_u32 s25, s20, 4096
	s_lshr_b32 s27, s25, 8
	s_and_b32 s31, s25, 255
	s_mul_i32 s35, s27, 0x200000
	s_lshl_b32 s41, s31, 7
	s_add_u32 s35, s35, s41
	s_add_u32 s0, s66, s35
	s_addc_u32 s1, s67, 0
	s_mul_i32 s35, s31, 0x20000
	s_lshl_b32 s41, s27, 7
	s_add_u32 s35, s35, s41
	s_add_u32 s42, s68, s35
	s_addc_u32 s43, s69, 0
	s_mov_b32 s5, 0x8000
	s_mov_b32 s6, 0x40000
	s_mov_b32 s44, 0x1000
	s_branch .Ltt7_r3_e
.Ltt7_r3_s0:
	s_sub_u32 s25, s20, -4096
	s_lshr_b32 s27, s25, 6
	s_and_b32 s31, s25, 63
	s_mul_i32 s35, s27, 0x80000
	s_lshl_b32 s41, s31, 7
	s_add_u32 s35, s35, s41
	s_add_u32 s0, s62, s35
	s_addc_u32 s1, s63, 0
	s_mul_i32 s35, s31, 0x80000
	s_lshl_b32 s41, s27, 7
	s_add_u32 s35, s35, s41
	s_add_u32 s42, s64, s35
	s_addc_u32 s43, s65, 0
	s_mov_b32 s5, 0x2000
	s_mov_b32 s6, 0x10000
	s_mov_b32 s44, 0x4000
.Ltt7_r3_e:
	v_mad_u32_u24 v5, v1, s5, v2
	global_load_dwordx4 v[72:75], v5, s[0:1] nt
	s_add_u32 s0, s0, s6
	s_addc_u32 s1, s1, 0
	global_load_dwordx4 v[76:79], v5, s[0:1] nt
	s_add_u32 s0, s0, s6
	s_addc_u32 s1, s1, 0
	global_load_dwordx4 v[80:83], v5, s[0:1] nt
	s_add_u32 s0, s0, s6
	s_addc_u32 s1, s1, 0
	global_load_dwordx4 v[84:87], v5, s[0:1] nt
	s_add_u32 s0, s0, s6
	s_addc_u32 s1, s1, 0
	global_load_dwordx4 v[88:91], v5, s[0:1] nt
	s_add_u32 s0, s0, s6
	s_addc_u32 s1, s1, 0
	global_load_dwordx4 v[92:95], v5, s[0:1] nt
	s_add_u32 s0, s0, s6
	s_addc_u32 s1, s1, 0
	global_load_dwordx4 v[96:99], v5, s[0:1] nt
	s_add_u32 s0, s0, s6
	s_addc_u32 s1, s1, 0
	global_load_dwordx4 v[100:103], v5, s[0:1] nt
	s_add_u32 s0, s0, s6
	s_addc_u32 s1, s1, 0
	s_add_u32 s20, s20, s23
	s_waitcnt vmcnt(16)
	ds_write_b32 v3, v8 offset:0
	ds_write_b32 v3, v9 offset:4
	ds_write_b32 v3, v10 offset:8
	ds_write_b32 v3, v11 offset:12
	ds_write_b32 v3, v12 offset:1056
	ds_write_b32 v3, v13 offset:1060
	ds_write_b32 v3, v14 offset:1064
	ds_write_b32 v3, v15 offset:1068
	ds_write_b32 v3, v16 offset:2112
	ds_write_b32 v3, v17 offset:2116
	ds_write_b32 v3, v18 offset:2120
	ds_write_b32 v3, v19 offset:2124
	ds_write_b32 v3, v20 offset:3168
	ds_write_b32 v3, v21 offset:3172
	ds_write_b32 v3, v22 offset:3176
	ds_write_b32 v3, v23 offset:3180
	ds_write_b32 v3, v24 offset:4224
	ds_write_b32 v3, v25 offset:4228
	ds_write_b32 v3, v26 offset:4232
	ds_write_b32 v3, v27 offset:4236
	ds_write_b32 v3, v28 offset:5280
	ds_write_b32 v3, v29 offset:5284
	ds_write_b32 v3, v30 offset:5288
	ds_write_b32 v3, v31 offset:5292
	ds_write_b32 v3, v32 offset:6336
	ds_write_b32 v3, v33 offset:6340
	ds_write_b32 v3, v34 offset:6344
	ds_write_b32 v3, v35 offset:6348
	ds_write_b32 v3, v36 offset:7392
	ds_write_b32 v3, v37 offset:7396
	ds_write_b32 v3, v38 offset:7400
	ds_write_b32 v3, v39 offset:7404
	s_mov_b32 s32, s2
	s_mov_b32 s33, s3
	s_lshl_b32 s49, s7, 3
	v_mad_u32_u24 v6, v1, s7, v2
	s_waitcnt lgkmcnt(0)
	ds_read_b32 v104, v4 offset:0
	ds_read_b32 v105, v4 offset:132
	ds_read_b32 v106, v4 offset:264
	ds_read_b32 v107, v4 offset:396
	ds_read_b32 v108, v4 offset:528
	ds_read_b32 v109, v4 offset:660
	ds_read_b32 v110, v4 offset:792
	ds_read_b32 v111, v4 offset:924
	ds_read_b32 v112, v4 offset:32
	ds_read_b32 v113, v4 offset:164
	ds_read_b32 v114, v4 offset:296
	ds_read_b32 v115, v4 offset:428
	ds_read_b32 v116, v4 offset:560
	ds_read_b32 v117, v4 offset:692
	ds_read_b32 v118, v4 offset:824
	ds_read_b32 v119, v4 offset:956
	s_waitcnt lgkmcnt(8)
	v_cvt_pk_bf16_f32 v136, v104, v105
	v_cvt_pk_bf16_f32 v137, v106, v107
	v_cvt_pk_bf16_f32 v138, v108, v109
	v_cvt_pk_bf16_f32 v139, v110, v111
	global_store_dwordx4 v6, v[136:139], s[32:33] nt
	s_add_u32 s32, s32, s49
	s_addc_u32 s33, s33, 0
	ds_read_b32 v120, v4 offset:64
	ds_read_b32 v121, v4 offset:196
	ds_read_b32 v122, v4 offset:328
	ds_read_b32 v123, v4 offset:460
	ds_read_b32 v124, v4 offset:592
	ds_read_b32 v125, v4 offset:724
	ds_read_b32 v126, v4 offset:856
	ds_read_b32 v127, v4 offset:988
	s_waitcnt lgkmcnt(8)
	v_cvt_pk_bf16_f32 v140, v112, v113
	v_cvt_pk_bf16_f32 v141, v114, v115
	v_cvt_pk_bf16_f32 v142, v116, v117
	v_cvt_pk_bf16_f32 v143, v118, v119
	global_store_dwordx4 v6, v[140:143], s[32:33] nt
	s_add_u32 s32, s32, s49
	s_addc_u32 s33, s33, 0
	ds_read_b32 v128, v4 offset:96
	ds_read_b32 v129, v4 offset:228
	ds_read_b32 v130, v4 offset:360
	ds_read_b32 v131, v4 offset:492
	ds_read_b32 v132, v4 offset:624
	ds_read_b32 v133, v4 offset:756
	ds_read_b32 v134, v4 offset:888
	ds_read_b32 v135, v4 offset:1020
	s_waitcnt lgkmcnt(8)
	v_cvt_pk_bf16_f32 v136, v120, v121
	v_cvt_pk_bf16_f32 v137, v122, v123
	v_cvt_pk_bf16_f32 v138, v124, v125
	v_cvt_pk_bf16_f32 v139, v126, v127
	global_store_dwordx4 v6, v[136:139], s[32:33] nt
	s_add_u32 s32, s32, s49
	s_addc_u32 s33, s33, 0
	s_waitcnt lgkmcnt(0)
	v_cvt_pk_bf16_f32 v140, v128, v129
	v_cvt_pk_bf16_f32 v141, v130, v131
	v_cvt_pk_bf16_f32 v142, v132, v133
	v_cvt_pk_bf16_f32 v143, v134, v135
	global_store_dwordx4 v6, v[140:143], s[32:33] nt
	s_add_u32 s32, s32, s49
	s_addc_u32 s33, s33, 0
	s_cmp_ge_u32 s20, 12288
	s_cbranch_scc1 .Ltt7_dr3
	s_cmp_lt_u32 s20, 4096
	s_cbranch_scc1 .Ltt7_r4_s0
	s_sub_u32 s25, s20, 4096
	s_lshr_b32 s27, s25, 8
	s_and_b32 s31, s25, 255
	s_mul_i32 s35, s27, 0x200000
	s_lshl_b32 s41, s31, 7
	s_add_u32 s35, s35, s41
	s_add_u32 s0, s66, s35
	s_addc_u32 s1, s67, 0
	s_mul_i32 s35, s31, 0x20000
	s_lshl_b32 s41, s27, 7
	s_add_u32 s35, s35, s41
	s_add_u32 s2, s68, s35
	s_addc_u32 s3, s69, 0
	s_mov_b32 s5, 0x8000
	s_mov_b32 s6, 0x40000
	s_mov_b32 s7, 0x1000
	s_branch .Ltt7_r4_e

.Ltt7_loop:
	s_cmp_ge_u32 s20, 12288
	s_cbranch_scc1 .Ltt7_dr4
	s_cmp_lt_u32 s20, 4096
	s_cbranch_scc1 .Ltt7_r5_s0
	s_sub_u32 s25, s20, 4096
	s_lshr_b32 s27, s25, 8
	s_and_b32 s31, s25, 255
	s_mul_i32 s35, s27, 0x200000
	s_lshl_b32 s41, s31, 7
	s_add_u32 s35, s35, s41
	s_add_u32 s0, s66, s35
	s_addc_u32 s1, s67, 0
	s_mul_i32 s35, s31, 0x20000
	s_lshl_b32 s41, s27, 7
	s_add_u32 s35, s35, s41
	s_add_u32 s10, s68, s35
	s_addc_u32 s11, s69, 0
	s_mov_b32 s5, 0x8000
	s_mov_b32 s6, 0x40000
	s_mov_b32 s47, 0x1000
	s_branch .Ltt7_r5_e

.Ltt7_r5_e:
	v_mad_u32_u24 v5, v1, s5, v2
	global_load_dwordx4 v[40:43], v5, s[0:1] nt
	s_add_u32 s0, s0, s6
	s_addc_u32 s1, s1, 0
	global_load_dwordx4 v[44:47], v5, s[0:1] nt
	s_add_u32 s0, s0, s6
	s_addc_u32 s1, s1, 0
	global_load_dwordx4 v[48:51], v5, s[0:1] nt
	s_add_u32 s0, s0, s6
	s_addc_u32 s1, s1, 0
	global_load_dwordx4 v[52:55], v5, s[0:1] nt
	s_add_u32 s0, s0, s6
	s_addc_u32 s1, s1, 0
	global_load_dwordx4 v[56:59], v5, s[0:1] nt
	s_add_u32 s0, s0, s6
	s_addc_u32 s1, s1, 0
	global_load_dwordx4 v[60:63], v5, s[0:1] nt
	s_add_u32 s0, s0, s6
	s_addc_u32 s1, s1, 0
	global_load_dwordx4 v[64:67], v5, s[0:1] nt
	s_add_u32 s0, s0, s6
	s_addc_u32 s1, s1, 0
	global_load_dwordx4 v[68:71], v5, s[0:1] nt
	s_add_u32 s0, s0, s6
	s_addc_u32 s1, s1, 0
	s_add_u32 s20, s20, s23
	s_waitcnt vmcnt(24)
	ds_write_b32 v3, v72 offset:0
	ds_write_b32 v3, v73 offset:4
	ds_write_b32 v3, v74 offset:8
	ds_write_b32 v3, v75 offset:12
	ds_write_b32 v3, v76 offset:1056
	ds_write_b32 v3, v77 offset:1060
	ds_write_b32 v3, v78 offset:1064
	ds_write_b32 v3, v79 offset:1068
	ds_write_b32 v3, v80 offset:2112
	ds_write_b32 v3, v81 offset:2116
	ds_write_b32 v3, v82 offset:2120
	ds_write_b32 v3, v83 offset:2124
	ds_write_b32 v3, v84 offset:3168
	ds_write_b32 v3, v85 offset:3172
	ds_write_b32 v3, v86 offset:3176
	ds_write_b32 v3, v87 offset:3180
	ds_write_b32 v3, v88 offset:4224
	ds_write_b32 v3, v89 offset:4228
	ds_write_b32 v3, v90 offset:4232
	ds_write_b32 v3, v91 offset:4236
	ds_write_b32 v3, v92 offset:5280
	ds_write_b32 v3, v93 offset:5284
	ds_write_b32 v3, v94 offset:5288
	ds_write_b32 v3, v95 offset:5292
	ds_write_b32 v3, v96 offset:6336
	ds_write_b32 v3, v97 offset:6340
	ds_write_b32 v3, v98 offset:6344
	ds_write_b32 v3, v99 offset:6348
	ds_write_b32 v3, v100 offset:7392
	ds_write_b32 v3, v101 offset:7396
	ds_write_b32 v3, v102 offset:7400
	ds_write_b32 v3, v103 offset:7404
	s_mov_b32 s32, s42
	s_mov_b32 s33, s43
	s_lshl_b32 s49, s44, 3
	v_mad_u32_u24 v6, v1, s44, v2
	s_waitcnt lgkmcnt(0)
	ds_read_b32 v104, v4 offset:0
	ds_read_b32 v105, v4 offset:132
	ds_read_b32 v106, v4 offset:264
	ds_read_b32 v107, v4 offset:396
	ds_read_b32 v108, v4 offset:528
	ds_read_b32 v109, v4 offset:660
	ds_read_b32 v110, v4 offset:792
	ds_read_b32 v111, v4 offset:924
	ds_read_b32 v112, v4 offset:32
	ds_read_b32 v113, v4 offset:164
	ds_read_b32 v114, v4 offset:296
	ds_read_b32 v115, v4 offset:428
	ds_read_b32 v116, v4 offset:560
	ds_read_b32 v117, v4 offset:692
	ds_read_b32 v118, v4 offset:824
	ds_read_b32 v119, v4 offset:956
	s_waitcnt lgkmcnt(8)
	v_cvt_pk_bf16_f32 v136, v104, v105
	v_cvt_pk_bf16_f32 v137, v106, v107
	v_cvt_pk_bf16_f32 v138, v108, v109
	v_cvt_pk_bf16_f32 v139, v110, v111
	global_store_dwordx4 v6, v[136:139], s[32:33] nt
	s_add_u32 s32, s32, s49
	s_addc_u32 s33, s33, 0
	ds_read_b32 v120, v4 offset:64
	ds_read_b32 v121, v4 offset:196
	ds_read_b32 v122, v4 offset:328
	ds_read_b32 v123, v4 offset:460
	ds_read_b32 v124, v4 offset:592
	ds_read_b32 v125, v4 offset:724
	ds_read_b32 v126, v4 offset:856
	ds_read_b32 v127, v4 offset:988
	s_waitcnt lgkmcnt(8)
	v_cvt_pk_bf16_f32 v140, v112, v113
	v_cvt_pk_bf16_f32 v141, v114, v115
	v_cvt_pk_bf16_f32 v142, v116, v117
	v_cvt_pk_bf16_f32 v143, v118, v119
	global_store_dwordx4 v6, v[140:143], s[32:33] nt
	s_add_u32 s32, s32, s49
	s_addc_u32 s33, s33, 0
	ds_read_b32 v128, v4 offset:96
	ds_read_b32 v129, v4 offset:228
	ds_read_b32 v130, v4 offset:360
	ds_read_b32 v131, v4 offset:492
	ds_read_b32 v132, v4 offset:624
	ds_read_b32 v133, v4 offset:756
	ds_read_b32 v134, v4 offset:888
	ds_read_b32 v135, v4 offset:1020
	s_waitcnt lgkmcnt(8)
	v_cvt_pk_bf16_f32 v136, v120, v121
	v_cvt_pk_bf16_f32 v137, v122, v123
	v_cvt_pk_bf16_f32 v138, v124, v125
	v_cvt_pk_bf16_f32 v139, v126, v127
	global_store_dwordx4 v6, v[136:139], s[32:33] nt
	s_add_u32 s32, s32, s49
	s_addc_u32 s33, s33, 0
	s_waitcnt lgkmcnt(0)
	v_cvt_pk_bf16_f32 v140, v128, v129
	v_cvt_pk_bf16_f32 v141, v130, v131
	v_cvt_pk_bf16_f32 v142, v132, v133
	v_cvt_pk_bf16_f32 v143, v134, v135
	global_store_dwordx4 v6, v[140:143], s[32:33] nt
	s_add_u32 s32, s32, s49
	s_addc_u32 s33, s33, 0
	s_cmp_ge_u32 s20, 12288
	s_cbranch_scc1 .Ltt7_dr5
	s_cmp_lt_u32 s20, 4096
	s_cbranch_scc1 .Ltt7_r6_s0
	s_sub_u32 s25, s20, 4096
	s_lshr_b32 s27, s25, 8
	s_and_b32 s31, s25, 255
	s_mul_i32 s35, s27, 0x200000
	s_lshl_b32 s41, s31, 7
	s_add_u32 s35, s35, s41
	s_add_u32 s0, s66, s35
	s_addc_u32 s1, s67, 0
	s_mul_i32 s35, s31, 0x20000
	s_lshl_b32 s41, s27, 7
	s_add_u32 s35, s35, s41
	s_add_u32 s42, s68, s35
	s_addc_u32 s43, s69, 0
	s_mov_b32 s5, 0x8000
	s_mov_b32 s6, 0x40000
	s_mov_b32 s44, 0x1000
	s_branch .Ltt7_r6_e

.Ltt7_r6_e:
	v_mad_u32_u24 v5, v1, s5, v2
	global_load_dwordx4 v[72:75], v5, s[0:1] nt
	s_add_u32 s0, s0, s6
	s_addc_u32 s1, s1, 0
	global_load_dwordx4 v[76:79], v5, s[0:1] nt
	s_add_u32 s0, s0, s6
	s_addc_u32 s1, s1, 0
	global_load_dwordx4 v[80:83], v5, s[0:1] nt
	s_add_u32 s0, s0, s6
	s_addc_u32 s1, s1, 0
	global_load_dwordx4 v[84:87], v5, s[0:1] nt
	s_add_u32 s0, s0, s6
	s_addc_u32 s1, s1, 0
	global_load_dwordx4 v[88:91], v5, s[0:1] nt
	s_add_u32 s0, s0, s6
	s_addc_u32 s1, s1, 0
	global_load_dwordx4 v[92:95], v5, s[0:1] nt
	s_add_u32 s0, s0, s6
	s_addc_u32 s1, s1, 0
	global_load_dwordx4 v[96:99], v5, s[0:1] nt
	s_add_u32 s0, s0, s6
	s_addc_u32 s1, s1, 0
	global_load_dwordx4 v[100:103], v5, s[0:1] nt
	s_add_u32 s0, s0, s6
	s_addc_u32 s1, s1, 0
	s_add_u32 s20, s20, s23
	s_waitcnt vmcnt(24)
	ds_write_b32 v3, v8 offset:0
	ds_write_b32 v3, v9 offset:4
	ds_write_b32 v3, v10 offset:8
	ds_write_b32 v3, v11 offset:12
	ds_write_b32 v3, v12 offset:1056
	ds_write_b32 v3, v13 offset:1060
	ds_write_b32 v3, v14 offset:1064
	ds_write_b32 v3, v15 offset:1068
	ds_write_b32 v3, v16 offset:2112
	ds_write_b32 v3, v17 offset:2116
	ds_write_b32 v3, v18 offset:2120
	ds_write_b32 v3, v19 offset:2124
	ds_write_b32 v3, v20 offset:3168
	ds_write_b32 v3, v21 offset:3172
	ds_write_b32 v3, v22 offset:3176
	ds_write_b32 v3, v23 offset:3180
	ds_write_b32 v3, v24 offset:4224
	ds_write_b32 v3, v25 offset:4228
	ds_write_b32 v3, v26 offset:4232
	ds_write_b32 v3, v27 offset:4236
	ds_write_b32 v3, v28 offset:5280
	ds_write_b32 v3, v29 offset:5284
	ds_write_b32 v3, v30 offset:5288
	ds_write_b32 v3, v31 offset:5292
	ds_write_b32 v3, v32 offset:6336
	ds_write_b32 v3, v33 offset:6340
	ds_write_b32 v3, v34 offset:6344
	ds_write_b32 v3, v35 offset:6348
	ds_write_b32 v3, v36 offset:7392
	ds_write_b32 v3, v37 offset:7396
	ds_write_b32 v3, v38 offset:7400
	ds_write_b32 v3, v39 offset:7404
	s_mov_b32 s32, s2
	s_mov_b32 s33, s3
	s_lshl_b32 s49, s7, 3
	v_mad_u32_u24 v6, v1, s7, v2
	s_waitcnt lgkmcnt(0)
	ds_read_b32 v104, v4 offset:0
	ds_read_b32 v105, v4 offset:132
	ds_read_b32 v106, v4 offset:264
	ds_read_b32 v107, v4 offset:396
	ds_read_b32 v108, v4 offset:528
	ds_read_b32 v109, v4 offset:660
	ds_read_b32 v110, v4 offset:792
	ds_read_b32 v111, v4 offset:924
	ds_read_b32 v112, v4 offset:32
	ds_read_b32 v113, v4 offset:164
	ds_read_b32 v114, v4 offset:296
	ds_read_b32 v115, v4 offset:428
	ds_read_b32 v116, v4 offset:560
	ds_read_b32 v117, v4 offset:692
	ds_read_b32 v118, v4 offset:824
	ds_read_b32 v119, v4 offset:956
	s_waitcnt lgkmcnt(8)
	v_cvt_pk_bf16_f32 v136, v104, v105
	v_cvt_pk_bf16_f32 v137, v106, v107
	v_cvt_pk_bf16_f32 v138, v108, v109
	v_cvt_pk_bf16_f32 v139, v110, v111
	global_store_dwordx4 v6, v[136:139], s[32:33] nt
	s_add_u32 s32, s32, s49
	s_addc_u32 s33, s33, 0
	ds_read_b32 v120, v4 offset:64
	ds_read_b32 v121, v4 offset:196
	ds_read_b32 v122, v4 offset:328
	ds_read_b32 v123, v4 offset:460
	ds_read_b32 v124, v4 offset:592
	ds_read_b32 v125, v4 offset:724
	ds_read_b32 v126, v4 offset:856
	ds_read_b32 v127, v4 offset:988
	s_waitcnt lgkmcnt(8)
	v_cvt_pk_bf16_f32 v140, v112, v113
	v_cvt_pk_bf16_f32 v141, v114, v115
	v_cvt_pk_bf16_f32 v142, v116, v117
	v_cvt_pk_bf16_f32 v143, v118, v119
	global_store_dwordx4 v6, v[140:143], s[32:33] nt
	s_add_u32 s32, s32, s49
	s_addc_u32 s33, s33, 0
	ds_read_b32 v128, v4 offset:96
	ds_read_b32 v129, v4 offset:228
	ds_read_b32 v130, v4 offset:360
	ds_read_b32 v131, v4 offset:492
	ds_read_b32 v132, v4 offset:624
	ds_read_b32 v133, v4 offset:756
	ds_read_b32 v134, v4 offset:888
	ds_read_b32 v135, v4 offset:1020
	s_waitcnt lgkmcnt(8)
	v_cvt_pk_bf16_f32 v136, v120, v121
	v_cvt_pk_bf16_f32 v137, v122, v123
	v_cvt_pk_bf16_f32 v138, v124, v125
	v_cvt_pk_bf16_f32 v139, v126, v127
	global_store_dwordx4 v6, v[136:139], s[32:33] nt
	s_add_u32 s32, s32, s49
	s_addc_u32 s33, s33, 0
	s_waitcnt lgkmcnt(0)
	v_cvt_pk_bf16_f32 v140, v128, v129
	v_cvt_pk_bf16_f32 v141, v130, v131
	v_cvt_pk_bf16_f32 v142, v132, v133
	v_cvt_pk_bf16_f32 v143, v134, v135
	global_store_dwordx4 v6, v[140:143], s[32:33] nt
	s_add_u32 s32, s32, s49
	s_addc_u32 s33, s33, 0
	s_cmp_ge_u32 s20, 12288
	s_cbranch_scc1 .Ltt7_dr6
	s_cmp_lt_u32 s20, 4096
	s_cbranch_scc1 .Ltt7_r7_s0
	s_sub_u32 s25, s20, 4096
	s_lshr_b32 s27, s25, 8
	s_and_b32 s31, s25, 255
	s_mul_i32 s35, s27, 0x200000
	s_lshl_b32 s41, s31, 7
	s_add_u32 s35, s35, s41
	s_add_u32 s0, s66, s35
	s_addc_u32 s1, s67, 0
	s_mul_i32 s35, s31, 0x20000
	s_lshl_b32 s41, s27, 7
	s_add_u32 s35, s35, s41
	s_add_u32 s2, s68, s35
	s_addc_u32 s3, s69, 0
	s_mov_b32 s5, 0x8000
	s_mov_b32 s6, 0x40000
	s_mov_b32 s7, 0x1000
	s_branch .Ltt7_r7_e

.LBB0_1154:
	s_waitcnt vmcnt(0)
	s_barrier
	s_cmp_lg_u32 s87, 0x100
	s_cbranch_scc1 .Ltt10_done
	s_cmp_lt_u32 s96, 96
	s_cbranch_scc1 .Ltt10_done
	s_sub_u32 s20, s96, 96
	s_lshl_b32 s20, s20, 3
	s_add_u32 s20, s20, s93
	s_movk_i32 s23, 1280
	v_mbcnt_hi_u32_b32 v0, -1, v212
	v_and_b32_e32 v0, 63, v0
	v_lshrrev_b32_e32 v1, 3, v0
	v_and_b32_e32 v2, 7, v0
	s_lshl_b32 s25, s93, 14
	v_mul_u32_u24_e32 v3, 0x84, v1
	v_mul_u32_u24_e32 v4, 0x420, v2
	v_lshlrev_b32_e32 v2, 4, v2
	v_add3_u32 v3, v3, v2, s25
	v_lshl_add_u32 v4, v1, 2, v4
	v_add_u32_e32 v4, s25, v4
	v_and_b32_e32 v7, 4, v1
	v_and_b32_e32 v5, 3, v1
	v_lshl_add_u32 v7, v7, 1, v5
	v_readlane_b32 s62, v244, 39
	v_readlane_b32 s63, v244, 40
	s_add_u32 s64, s76, 0x4189000
	s_addc_u32 s65, s77, 0
	v_readlane_b32 s66, v244, 21
	v_readlane_b32 s67, v244, 22
	s_add_u32 s68, s76, 0xa989000
	s_addc_u32 s69, s77, 0
	s_nop 0
	s_add_u32 s66, s66, 0x4000000
	s_addc_u32 s67, s67, 0
	s_cmp_ge_u32 s20, 10240
	s_cbranch_scc1 .Ltt10_done
	s_cmp_lt_u32 s20, 2048
	s_cbranch_scc1 .Ltt10_r1_s0
	s_sub_u32 s25, s20, 2048
	s_lshr_b32 s27, s25, 6
	s_and_b32 s31, s25, 63
	s_mul_i32 s35, s27, 0x80000
	s_lshl_b32 s41, s31, 7
	s_add_u32 s35, s35, s41
	s_add_u32 s0, s66, s35
	s_addc_u32 s1, s67, 0
	s_mul_i32 s35, s31, 0x80000
	s_lshl_b32 s41, s27, 7
	s_add_u32 s35, s35, s41
	s_add_u32 s2, s68, s35
	s_addc_u32 s3, s69, 0
	s_mov_b32 s5, 0x2000
	s_mov_b32 s6, 0x10000
	s_mov_b32 s7, 0x4000
	s_branch .Ltt10_r1_e

.Ltt10_r2_e:
	v_mad_u32_u24 v5, v1, s5, v2
	global_load_dwordx4 v[40:43], v5, s[0:1] nt
	s_add_u32 s0, s0, s6
	s_addc_u32 s1, s1, 0
	global_load_dwordx4 v[44:47], v5, s[0:1] nt
	s_add_u32 s0, s0, s6
	s_addc_u32 s1, s1, 0
	global_load_dwordx4 v[48:51], v5, s[0:1] nt
	s_add_u32 s0, s0, s6
	s_addc_u32 s1, s1, 0
	global_load_dwordx4 v[52:55], v5, s[0:1] nt
	s_add_u32 s0, s0, s6
	s_addc_u32 s1, s1, 0
	global_load_dwordx4 v[56:59], v5, s[0:1] nt
	s_add_u32 s0, s0, s6
	s_addc_u32 s1, s1, 0
	global_load_dwordx4 v[60:63], v5, s[0:1] nt
	s_add_u32 s0, s0, s6
	s_addc_u32 s1, s1, 0
	global_load_dwordx4 v[64:67], v5, s[0:1] nt
	s_add_u32 s0, s0, s6
	s_addc_u32 s1, s1, 0
	global_load_dwordx4 v[68:71], v5, s[0:1] nt
	s_add_u32 s0, s0, s6
	s_addc_u32 s1, s1, 0
	s_add_u32 s20, s20, s23
	s_cmp_ge_u32 s20, 10240
	s_cbranch_scc1 .Ltt10_dr2
	s_cmp_lt_u32 s20, 2048
	s_cbranch_scc1 .Ltt10_r3_s0
	s_sub_u32 s25, s20, 2048
	s_lshr_b32 s27, s25, 6
	s_and_b32 s31, s25, 63
	s_mul_i32 s35, s27, 0x80000
	s_lshl_b32 s41, s31, 7
	s_add_u32 s35, s35, s41
	s_add_u32 s0, s66, s35
	s_addc_u32 s1, s67, 0
	s_mul_i32 s35, s31, 0x80000
	s_lshl_b32 s41, s27, 7
	s_add_u32 s35, s35, s41
	s_add_u32 s42, s68, s35
	s_addc_u32 s43, s69, 0
	s_mov_b32 s5, 0x2000
	s_mov_b32 s6, 0x10000
	s_mov_b32 s44, 0x4000
	s_branch .Ltt10_r3_e
.Ltt10_r3_s0:
	s_sub_u32 s25, s20, 0
	s_lshr_b32 s27, s25, 6
	s_and_b32 s31, s25, 63
	s_mul_i32 s35, s27, 0x80000
	s_lshl_b32 s41, s31, 7
	s_add_u32 s35, s35, s41
	s_add_u32 s0, s62, s35
	s_addc_u32 s1, s63, 0
	s_mul_i32 s35, s31, 0x20000
	s_lshl_b32 s41, s27, 7
	s_add_u32 s35, s35, s41
	s_add_u32 s42, s64, s35
	s_addc_u32 s43, s65, 0
	s_mov_b32 s5, 0x2000
	s_mov_b32 s6, 0x10000
	s_mov_b32 s44, 0x1000
.Ltt10_r3_e:
	v_mad_u32_u24 v5, v1, s5, v2
	global_load_dwordx4 v[72:75], v5, s[0:1] nt
	s_add_u32 s0, s0, s6
	s_addc_u32 s1, s1, 0
	global_load_dwordx4 v[76:79], v5, s[0:1] nt
	s_add_u32 s0, s0, s6
	s_addc_u32 s1, s1, 0
	global_load_dwordx4 v[80:83], v5, s[0:1] nt
	s_add_u32 s0, s0, s6
	s_addc_u32 s1, s1, 0
	global_load_dwordx4 v[84:87], v5, s[0:1] nt
	s_add_u32 s0, s0, s6
	s_addc_u32 s1, s1, 0
	global_load_dwordx4 v[88:91], v5, s[0:1] nt
	s_add_u32 s0, s0, s6
	s_addc_u32 s1, s1, 0
	global_load_dwordx4 v[92:95], v5, s[0:1] nt
	s_add_u32 s0, s0, s6
	s_addc_u32 s1, s1, 0
	global_load_dwordx4 v[96:99], v5, s[0:1] nt
	s_add_u32 s0, s0, s6
	s_addc_u32 s1, s1, 0
	global_load_dwordx4 v[100:103], v5, s[0:1] nt
	s_add_u32 s0, s0, s6
	s_addc_u32 s1, s1, 0
	s_add_u32 s20, s20, s23
	s_waitcnt vmcnt(16)
	ds_write_b32 v3, v8 offset:0
	ds_write_b32 v3, v9 offset:4
	ds_write_b32 v3, v10 offset:8
	ds_write_b32 v3, v11 offset:12
	ds_write_b32 v3, v12 offset:1056
	ds_write_b32 v3, v13 offset:1060
	ds_write_b32 v3, v14 offset:1064
	ds_write_b32 v3, v15 offset:1068
	ds_write_b32 v3, v16 offset:2112
	ds_write_b32 v3, v17 offset:2116
	ds_write_b32 v3, v18 offset:2120
	ds_write_b32 v3, v19 offset:2124
	ds_write_b32 v3, v20 offset:3168
	ds_write_b32 v3, v21 offset:3172
	ds_write_b32 v3, v22 offset:3176
	ds_write_b32 v3, v23 offset:3180
	ds_write_b32 v3, v24 offset:4224
	ds_write_b32 v3, v25 offset:4228
	ds_write_b32 v3, v26 offset:4232
	ds_write_b32 v3, v27 offset:4236
	ds_write_b32 v3, v28 offset:5280
	ds_write_b32 v3, v29 offset:5284
	ds_write_b32 v3, v30 offset:5288
	ds_write_b32 v3, v31 offset:5292
	ds_write_b32 v3, v32 offset:6336
	ds_write_b32 v3, v33 offset:6340
	ds_write_b32 v3, v34 offset:6344
	ds_write_b32 v3, v35 offset:6348
	ds_write_b32 v3, v36 offset:7392
	ds_write_b32 v3, v37 offset:7396
	ds_write_b32 v3, v38 offset:7400
	ds_write_b32 v3, v39 offset:7404
	s_mov_b32 s32, s2
	s_mov_b32 s33, s3
	s_lshl_b32 s49, s7, 3
	v_mad_u32_u24 v6, v1, s7, v2
	s_waitcnt lgkmcnt(0)
	ds_read_b32 v104, v4 offset:0
	ds_read_b32 v105, v4 offset:132
	ds_read_b32 v106, v4 offset:264
	ds_read_b32 v107, v4 offset:396
	ds_read_b32 v108, v4 offset:528
	ds_read_b32 v109, v4 offset:660
	ds_read_b32 v110, v4 offset:792
	ds_read_b32 v111, v4 offset:924
	ds_read_b32 v112, v4 offset:32
	ds_read_b32 v113, v4 offset:164
	ds_read_b32 v114, v4 offset:296
	ds_read_b32 v115, v4 offset:428
	ds_read_b32 v116, v4 offset:560
	ds_read_b32 v117, v4 offset:692
	ds_read_b32 v118, v4 offset:824
	ds_read_b32 v119, v4 offset:956
	s_waitcnt lgkmcnt(8)
	v_cvt_pk_bf16_f32 v136, v104, v105
	v_cvt_pk_bf16_f32 v137, v106, v107
	v_cvt_pk_bf16_f32 v138, v108, v109
	v_cvt_pk_bf16_f32 v139, v110, v111
	global_store_dwordx4 v6, v[136:139], s[32:33] nt
	s_add_u32 s32, s32, s49
	s_addc_u32 s33, s33, 0
	ds_read_b32 v120, v4 offset:64
	ds_read_b32 v121, v4 offset:196
	ds_read_b32 v122, v4 offset:328
	ds_read_b32 v123, v4 offset:460
	ds_read_b32 v124, v4 offset:592
	ds_read_b32 v125, v4 offset:724
	ds_read_b32 v126, v4 offset:856
	ds_read_b32 v127, v4 offset:988
	s_waitcnt lgkmcnt(8)
	v_cvt_pk_bf16_f32 v140, v112, v113
	v_cvt_pk_bf16_f32 v141, v114, v115
	v_cvt_pk_bf16_f32 v142, v116, v117
	v_cvt_pk_bf16_f32 v143, v118, v119
	global_store_dwordx4 v6, v[140:143], s[32:33] nt
	s_add_u32 s32, s32, s49
	s_addc_u32 s33, s33, 0
	ds_read_b32 v128, v4 offset:96
	ds_read_b32 v129, v4 offset:228
	ds_read_b32 v130, v4 offset:360
	ds_read_b32 v131, v4 offset:492
	ds_read_b32 v132, v4 offset:624
	ds_read_b32 v133, v4 offset:756
	ds_read_b32 v134, v4 offset:888
	ds_read_b32 v135, v4 offset:1020
	s_waitcnt lgkmcnt(8)
	v_cvt_pk_bf16_f32 v136, v120, v121
	v_cvt_pk_bf16_f32 v137, v122, v123
	v_cvt_pk_bf16_f32 v138, v124, v125
	v_cvt_pk_bf16_f32 v139, v126, v127
	global_store_dwordx4 v6, v[136:139], s[32:33] nt
	s_add_u32 s32, s32, s49
	s_addc_u32 s33, s33, 0
	s_waitcnt lgkmcnt(0)
	v_cvt_pk_bf16_f32 v140, v128, v129
	v_cvt_pk_bf16_f32 v141, v130, v131
	v_cvt_pk_bf16_f32 v142, v132, v133
	v_cvt_pk_bf16_f32 v143, v134, v135
	global_store_dwordx4 v6, v[140:143], s[32:33] nt
	s_add_u32 s32, s32, s49
	s_addc_u32 s33, s33, 0
	s_cmp_ge_u32 s20, 10240
	s_cbranch_scc1 .Ltt10_dr3
	s_cmp_lt_u32 s20, 2048
	s_cbranch_scc1 .Ltt10_r4_s0
	s_sub_u32 s25, s20, 2048
	s_lshr_b32 s27, s25, 6
	s_and_b32 s31, s25, 63
	s_mul_i32 s35, s27, 0x80000
	s_lshl_b32 s41, s31, 7
	s_add_u32 s35, s35, s41
	s_add_u32 s0, s66, s35
	s_addc_u32 s1, s67, 0
	s_mul_i32 s35, s31, 0x80000
	s_lshl_b32 s41, s27, 7
	s_add_u32 s35, s35, s41
	s_add_u32 s2, s68, s35
	s_addc_u32 s3, s69, 0
	s_mov_b32 s5, 0x2000
	s_mov_b32 s6, 0x10000
	s_mov_b32 s7, 0x4000
	s_branch .Ltt10_r4_e

.Ltt10_loop:
	s_cmp_ge_u32 s20, 10240
	s_cbranch_scc1 .Ltt10_dr4
	s_cmp_lt_u32 s20, 2048
	s_cbranch_scc1 .Ltt10_r5_s0
	s_sub_u32 s25, s20, 2048
	s_lshr_b32 s27, s25, 6
	s_and_b32 s31, s25, 63
	s_mul_i32 s35, s27, 0x80000
	s_lshl_b32 s41, s31, 7
	s_add_u32 s35, s35, s41
	s_add_u32 s0, s66, s35
	s_addc_u32 s1, s67, 0
	s_mul_i32 s35, s31, 0x80000
	s_lshl_b32 s41, s27, 7
	s_add_u32 s35, s35, s41
	s_add_u32 s10, s68, s35
	s_addc_u32 s11, s69, 0
	s_mov_b32 s5, 0x2000
	s_mov_b32 s6, 0x10000
	s_mov_b32 s47, 0x4000
	s_branch .Ltt10_r5_e

.Ltt10_r5_e:
	v_mad_u32_u24 v5, v1, s5, v2
	global_load_dwordx4 v[40:43], v5, s[0:1] nt
	s_add_u32 s0, s0, s6
	s_addc_u32 s1, s1, 0
	global_load_dwordx4 v[44:47], v5, s[0:1] nt
	s_add_u32 s0, s0, s6
	s_addc_u32 s1, s1, 0
	global_load_dwordx4 v[48:51], v5, s[0:1] nt
	s_add_u32 s0, s0, s6
	s_addc_u32 s1, s1, 0
	global_load_dwordx4 v[52:55], v5, s[0:1] nt
	s_add_u32 s0, s0, s6
	s_addc_u32 s1, s1, 0
	global_load_dwordx4 v[56:59], v5, s[0:1] nt
	s_add_u32 s0, s0, s6
	s_addc_u32 s1, s1, 0
	global_load_dwordx4 v[60:63], v5, s[0:1] nt
	s_add_u32 s0, s0, s6
	s_addc_u32 s1, s1, 0
	global_load_dwordx4 v[64:67], v5, s[0:1] nt
	s_add_u32 s0, s0, s6
	s_addc_u32 s1, s1, 0
	global_load_dwordx4 v[68:71], v5, s[0:1] nt
	s_add_u32 s0, s0, s6
	s_addc_u32 s1, s1, 0
	s_add_u32 s20, s20, s23
	s_waitcnt vmcnt(24)
	ds_write_b32 v3, v72 offset:0
	ds_write_b32 v3, v73 offset:4
	ds_write_b32 v3, v74 offset:8
	ds_write_b32 v3, v75 offset:12
	ds_write_b32 v3, v76 offset:1056
	ds_write_b32 v3, v77 offset:1060
	ds_write_b32 v3, v78 offset:1064
	ds_write_b32 v3, v79 offset:1068
	ds_write_b32 v3, v80 offset:2112
	ds_write_b32 v3, v81 offset:2116
	ds_write_b32 v3, v82 offset:2120
	ds_write_b32 v3, v83 offset:2124
	ds_write_b32 v3, v84 offset:3168
	ds_write_b32 v3, v85 offset:3172
	ds_write_b32 v3, v86 offset:3176
	ds_write_b32 v3, v87 offset:3180
	ds_write_b32 v3, v88 offset:4224
	ds_write_b32 v3, v89 offset:4228
	ds_write_b32 v3, v90 offset:4232
	ds_write_b32 v3, v91 offset:4236
	ds_write_b32 v3, v92 offset:5280
	ds_write_b32 v3, v93 offset:5284
	ds_write_b32 v3, v94 offset:5288
	ds_write_b32 v3, v95 offset:5292
	ds_write_b32 v3, v96 offset:6336
	ds_write_b32 v3, v97 offset:6340
	ds_write_b32 v3, v98 offset:6344
	ds_write_b32 v3, v99 offset:6348
	ds_write_b32 v3, v100 offset:7392
	ds_write_b32 v3, v101 offset:7396
	ds_write_b32 v3, v102 offset:7400
	ds_write_b32 v3, v103 offset:7404
	s_mov_b32 s32, s42
	s_mov_b32 s33, s43
	s_lshl_b32 s49, s44, 3
	v_mad_u32_u24 v6, v1, s44, v2
	s_waitcnt lgkmcnt(0)
	ds_read_b32 v104, v4 offset:0
	ds_read_b32 v105, v4 offset:132
	ds_read_b32 v106, v4 offset:264
	ds_read_b32 v107, v4 offset:396
	ds_read_b32 v108, v4 offset:528
	ds_read_b32 v109, v4 offset:660
	ds_read_b32 v110, v4 offset:792
	ds_read_b32 v111, v4 offset:924
	ds_read_b32 v112, v4 offset:32
	ds_read_b32 v113, v4 offset:164
	ds_read_b32 v114, v4 offset:296
	ds_read_b32 v115, v4 offset:428
	ds_read_b32 v116, v4 offset:560
	ds_read_b32 v117, v4 offset:692
	ds_read_b32 v118, v4 offset:824
	ds_read_b32 v119, v4 offset:956
	s_waitcnt lgkmcnt(8)
	v_cvt_pk_bf16_f32 v136, v104, v105
	v_cvt_pk_bf16_f32 v137, v106, v107
	v_cvt_pk_bf16_f32 v138, v108, v109
	v_cvt_pk_bf16_f32 v139, v110, v111
	global_store_dwordx4 v6, v[136:139], s[32:33] nt
	s_add_u32 s32, s32, s49
	s_addc_u32 s33, s33, 0
	ds_read_b32 v120, v4 offset:64
	ds_read_b32 v121, v4 offset:196
	ds_read_b32 v122, v4 offset:328
	ds_read_b32 v123, v4 offset:460
	ds_read_b32 v124, v4 offset:592
	ds_read_b32 v125, v4 offset:724
	ds_read_b32 v126, v4 offset:856
	ds_read_b32 v127, v4 offset:988
	s_waitcnt lgkmcnt(8)
	v_cvt_pk_bf16_f32 v140, v112, v113
	v_cvt_pk_bf16_f32 v141, v114, v115
	v_cvt_pk_bf16_f32 v142, v116, v117
	v_cvt_pk_bf16_f32 v143, v118, v119
	global_store_dwordx4 v6, v[140:143], s[32:33] nt
	s_add_u32 s32, s32, s49
	s_addc_u32 s33, s33, 0
	ds_read_b32 v128, v4 offset:96
	ds_read_b32 v129, v4 offset:228
	ds_read_b32 v130, v4 offset:360
	ds_read_b32 v131, v4 offset:492
	ds_read_b32 v132, v4 offset:624
	ds_read_b32 v133, v4 offset:756
	ds_read_b32 v134, v4 offset:888
	ds_read_b32 v135, v4 offset:1020
	s_waitcnt lgkmcnt(8)
	v_cvt_pk_bf16_f32 v136, v120, v121
	v_cvt_pk_bf16_f32 v137, v122, v123
	v_cvt_pk_bf16_f32 v138, v124, v125
	v_cvt_pk_bf16_f32 v139, v126, v127
	global_store_dwordx4 v6, v[136:139], s[32:33] nt
	s_add_u32 s32, s32, s49
	s_addc_u32 s33, s33, 0
	s_waitcnt lgkmcnt(0)
	v_cvt_pk_bf16_f32 v140, v128, v129
	v_cvt_pk_bf16_f32 v141, v130, v131
	v_cvt_pk_bf16_f32 v142, v132, v133
	v_cvt_pk_bf16_f32 v143, v134, v135
	global_store_dwordx4 v6, v[140:143], s[32:33] nt
	s_add_u32 s32, s32, s49
	s_addc_u32 s33, s33, 0
	s_cmp_ge_u32 s20, 10240
	s_cbranch_scc1 .Ltt10_dr5
	s_cmp_lt_u32 s20, 2048
	s_cbranch_scc1 .Ltt10_r6_s0
	s_sub_u32 s25, s20, 2048
	s_lshr_b32 s27, s25, 6
	s_and_b32 s31, s25, 63
	s_mul_i32 s35, s27, 0x80000
	s_lshl_b32 s41, s31, 7
	s_add_u32 s35, s35, s41
	s_add_u32 s0, s66, s35
	s_addc_u32 s1, s67, 0
	s_mul_i32 s35, s31, 0x80000
	s_lshl_b32 s41, s27, 7
	s_add_u32 s35, s35, s41
	s_add_u32 s42, s68, s35
	s_addc_u32 s43, s69, 0
	s_mov_b32 s5, 0x2000
	s_mov_b32 s6, 0x10000
	s_mov_b32 s44, 0x4000
	s_branch .Ltt10_r6_e

.Ltt10_r6_e:
	v_mad_u32_u24 v5, v1, s5, v2
	global_load_dwordx4 v[72:75], v5, s[0:1] nt
	s_add_u32 s0, s0, s6
	s_addc_u32 s1, s1, 0
	global_load_dwordx4 v[76:79], v5, s[0:1] nt
	s_add_u32 s0, s0, s6
	s_addc_u32 s1, s1, 0
	global_load_dwordx4 v[80:83], v5, s[0:1] nt
	s_add_u32 s0, s0, s6
	s_addc_u32 s1, s1, 0
	global_load_dwordx4 v[84:87], v5, s[0:1] nt
	s_add_u32 s0, s0, s6
	s_addc_u32 s1, s1, 0
	global_load_dwordx4 v[88:91], v5, s[0:1] nt
	s_add_u32 s0, s0, s6
	s_addc_u32 s1, s1, 0
	global_load_dwordx4 v[92:95], v5, s[0:1] nt
	s_add_u32 s0, s0, s6
	s_addc_u32 s1, s1, 0
	global_load_dwordx4 v[96:99], v5, s[0:1] nt
	s_add_u32 s0, s0, s6
	s_addc_u32 s1, s1, 0
	global_load_dwordx4 v[100:103], v5, s[0:1] nt
	s_add_u32 s0, s0, s6
	s_addc_u32 s1, s1, 0
	s_add_u32 s20, s20, s23
	s_waitcnt vmcnt(24)
	ds_write_b32 v3, v8 offset:0
	ds_write_b32 v3, v9 offset:4
	ds_write_b32 v3, v10 offset:8
	ds_write_b32 v3, v11 offset:12
	ds_write_b32 v3, v12 offset:1056
	ds_write_b32 v3, v13 offset:1060
	ds_write_b32 v3, v14 offset:1064
	ds_write_b32 v3, v15 offset:1068
	ds_write_b32 v3, v16 offset:2112
	ds_write_b32 v3, v17 offset:2116
	ds_write_b32 v3, v18 offset:2120
	ds_write_b32 v3, v19 offset:2124
	ds_write_b32 v3, v20 offset:3168
	ds_write_b32 v3, v21 offset:3172
	ds_write_b32 v3, v22 offset:3176
	ds_write_b32 v3, v23 offset:3180
	ds_write_b32 v3, v24 offset:4224
	ds_write_b32 v3, v25 offset:4228
	ds_write_b32 v3, v26 offset:4232
	ds_write_b32 v3, v27 offset:4236
	ds_write_b32 v3, v28 offset:5280
	ds_write_b32 v3, v29 offset:5284
	ds_write_b32 v3, v30 offset:5288
	ds_write_b32 v3, v31 offset:5292
	ds_write_b32 v3, v32 offset:6336
	ds_write_b32 v3, v33 offset:6340
	ds_write_b32 v3, v34 offset:6344
	ds_write_b32 v3, v35 offset:6348
	ds_write_b32 v3, v36 offset:7392
	ds_write_b32 v3, v37 offset:7396
	ds_write_b32 v3, v38 offset:7400
	ds_write_b32 v3, v39 offset:7404
	s_mov_b32 s32, s2
	s_mov_b32 s33, s3
	s_lshl_b32 s49, s7, 3
	v_mad_u32_u24 v6, v1, s7, v2
	s_waitcnt lgkmcnt(0)
	ds_read_b32 v104, v4 offset:0
	ds_read_b32 v105, v4 offset:132
	ds_read_b32 v106, v4 offset:264
	ds_read_b32 v107, v4 offset:396
	ds_read_b32 v108, v4 offset:528
	ds_read_b32 v109, v4 offset:660
	ds_read_b32 v110, v4 offset:792
	ds_read_b32 v111, v4 offset:924
	ds_read_b32 v112, v4 offset:32
	ds_read_b32 v113, v4 offset:164
	ds_read_b32 v114, v4 offset:296
	ds_read_b32 v115, v4 offset:428
	ds_read_b32 v116, v4 offset:560
	ds_read_b32 v117, v4 offset:692
	ds_read_b32 v118, v4 offset:824
	ds_read_b32 v119, v4 offset:956
	s_waitcnt lgkmcnt(8)
	v_cvt_pk_bf16_f32 v136, v104, v105
	v_cvt_pk_bf16_f32 v137, v106, v107
	v_cvt_pk_bf16_f32 v138, v108, v109
	v_cvt_pk_bf16_f32 v139, v110, v111
	global_store_dwordx4 v6, v[136:139], s[32:33] nt
	s_add_u32 s32, s32, s49
	s_addc_u32 s33, s33, 0
	ds_read_b32 v120, v4 offset:64
	ds_read_b32 v121, v4 offset:196
	ds_read_b32 v122, v4 offset:328
	ds_read_b32 v123, v4 offset:460
	ds_read_b32 v124, v4 offset:592
	ds_read_b32 v125, v4 offset:724
	ds_read_b32 v126, v4 offset:856
	ds_read_b32 v127, v4 offset:988
	s_waitcnt lgkmcnt(8)
	v_cvt_pk_bf16_f32 v140, v112, v113
	v_cvt_pk_bf16_f32 v141, v114, v115
	v_cvt_pk_bf16_f32 v142, v116, v117
	v_cvt_pk_bf16_f32 v143, v118, v119
	global_store_dwordx4 v6, v[140:143], s[32:33] nt
	s_add_u32 s32, s32, s49
	s_addc_u32 s33, s33, 0
	ds_read_b32 v128, v4 offset:96
	ds_read_b32 v129, v4 offset:228
	ds_read_b32 v130, v4 offset:360
	ds_read_b32 v131, v4 offset:492
	ds_read_b32 v132, v4 offset:624
	ds_read_b32 v133, v4 offset:756
	ds_read_b32 v134, v4 offset:888
	ds_read_b32 v135, v4 offset:1020
	s_waitcnt lgkmcnt(8)
	v_cvt_pk_bf16_f32 v136, v120, v121
	v_cvt_pk_bf16_f32 v137, v122, v123
	v_cvt_pk_bf16_f32 v138, v124, v125
	v_cvt_pk_bf16_f32 v139, v126, v127
	global_store_dwordx4 v6, v[136:139], s[32:33] nt
	s_add_u32 s32, s32, s49
	s_addc_u32 s33, s33, 0
	s_waitcnt lgkmcnt(0)
	v_cvt_pk_bf16_f32 v140, v128, v129
	v_cvt_pk_bf16_f32 v141, v130, v131
	v_cvt_pk_bf16_f32 v142, v132, v133
	v_cvt_pk_bf16_f32 v143, v134, v135
	global_store_dwordx4 v6, v[140:143], s[32:33] nt
	s_add_u32 s32, s32, s49
	s_addc_u32 s33, s33, 0
	s_cmp_ge_u32 s20, 10240
	s_cbranch_scc1 .Ltt10_dr6
	s_cmp_lt_u32 s20, 2048
	s_cbranch_scc1 .Ltt10_r7_s0
	s_sub_u32 s25, s20, 2048
	s_lshr_b32 s27, s25, 6
	s_and_b32 s31, s25, 63
	s_mul_i32 s35, s27, 0x80000
	s_lshl_b32 s41, s31, 7
	s_add_u32 s35, s35, s41
	s_add_u32 s0, s66, s35
	s_addc_u32 s1, s67, 0
	s_mul_i32 s35, s31, 0x80000
	s_lshl_b32 s41, s27, 7
	s_add_u32 s35, s35, s41
	s_add_u32 s2, s68, s35
	s_addc_u32 s3, s69, 0
	s_mov_b32 s5, 0x2000
	s_mov_b32 s6, 0x10000
	s_mov_b32 s7, 0x4000
	s_branch .Ltt10_r7_e
